# removed 135 XNACK-replay s_nop 0 pads between back-to-back loads (xnack off; asm guide 4.1 note a)
# baseline (speedup 1.0000x reference)
; __device__ __forceinline__ void norm_rows(const float* x, const float* w, bf16* H, int gw, int ngw, int lane) {
;     for (int m0 = gw; m0 < M; m0 += 4 * ngw) {
;         f32x4 v[4][8]; float s[4];
; #pragma unroll
;         for (int q = 0; q < 4; ++q) { const int m = (m0 + q * ngw < M) ? m0 + q * ngw : m0; const f32x4* xr = (const f32x4*)(x + (size_t)m * D) + lane;
; #pragma unroll
;             for (int j = 0; j < 8; ++j) v[q][j] = xr[64 * j]; }
; #pragma unroll
;         for (int q = 0; q < 4; ++q) { float a = 0.f;
; #pragma unroll
;             for (int j = 0; j < 8; ++j) a += (v[q][j].x * v[q][j].x + v[q][j].y * v[q][j].y) + (v[q][j].z * v[q][j].z + v[q][j].w * v[q][j].w);
.LBB0_112:
	global_load_dwordx4 v[114:117], v[148:149], off offset:-4096
	global_load_dwordx4 v[102:105], v[148:149], off offset:-3072
	global_load_dwordx4 v[74:77], v[148:149], off offset:-2048
	global_load_dwordx4 v[42:45], v[148:149], off
	global_load_dwordx4 v[58:61], v[148:149], off offset:-1024
	global_load_dwordx4 v[26:29], v[148:149], off offset:1024
	global_load_dwordx4 v[14:17], v[148:149], off offset:2048
	global_load_dwordx4 v[2:5], v[148:149], off offset:3072
	s_add_i32 s1, s22, s0
	s_cmpk_lt_i32 s1, 0x4000
	s_cselect_b64 s[20:21], -1, 0
	s_and_b64 s[6:7], s[20:21], exec
	s_cselect_b32 s6, s1, s0
	s_ashr_i32 s7, s6, 31
	s_lshl_b64 s[6:7], s[6:7], 13
	v_lshl_add_u64 v[6:7], v[134:135], 0, s[6:7]
	global_load_dwordx4 v[118:121], v[6:7], off
	global_load_dwordx4 v[94:97], v[6:7], off offset:1024
	global_load_dwordx4 v[82:85], v[6:7], off offset:2048
	global_load_dwordx4 v[66:69], v[6:7], off offset:3072
	s_movk_i32 s8, 0x1000
	v_add_co_u32_e32 v6, vcc, s8, v6
	s_add_i32 s10, s49, s0
	s_nop 0
	v_addc_co_u32_e32 v7, vcc, 0, v7, vcc
	global_load_dwordx4 v[50:53], v[6:7], off
	global_load_dwordx4 v[34:37], v[6:7], off offset:1024
	global_load_dwordx4 v[22:25], v[6:7], off offset:2048
	global_load_dwordx4 v[10:13], v[6:7], off offset:3072
	s_cmpk_lt_i32 s10, 0x4000
	s_cselect_b64 s[28:29], -1, 0
	s_and_b64 s[6:7], s[28:29], exec
	s_cselect_b32 s6, s10, s0
	s_ashr_i32 s7, s6, 31
	s_lshl_b64 s[6:7], s[6:7], 13
	v_lshl_add_u64 v[6:7], v[134:135], 0, s[6:7]
	global_load_dwordx4 v[110:113], v[6:7], off
	global_load_dwordx4 v[90:93], v[6:7], off offset:1024
	global_load_dwordx4 v[78:81], v[6:7], off offset:2048
	global_load_dwordx4 v[62:65], v[6:7], off offset:3072
	v_add_co_u32_e32 v6, vcc, s8, v6
	s_add_i32 s12, s50, s0
	s_nop 0
	v_addc_co_u32_e32 v7, vcc, 0, v7, vcc
	global_load_dwordx4 v[46:49], v[6:7], off
	global_load_dwordx4 v[30:33], v[6:7], off offset:1024
	global_load_dwordx4 v[18:21], v[6:7], off offset:2048
	global_load_dwordx4 v[6:9], v[6:7], off offset:3072
	s_cmpk_lt_i32 s12, 0x4000
	s_cselect_b64 s[24:25], -1, 0
	s_and_b64 s[6:7], s[24:25], exec
	s_cselect_b32 s6, s12, s0
	s_ashr_i32 s7, s6, 31
	s_lshl_b64 s[6:7], s[6:7], 13
	s_cmpk_gt_i32 s1, 0x3fff
	s_waitcnt vmcnt(0)
	v_mov_b32_e32 v40, v115
	v_mov_b32_e32 v41, v103
	v_mov_b32_e32 v56, v117
	v_mov_b32_e32 v57, v105
	v_mov_b32_e32 v38, v114
	v_mov_b32_e32 v39, v102
	v_mov_b32_e32 v54, v116
	v_mov_b32_e32 v55, v104
	v_pk_mul_f32 v[70:71], v[76:77], v[76:77]
	v_pk_mul_f32 v[72:73], v[74:75], v[74:75]
	v_pk_mul_f32 v[40:41], v[40:41], v[40:41]
	v_pk_mul_f32 v[56:57], v[56:57], v[56:57]
	v_pk_mov_b32 v[98:99], v[72:73], v[70:71] op_sel:[1,0]
	v_mov_b32_e32 v73, v71
	v_pk_fma_f32 v[38:39], v[38:39], v[38:39], v[40:41]
	v_pk_fma_f32 v[40:41], v[54:55], v[54:55], v[56:57]
	v_mul_f32_e32 v89, v42, v42
	v_mul_f32_e32 v86, v59, v59
	v_mul_f32_e32 v88, v61, v61
	v_pk_add_f32 v[54:55], v[98:99], v[72:73]
	v_pk_add_f32 v[38:39], v[38:39], v[40:41]
	v_mul_f32_e32 v100, v43, v43
	v_mul_f32_e32 v101, v44, v44
	v_mul_f32_e32 v106, v45, v45
	v_pk_fma_f32 v[70:71], v[58:59], v[58:59], v[86:87] op_sel_hi:[1,1,0]
	v_pk_fma_f32 v[86:87], v[60:61], v[60:61], v[88:89] op_sel_hi:[1,1,0]
	v_pk_add_f32 v[40:41], v[54:55], v[54:55] op_sel:[0,1] op_sel_hi:[1,0]
	v_pk_add_f32 v[38:39], v[38:39], v[38:39] op_sel:[0,1] op_sel_hi:[1,0]
	v_mov_b32_e32 v71, v101
	v_mov_b32_e32 v87, v106
	v_mov_b32_e32 v41, v100
	v_mov_b32_e32 v39, v89
	v_pk_add_f32 v[38:39], v[38:39], v[40:41]
	v_pk_add_f32 v[40:41], v[70:71], v[86:87]
	v_pk_mul_f32 v[54:55], v[26:27], v[26:27]
	v_pk_add_f32 v[38:39], v[38:39], v[40:41]
	v_pk_mul_f32 v[40:41], v[28:29], v[28:29]
	v_pk_add_f32 v[38:39], v[38:39], v[38:39] op_sel:[0,1] op_sel_hi:[1,0]
	v_pk_mov_b32 v[56:57], v[54:55], v[40:41] op_sel:[1,0]
	v_mov_b32_e32 v55, v41
	v_pk_add_f32 v[40:41], v[56:57], v[54:55]
	v_mul_f32_e32 v54, v2, v2
	v_mul_f32_e32 v55, v3, v3
	v_pk_add_f32 v[40:41], v[40:41], v[40:41] op_sel:[0,1] op_sel_hi:[1,0]
	v_mov_b32_e32 v39, v54
	v_mov_b32_e32 v41, v55
	v_pk_add_f32 v[38:39], v[38:39], v[40:41]
	v_mul_f32_e32 v40, v15, v15
	v_mul_f32_e32 v54, v17, v17
	v_mul_f32_e32 v56, v4, v4
	v_mul_f32_e32 v57, v5, v5
	v_pk_fma_f32 v[40:41], v[14:15], v[14:15], v[40:41] op_sel_hi:[1,1,0]
	v_pk_fma_f32 v[54:55], v[16:17], v[16:17], v[54:55] op_sel_hi:[1,1,0]
	v_mov_b32_e32 v41, v56
	v_mov_b32_e32 v55, v57
	v_pk_add_f32 v[40:41], v[40:41], v[54:55]
	v_mov_b32_e32 v54, v119
	v_mov_b32_e32 v55, v95
	v_pk_add_f32 v[38:39], v[38:39], v[40:41]
	v_mov_b32_e32 v40, v118
	v_mov_b32_e32 v41, v94
	v_pk_mul_f32 v[54:55], v[54:55], v[54:55]
	v_mov_b32_e32 v56, v121
	v_mov_b32_e32 v57, v97
	v_pk_fma_f32 v[40:41], v[40:41], v[40:41], v[54:55]
	v_mov_b32_e32 v54, v120
	v_mov_b32_e32 v55, v96
	v_pk_mul_f32 v[56:57], v[56:57], v[56:57]
	v_mov_b32_e32 v154, v113
	v_pk_fma_f32 v[54:55], v[54:55], v[54:55], v[56:57]
	v_pk_mul_f32 v[56:57], v[82:83], v[82:83]
	v_pk_add_f32 v[40:41], v[40:41], v[54:55]
	v_pk_mul_f32 v[54:55], v[84:85], v[84:85]
	v_pk_add_f32 v[40:41], v[40:41], v[40:41] op_sel:[0,1] op_sel_hi:[1,0]
	v_pk_mov_b32 v[70:71], v[56:57], v[54:55] op_sel:[1,0]
	v_mov_b32_e32 v57, v55
	v_pk_add_f32 v[54:55], v[70:71], v[56:57]
	v_mul_f32_e32 v56, v50, v50
	v_mul_f32_e32 v57, v51, v51
	v_pk_add_f32 v[54:55], v[54:55], v[54:55] op_sel:[0,1] op_sel_hi:[1,0]
	v_mov_b32_e32 v41, v56
	v_mov_b32_e32 v55, v57
	v_pk_add_f32 v[40:41], v[40:41], v[54:55]
	v_mul_f32_e32 v54, v67, v67
	v_mul_f32_e32 v56, v69, v69
	v_mul_f32_e32 v70, v52, v52
	v_mul_f32_e32 v71, v53, v53
	v_pk_fma_f32 v[54:55], v[66:67], v[66:67], v[54:55] op_sel_hi:[1,1,0]
	v_pk_fma_f32 v[56:57], v[68:69], v[68:69], v[56:57] op_sel_hi:[1,1,0]
; __device__ __forceinline__ void norm_rows(const float* x, const float* w, bf16* H, int gw, int ngw, int lane) {
;     ...
;         for (int q = 0; q < 4; ++q) { const int m = (m0 + q * ngw < M) ? m0 + q * ngw : m0; const f32x4* xr = (const f32x4*)(x + (size_t)m * D) + lane;
; #pragma unroll
;             for (int j = 0; j < 8; ++j) v[q][j] = xr[64 * j]; }
; #pragma unroll
;         for (int q = 0; q < 4; ++q) { float a = 0.f;
; #pragma unroll
;             for (int j = 0; j < 8; ++j) a += (v[q][j].x * v[q][j].x + v[q][j].y * v[q][j].y) + (v[q][j].z * v[q][j].z + v[q][j].w * v[q][j].w);
;             s[q] = rsqrtf(wave_sum(a) * (1.f / D) + 1e-6f); }
	v_mov_b32_e32 v55, v70
	v_mov_b32_e32 v57, v71
	v_pk_add_f32 v[54:55], v[54:55], v[56:57]
	v_pk_mul_f32 v[56:57], v[34:35], v[34:35]
	v_pk_add_f32 v[40:41], v[40:41], v[54:55]
	v_pk_mul_f32 v[54:55], v[36:37], v[36:37]
	v_pk_add_f32 v[40:41], v[40:41], v[40:41] op_sel:[0,1] op_sel_hi:[1,0]
	v_pk_mov_b32 v[70:71], v[56:57], v[54:55] op_sel:[1,0]
	v_mov_b32_e32 v57, v55
	v_pk_add_f32 v[54:55], v[70:71], v[56:57]
	v_mul_f32_e32 v56, v10, v10
	v_mul_f32_e32 v57, v11, v11
	v_pk_add_f32 v[54:55], v[54:55], v[54:55] op_sel:[0,1] op_sel_hi:[1,0]
	v_mov_b32_e32 v41, v56
	v_mov_b32_e32 v55, v57
	v_pk_add_f32 v[40:41], v[40:41], v[54:55]
	v_mul_f32_e32 v54, v23, v23
	v_mul_f32_e32 v56, v25, v25
	v_mul_f32_e32 v70, v12, v12
	v_mul_f32_e32 v71, v13, v13
	v_pk_fma_f32 v[54:55], v[22:23], v[22:23], v[54:55] op_sel_hi:[1,1,0]
	v_pk_fma_f32 v[56:57], v[24:25], v[24:25], v[56:57] op_sel_hi:[1,1,0]
	v_mov_b32_e32 v55, v70
	v_mov_b32_e32 v57, v71
	v_pk_add_f32 v[54:55], v[54:55], v[56:57]
	v_mov_b32_e32 v155, v93
	v_pk_add_f32 v[40:41], v[40:41], v[54:55]
	v_mov_b32_e32 v55, v38
	v_mov_b32_e32 v54, v40
	v_mov_b32_e32 v38, v41
	v_pk_add_f32 v[38:39], v[54:55], v[38:39]
	v_lshl_add_u64 v[54:55], v[134:135], 0, s[6:7]
	global_load_dwordx4 v[126:129], v[54:55], off
	global_load_dwordx4 v[122:125], v[54:55], off offset:1024
	global_load_dwordx4 v[106:109], v[54:55], off offset:2048
	global_load_dwordx4 v[98:101], v[54:55], off offset:3072
	ds_bpermute_b32 v41, v158, v39
	ds_bpermute_b32 v40, v158, v38
	v_add_co_u32_e32 v130, vcc, s8, v54
	v_pk_mul_f32 v[154:155], v[154:155], v[154:155]
	s_nop 0
	v_addc_co_u32_e32 v131, vcc, 0, v55, vcc
	s_waitcnt lgkmcnt(0)
	v_pk_add_f32 v[38:39], v[38:39], v[40:41]
	ds_bpermute_b32 v41, v159, v39
	ds_bpermute_b32 v40, v159, v38
	s_mov_b32 s6, 0x3a000000
	s_waitcnt lgkmcnt(0)
	v_pk_add_f32 v[38:39], v[38:39], v[40:41]
	ds_bpermute_b32 v41, v160, v39
	ds_bpermute_b32 v40, v160, v38
	s_waitcnt lgkmcnt(0)
	v_pk_add_f32 v[132:133], v[38:39], v[40:41]
	global_load_dwordx4 v[86:89], v[130:131], off
	global_load_dwordx4 v[70:73], v[130:131], off offset:1024
	global_load_dwordx4 v[54:57], v[130:131], off offset:2048
	global_load_dwordx4 v[38:41], v[130:131], off offset:3072
	ds_bpermute_b32 v151, v161, v133
	ds_bpermute_b32 v150, v161, v132
	v_mov_b32_e32 v130, v110
	v_mov_b32_e32 v131, v90
	s_waitcnt lgkmcnt(0)
	v_pk_add_f32 v[150:151], v[132:133], v[150:151]
	v_mov_b32_e32 v132, v111
	v_mov_b32_e32 v133, v91
	v_pk_mul_f32 v[132:133], v[132:133], v[132:133]
	ds_bpermute_b32 v153, v162, v151
	v_pk_fma_f32 v[130:131], v[130:131], v[130:131], v[132:133]
	v_mov_b32_e32 v132, v112
	v_mov_b32_e32 v133, v92
	v_pk_fma_f32 v[132:133], v[132:133], v[132:133], v[154:155]
	v_pk_mul_f32 v[154:155], v[78:79], v[78:79]
	v_pk_add_f32 v[130:131], v[130:131], v[132:133]
	v_pk_mul_f32 v[132:133], v[80:81], v[80:81]
	v_pk_add_f32 v[130:131], v[130:131], v[130:131] op_sel:[0,1] op_sel_hi:[1,0]
	v_pk_mov_b32 v[156:157], v[154:155], v[132:133] op_sel:[1,0]
	v_mov_b32_e32 v155, v133
	v_pk_add_f32 v[132:133], v[156:157], v[154:155]
	v_mul_f32_e32 v154, v46, v46
	v_mul_f32_e32 v155, v47, v47
	v_pk_add_f32 v[132:133], v[132:133], v[132:133] op_sel:[0,1] op_sel_hi:[1,0]
	v_mov_b32_e32 v131, v154
	v_mov_b32_e32 v133, v155
	v_pk_add_f32 v[130:131], v[130:131], v[132:133]
	v_mul_f32_e32 v132, v63, v63
	v_mul_f32_e32 v154, v65, v65
	v_mul_f32_e32 v156, v48, v48
	v_mul_f32_e32 v157, v49, v49
	v_pk_fma_f32 v[132:133], v[62:63], v[62:63], v[132:133] op_sel_hi:[1,1,0]
	v_pk_fma_f32 v[154:155], v[64:65], v[64:65], v[154:155] op_sel_hi:[1,1,0]
	v_mov_b32_e32 v133, v156
	v_mov_b32_e32 v155, v157
	v_pk_add_f32 v[132:133], v[132:133], v[154:155]
	v_pk_mul_f32 v[154:155], v[30:31], v[30:31]
	v_pk_add_f32 v[130:131], v[130:131], v[132:133]
	v_pk_mul_f32 v[132:133], v[32:33], v[32:33]
	v_pk_add_f32 v[130:131], v[130:131], v[130:131] op_sel:[0,1] op_sel_hi:[1,0]
	v_pk_mov_b32 v[156:157], v[154:155], v[132:133] op_sel:[1,0]
	v_mov_b32_e32 v155, v133
	v_pk_add_f32 v[132:133], v[156:157], v[154:155]
	v_mul_f32_e32 v154, v6, v6
	v_mul_f32_e32 v155, v7, v7
	v_pk_add_f32 v[132:133], v[132:133], v[132:133] op_sel:[0,1] op_sel_hi:[1,0]
	v_mov_b32_e32 v131, v154
	v_mov_b32_e32 v133, v155
	v_pk_add_f32 v[130:131], v[130:131], v[132:133]
	v_mul_f32_e32 v132, v19, v19
	v_mul_f32_e32 v154, v21, v21
	v_mul_f32_e32 v156, v8, v8
	v_mul_f32_e32 v157, v9, v9
	v_pk_fma_f32 v[132:133], v[18:19], v[18:19], v[132:133] op_sel_hi:[1,1,0]
	v_pk_fma_f32 v[154:155], v[20:21], v[20:21], v[154:155] op_sel_hi:[1,1,0]
	v_mov_b32_e32 v133, v156
	v_mov_b32_e32 v155, v157
	v_pk_add_f32 v[132:133], v[132:133], v[154:155]
	s_waitcnt vmcnt(7)
	v_mov_b32_e32 v156, v129
	v_pk_add_f32 v[154:155], v[130:131], v[132:133]
	v_mov_b32_e32 v132, v127
	s_waitcnt vmcnt(6)
; __device__ __forceinline__ unsigned pk2(float lo, float hi) { f32x2_t v = {lo, hi}; bf16x2_t b = __builtin_convertvector(v, bf16x2_t); return __builtin_bit_cast(unsigned, b); }
; __device__ __forceinline__ void norm_rows(const float* x, const float* w, bf16* H, int gw, int ngw, int lane) {
;     ...
;         for (int q = 0; q < 4; ++q) { float a = 0.f;
; #pragma unroll
;             for (int j = 0; j < 8; ++j) a += (v[q][j].x * v[q][j].x + v[q][j].y * v[q][j].y) + (v[q][j].z * v[q][j].z + v[q][j].w * v[q][j].w);
;             s[q] = rsqrtf(wave_sum(a) * (1.f / D) + 1e-6f); }
; #pragma unroll
;         for (int j = 0; j < 8; ++j) { const f32x4 ww = ((const f32x4*)w)[lane + 64 * j];
; #pragma unroll
;             for (int q = 0; q < 4; ++q) { const int m = m0 + q * ngw;
;                 if (m < M) { u32x2v o; o.x = pk2(v[q][j].x * s[q] * ww.x, v[q][j].y * s[q] * ww.y); o.y = pk2(v[q][j].z * s[q] * ww.z, v[q][j].w * s[q] * ww.w); ((u32x2v*)(H + (size_t)m * D) + lane)[64 * j] = o; } } }
	v_mov_b32_e32 v133, v123
	v_mov_b32_e32 v130, v126
	v_mov_b32_e32 v131, v122
	v_pk_mul_f32 v[132:133], v[132:133], v[132:133]
	v_mov_b32_e32 v157, v125
	v_pk_fma_f32 v[130:131], v[130:131], v[130:131], v[132:133]
	v_mov_b32_e32 v132, v128
	v_mov_b32_e32 v133, v124
	v_pk_mul_f32 v[156:157], v[156:157], v[156:157]
	ds_bpermute_b32 v152, v162, v150
	v_pk_fma_f32 v[132:133], v[132:133], v[132:133], v[156:157]
	s_waitcnt vmcnt(3)
	v_mul_f32_e32 v166, v86, v86
	v_pk_add_f32 v[156:157], v[130:131], v[132:133]
	v_pk_mul_f32 v[130:131], v[108:109], v[108:109]
	v_pk_mul_f32 v[132:133], v[106:107], v[106:107]
	v_mul_f32_e32 v167, v87, v87
	v_pk_mov_b32 v[164:165], v[132:133], v[130:131] op_sel:[1,0]
	v_mov_b32_e32 v133, v131
	v_pk_add_f32 v[164:165], v[164:165], v[132:133]
	global_load_dwordx4 v[130:133], v[138:139], off
	v_pk_add_f32 v[156:157], v[156:157], v[156:157] op_sel:[0,1] op_sel_hi:[1,0]
	v_pk_add_f32 v[164:165], v[164:165], v[164:165] op_sel:[0,1] op_sel_hi:[1,0]
	v_mov_b32_e32 v157, v166
	v_mov_b32_e32 v165, v167
	v_pk_add_f32 v[156:157], v[156:157], v[164:165]
	v_mul_f32_e32 v164, v99, v99
	v_mul_f32_e32 v166, v101, v101
	v_mul_f32_e32 v168, v88, v88
	v_mul_f32_e32 v169, v89, v89
	v_pk_fma_f32 v[164:165], v[98:99], v[98:99], v[164:165] op_sel_hi:[1,1,0]
	v_pk_fma_f32 v[166:167], v[100:101], v[100:101], v[166:167] op_sel_hi:[1,1,0]
	v_mov_b32_e32 v165, v168
	v_mov_b32_e32 v167, v169
	v_pk_add_f32 v[164:165], v[164:165], v[166:167]
	s_waitcnt vmcnt(3)
	v_pk_mul_f32 v[166:167], v[70:71], v[70:71]
	v_pk_add_f32 v[156:157], v[156:157], v[164:165]
	v_pk_mul_f32 v[164:165], v[72:73], v[72:73]
	v_pk_add_f32 v[156:157], v[156:157], v[156:157] op_sel:[0,1] op_sel_hi:[1,0]
	v_pk_mov_b32 v[168:169], v[166:167], v[164:165] op_sel:[1,0]
	v_mov_b32_e32 v167, v165
	v_pk_add_f32 v[164:165], v[168:169], v[166:167]
	s_waitcnt vmcnt(1)
	v_mul_f32_e32 v166, v38, v38
	v_mul_f32_e32 v167, v39, v39
	v_pk_add_f32 v[164:165], v[164:165], v[164:165] op_sel:[0,1] op_sel_hi:[1,0]
	v_mov_b32_e32 v157, v166
	v_mov_b32_e32 v165, v167
	v_pk_add_f32 v[156:157], v[156:157], v[164:165]
	v_mul_f32_e32 v164, v55, v55
	v_mul_f32_e32 v166, v57, v57
	v_mul_f32_e32 v168, v40, v40
	v_mul_f32_e32 v169, v41, v41
	v_pk_fma_f32 v[164:165], v[54:55], v[54:55], v[164:165] op_sel_hi:[1,1,0]
	v_pk_fma_f32 v[166:167], v[56:57], v[56:57], v[166:167] op_sel_hi:[1,1,0]
	v_mov_b32_e32 v165, v168
	v_mov_b32_e32 v167, v169
	v_pk_add_f32 v[164:165], v[164:165], v[166:167]
	s_waitcnt lgkmcnt(0)
	v_pk_add_f32 v[150:151], v[150:151], v[152:153]
	v_pk_add_f32 v[156:157], v[156:157], v[164:165]
	v_mov_b32_e32 v165, v154
	v_mov_b32_e32 v164, v156
	v_mov_b32_e32 v154, v157
	v_pk_add_f32 v[154:155], v[164:165], v[154:155]
	ds_bpermute_b32 v157, v158, v155
	ds_bpermute_b32 v156, v158, v154
	ds_bpermute_b32 v153, v163, v151
	ds_bpermute_b32 v152, v163, v150
	s_waitcnt lgkmcnt(2)
	v_pk_add_f32 v[154:155], v[154:155], v[156:157]
	ds_bpermute_b32 v157, v159, v155
	ds_bpermute_b32 v156, v159, v154
	s_waitcnt lgkmcnt(2)
	v_pk_add_f32 v[150:151], v[150:151], v[152:153]
	s_waitcnt lgkmcnt(0)
	v_pk_add_f32 v[152:153], v[154:155], v[156:157]
	ds_bpermute_b32 v155, v160, v153
	ds_bpermute_b32 v154, v160, v152
	v_pk_fma_f32 v[150:151], v[150:151], s[6:7], v[178:179] op_sel_hi:[1,0,0]
	s_waitcnt lgkmcnt(0)
	v_pk_add_f32 v[152:153], v[152:153], v[154:155]
	ds_bpermute_b32 v155, v161, v153
	ds_bpermute_b32 v154, v161, v152
	v_mul_f32_e32 v156, 0x4b800000, v151
	v_cmp_gt_f32_e32 vcc, s33, v151
	v_cmp_gt_f32_e64 s[6:7], s33, v150
	s_waitcnt lgkmcnt(0)
	v_pk_add_f32 v[154:155], v[152:153], v[154:155]
	v_cndmask_b32_e32 v151, v151, v156, vcc
	v_mul_f32_e32 v156, 0x4b800000, v150
	v_cndmask_b32_e64 v150, v150, v156, s[6:7]
	ds_bpermute_b32 v157, v162, v155
	ds_bpermute_b32 v156, v162, v154
	v_rsq_f32_e32 v151, v151
	v_rsq_f32_e32 v150, v150
	v_mul_f32_e32 v152, 0x45800000, v151
	s_waitcnt lgkmcnt(0)
	v_pk_add_f32 v[154:155], v[154:155], v[156:157]
	v_cndmask_b32_e32 v152, v151, v152, vcc
	ds_bpermute_b32 v157, v163, v155
	ds_bpermute_b32 v156, v163, v154
	v_pk_mul_f32 v[114:115], v[114:115], v[152:153] op_sel_hi:[1,0]
	v_pk_mul_f32 v[116:117], v[116:117], v[152:153] op_sel_hi:[1,0]
	s_waitcnt vmcnt(0)
	v_pk_mul_f32 v[114:115], v[114:115], v[130:131]
	v_pk_mul_f32 v[116:117], v[116:117], v[132:133]
	v_mul_f32_e32 v151, 0x45800000, v150
	v_cvt_pk_bf16_f32 v114, v114, v115
	v_cvt_pk_bf16_f32 v115, v116, v117
	v_lshl_add_u64 v[116:117], s[4:5], 0, v[0:1]
	v_cndmask_b32_e64 v150, v150, v151, s[6:7]
	global_store_dwordx2 v[116:117], v[114:115], off offset:-2048
	v_lshl_add_u64 v[114:115], s[2:3], 0, v[0:1]
	s_cbranch_scc1 .LBB0_114
	v_pk_mul_f32 v[118:119], v[118:119], v[150:151] op_sel_hi:[1,0]
	v_pk_mul_f32 v[120:121], v[120:121], v[150:151] op_sel_hi:[1,0]
	v_pk_mul_f32 v[118:119], v[118:119], v[130:131]
	v_pk_mul_f32 v[120:121], v[120:121], v[132:133]
	v_cvt_pk_bf16_f32 v118, v118, v119
	v_cvt_pk_bf16_f32 v119, v120, v121
	v_add_co_u32_e32 v120, vcc, 0x6800000, v114
	s_nop 1
	v_addc_co_u32_e32 v121, vcc, 0, v115, vcc
	global_store_dwordx2 v[120:121], v[118:119], off

;     __device__ __forceinline__ void operator()(const f32x4 (&acc)[2][2][4][2], const Unit& u, int wr, int wc, int fr, int fq) const {
;         const int row0 = u.pm * BM + wr * 64 + fr; const int col0 = u.pn * BM + wc * 32 + 4 * fq;
; #pragma unroll
;         for (int ai = 0; ai < 2; ++ai) {
;             f32x4 b[4][2][2];
; #pragma unroll
;             for (int m = 0; m < 4; ++m) { const size_t off = (size_t)(row0 + ai * HALF + m * 16) * ldc + col0;
; #pragma unroll
;                 for (int bj = 0; bj < 2; ++bj)
; #pragma unroll
;                     for (int n = 0; n < 2; ++n) b[m][bj][n] = *(const f32x4*)(base + off + bj * HALF + n * 16); }
;             asm volatile("" ::: "memory");
; #pragma unroll
;             for (int m = 0; m < 4; ++m) { const size_t off = (size_t)(row0 + ai * HALF + m * 16) * ldc + col0;
; #pragma unroll
;                 for (int bj = 0; bj < 2; ++bj)
; #pragma unroll
;                     for (int n = 0; n < 2; ++n) *(f32x4*)(out + off + bj * HALF + n * 16) = b[m][bj][n] + acc[ai][bj][m][n]; }
.LBB0_182:
	v_lshl_or_b32 v132, s24, 8, v158
	v_lshl_add_u32 v130, s25, 8, v156
	v_ashrrev_i32_e32 v133, 31, v132
	v_readlane_b32 s10, v250, 35
	v_lshlrev_b64 v[148:149], 2, v[132:133]
	v_readlane_b32 s11, v250, 36
	v_ashrrev_i32_e32 v131, 31, v130
	v_lshlrev_b64 v[152:153], 13, v[130:131]
	v_lshl_add_u64 v[150:151], s[10:11], 0, v[148:149]
	v_lshl_add_u64 v[132:133], v[150:151], 0, v[152:153]
	global_load_dwordx4 v[160:163], v[132:133], off
	global_load_dwordx4 v[164:167], v[132:133], off offset:64
	global_load_dwordx4 v[168:171], v[132:133], off offset:512
	global_load_dwordx4 v[172:175], v[132:133], off offset:576
	v_or_b32_e32 v132, 16, v130
	v_ashrrev_i32_e32 v133, 31, v132
	v_lshlrev_b64 v[176:177], 13, v[132:133]
	v_lshl_add_u64 v[132:133], v[150:151], 0, v[176:177]
	global_load_dwordx4 v[180:183], v[132:133], off
	global_load_dwordx4 v[184:187], v[132:133], off offset:64
	global_load_dwordx4 v[202:205], v[132:133], off offset:512
	global_load_dwordx4 v[206:209], v[132:133], off offset:576
	v_or_b32_e32 v132, 32, v130
	v_ashrrev_i32_e32 v133, 31, v132
	v_or_b32_e32 v130, 48, v130
	v_lshlrev_b64 v[188:189], 13, v[132:133]
	v_ashrrev_i32_e32 v131, 31, v130
	v_lshl_add_u64 v[132:133], v[150:151], 0, v[188:189]
	v_lshlrev_b64 v[154:155], 13, v[130:131]
	global_load_dwordx4 v[210:213], v[132:133], off
	global_load_dwordx4 v[214:217], v[132:133], off offset:64
	global_load_dwordx4 v[218:221], v[132:133], off offset:512
	global_load_dwordx4 v[222:225], v[132:133], off offset:576
	v_lshl_add_u64 v[130:131], v[150:151], 0, v[154:155]
	global_load_dwordx4 v[226:229], v[130:131], off
	global_load_dwordx4 v[138:141], v[130:131], off offset:64
	global_load_dwordx4 v[134:137], v[130:131], off offset:512
	global_load_dwordx4 v[130:133], v[130:131], off offset:576
	v_readlane_b32 s28, v252, 57
	v_readlane_b32 s29, v252, 58
	s_mov_b64 s[10:11], 0x100000
	s_and_b64 vcc, exec, s[42:43]
	v_readlane_b32 s30, v252, 59
	v_readlane_b32 s31, v252, 60
	s_waitcnt vmcnt(0)
	v_pk_add_f32 v[126:127], v[126:127], v[160:161]
	v_lshl_add_u64 v[160:161], s[28:29], 0, v[152:153]
	v_lshl_add_u64 v[160:161], v[160:161], 0, v[148:149]
	v_pk_add_f32 v[116:117], v[116:117], v[170:171]
	v_pk_add_f32 v[114:115], v[114:115], v[168:169]
	global_store_dwordx4 v[160:161], v[114:117], off offset:512
	v_pk_add_f32 v[112:113], v[112:113], v[174:175]
	v_pk_add_f32 v[100:101], v[100:101], v[204:205]
	v_lshl_add_u64 v[114:115], s[28:29], 0, v[176:177]
	v_lshl_add_u64 v[114:115], v[114:115], 0, v[148:149]
	v_pk_add_f32 v[98:99], v[98:99], v[202:203]
	global_store_dwordx4 v[114:115], v[98:101], off offset:512
	v_pk_add_f32 v[110:111], v[110:111], v[172:173]
	v_pk_add_f32 v[96:97], v[96:97], v[208:209]
	v_lshl_add_u64 v[98:99], s[28:29], 0, v[188:189]
	v_lshl_add_u64 v[98:99], v[98:99], 0, v[148:149]
	v_pk_add_f32 v[84:85], v[84:85], v[220:221]
	v_pk_add_f32 v[82:83], v[82:83], v[218:219]
	v_pk_add_f32 v[94:95], v[94:95], v[206:207]
	global_store_dwordx4 v[98:99], v[82:85], off offset:512
	v_pk_add_f32 v[80:81], v[80:81], v[224:225]
	v_pk_add_f32 v[78:79], v[78:79], v[222:223]
	v_lshl_add_u64 v[82:83], s[28:29], 0, v[154:155]
	v_pk_add_f32 v[128:129], v[128:129], v[162:163]
	v_pk_add_f32 v[124:125], v[124:125], v[166:167]
	v_pk_add_f32 v[122:123], v[122:123], v[164:165]
	global_store_dwordx4 v[160:161], v[110:113], off offset:576
	v_pk_add_f32 v[108:109], v[108:109], v[186:187]
	v_pk_add_f32 v[106:107], v[106:107], v[184:185]
	v_pk_add_f32 v[112:113], v[120:121], v[182:183]
	v_pk_add_f32 v[110:111], v[118:119], v[180:181]
	global_store_dwordx4 v[114:115], v[94:97], off offset:576
	v_pk_add_f32 v[92:93], v[92:93], v[216:217]
	v_pk_add_f32 v[90:91], v[90:91], v[214:215]
	v_pk_add_f32 v[96:97], v[104:105], v[212:213]
	v_pk_add_f32 v[94:95], v[102:103], v[210:211]
	global_store_dwordx4 v[98:99], v[78:81], off offset:576
	v_lshl_add_u64 v[82:83], v[82:83], 0, v[148:149]
	v_pk_add_f32 v[76:77], v[76:77], v[140:141]
	v_pk_add_f32 v[80:81], v[88:89], v[228:229]
	v_pk_add_f32 v[78:79], v[86:87], v[226:227]
	v_pk_add_f32 v[74:75], v[74:75], v[138:139]
	v_pk_add_f32 v[72:73], v[72:73], v[136:137]
	v_pk_add_f32 v[70:71], v[70:71], v[134:135]
	v_pk_add_f32 v[68:69], v[68:69], v[132:133]
	v_pk_add_f32 v[66:67], v[66:67], v[130:131]
	v_lshl_add_u64 v[132:133], v[152:153], 0, s[10:11]
	global_store_dwordx4 v[160:161], v[126:129], off
	global_store_dwordx4 v[160:161], v[122:125], off offset:64
	global_store_dwordx4 v[114:115], v[110:113], off
	global_store_dwordx4 v[114:115], v[106:109], off offset:64
	global_store_dwordx4 v[98:99], v[94:97], off
	global_store_dwordx4 v[98:99], v[90:93], off offset:64
	global_store_dwordx4 v[82:83], v[78:81], off
	global_store_dwordx4 v[82:83], v[74:77], off offset:64
	global_store_dwordx4 v[82:83], v[70:73], off offset:512
	global_store_dwordx4 v[82:83], v[66:69], off offset:576
	s_mov_b64 s[10:11], 0x120000
	v_lshl_add_u64 v[134:135], v[152:153], 0, s[10:11]
	v_lshl_add_u64 v[66:67], v[150:151], 0, v[132:133]
	global_load_dwordx4 v[80:83], v[66:67], off
	global_load_dwordx4 v[84:87], v[66:67], off offset:64
	global_load_dwordx4 v[88:91], v[66:67], off offset:512
	global_load_dwordx4 v[92:95], v[66:67], off offset:576
	v_lshl_add_u64 v[66:67], v[150:151], 0, v[134:135]
	s_mov_b64 s[10:11], 0x140000
	global_load_dwordx4 v[96:99], v[66:67], off
	global_load_dwordx4 v[100:103], v[66:67], off offset:64
	global_load_dwordx4 v[104:107], v[66:67], off offset:512
	global_load_dwordx4 v[108:111], v[66:67], off offset:576
	v_lshl_add_u64 v[136:137], v[152:153], 0, s[10:11]
	s_mov_b64 s[10:11], 0x160000
	v_lshl_add_u64 v[66:67], v[150:151], 0, v[136:137]
	v_lshl_add_u64 v[78:79], v[152:153], 0, s[10:11]
	global_load_dwordx4 v[112:115], v[66:67], off
	global_load_dwordx4 v[116:119], v[66:67], off offset:64
	global_load_dwordx4 v[120:123], v[66:67], off offset:512
	global_load_dwordx4 v[124:127], v[66:67], off offset:576
	v_lshl_add_u64 v[66:67], v[150:151], 0, v[78:79]
	global_load_dwordx4 v[128:131], v[66:67], off
	global_load_dwordx4 v[74:77], v[66:67], off offset:64
	global_load_dwordx4 v[70:73], v[66:67], off offset:512
	global_load_dwordx4 v[66:69], v[66:67], off offset:576
	s_mov_b64 s[10:11], -1
	s_waitcnt vmcnt(15)
; #define PG8_BAR __builtin_amdgcn_s_barrier()
;     __device__ __forceinline__ void operator()(const f32x4 (&acc)[2][2][4][2], const Unit& u, int wr, int wc, int fr, int fq) const {
;     ...
;             for (int m = 0; m < 4; ++m) { const size_t off = (size_t)(row0 + ai * HALF + m * 16) * ldc + col0;
; #pragma unroll
;                 for (int bj = 0; bj < 2; ++bj)
; #pragma unroll
;                     for (int n = 0; n < 2; ++n) *(f32x4*)(out + off + bj * HALF + n * 16) = b[m][bj][n] + acc[ai][bj][m][n]; }
; template <class Epi, class Sched, bool ALIGN_EPI = false, bool SP2 = false>
; __device__ __forceinline__ void gemm_phase(PG8_LAS unsigned char* lds, const Gemm g, const Sched& S, const Epi& E) {
;     ...
;         if constexpr (ALIGN_EPI) { if (wr == 0) PG8_BAR; }
;         if constexpr (!Epi::AFTER_DRAIN) { E(acc, cur, wr, wc, fr, fq); S.done(cur); }
;         if (!has_next) break;
; #pragma unroll
;         for (int a = 0; a < 2; ++a)
; #pragma unroll
;             for (int b = 0; b < 2; ++b)
; #pragma unroll
;                 for (int m = 0; m < 4; ++m)
; #pragma unroll
;                     for (int n = 0; n < 2; ++n) acc[a][b][m][n] = (f32x4){0.f, 0.f, 0.f, 0.f};
;         cur = nxt; cA = nA; cB = nB; ++ui;
;         if constexpr (ALIGN_EPI) { if (wr == 1) PG8_BAR; }
	v_pk_add_f32 v[62:63], v[62:63], v[80:81]
	v_lshl_add_u64 v[80:81], s[28:29], 0, v[132:133]
	v_lshl_add_u64 v[80:81], v[80:81], 0, v[148:149]
	s_waitcnt vmcnt(13)
	v_pk_add_f32 v[52:53], v[52:53], v[90:91]
	v_pk_add_f32 v[50:51], v[50:51], v[88:89]
	global_store_dwordx4 v[80:81], v[50:53], off offset:512
	s_waitcnt vmcnt(10)
	v_pk_add_f32 v[36:37], v[36:37], v[106:107]
	v_pk_add_f32 v[34:35], v[34:35], v[104:105]
	v_lshl_add_u64 v[50:51], s[28:29], 0, v[134:135]
	v_lshl_add_u64 v[50:51], v[50:51], 0, v[148:149]
	global_store_dwordx4 v[50:51], v[34:37], off offset:512
	s_waitcnt vmcnt(7)
	v_pk_add_f32 v[20:21], v[20:21], v[122:123]
	v_pk_add_f32 v[18:19], v[18:19], v[120:121]
	v_lshl_add_u64 v[34:35], s[28:29], 0, v[136:137]
	v_lshl_add_u64 v[34:35], v[34:35], 0, v[148:149]
	v_pk_add_f32 v[48:49], v[48:49], v[94:95]
	v_pk_add_f32 v[46:47], v[46:47], v[92:93]
	v_pk_add_f32 v[32:33], v[32:33], v[110:111]
	v_pk_add_f32 v[30:31], v[30:31], v[108:109]
	global_store_dwordx4 v[34:35], v[18:21], off offset:512
	s_waitcnt vmcnt(7)
	v_pk_add_f32 v[16:17], v[16:17], v[126:127]
	v_pk_add_f32 v[14:15], v[14:15], v[124:125]
	v_lshl_add_u64 v[18:19], s[28:29], 0, v[78:79]
	v_pk_add_f32 v[64:65], v[64:65], v[82:83]
	v_pk_add_f32 v[60:61], v[60:61], v[86:87]
	v_pk_add_f32 v[58:59], v[58:59], v[84:85]
	global_store_dwordx4 v[80:81], v[46:49], off offset:576
	v_pk_add_f32 v[44:45], v[44:45], v[102:103]
	v_pk_add_f32 v[42:43], v[42:43], v[100:101]
	v_pk_add_f32 v[48:49], v[56:57], v[98:99]
	v_pk_add_f32 v[46:47], v[54:55], v[96:97]
	global_store_dwordx4 v[50:51], v[30:33], off offset:576
	v_pk_add_f32 v[28:29], v[28:29], v[118:119]
	v_pk_add_f32 v[26:27], v[26:27], v[116:117]
	v_pk_add_f32 v[32:33], v[40:41], v[114:115]
	v_pk_add_f32 v[30:31], v[38:39], v[112:113]
	global_store_dwordx4 v[34:35], v[14:17], off offset:576
	v_lshl_add_u64 v[18:19], v[18:19], 0, v[148:149]
	s_waitcnt vmcnt(8)
	v_pk_add_f32 v[12:13], v[12:13], v[76:77]
	v_pk_add_f32 v[16:17], v[24:25], v[130:131]
	v_pk_add_f32 v[14:15], v[22:23], v[128:129]
	v_pk_add_f32 v[10:11], v[10:11], v[74:75]
	s_waitcnt vmcnt(7)
	v_pk_add_f32 v[8:9], v[8:9], v[72:73]
	v_pk_add_f32 v[6:7], v[6:7], v[70:71]
	s_waitcnt vmcnt(6)
	v_pk_add_f32 v[4:5], v[4:5], v[68:69]
	v_pk_add_f32 v[2:3], v[2:3], v[66:67]
	global_store_dwordx4 v[80:81], v[62:65], off
	global_store_dwordx4 v[80:81], v[58:61], off offset:64
	global_store_dwordx4 v[50:51], v[46:49], off
	global_store_dwordx4 v[50:51], v[42:45], off offset:64
	global_store_dwordx4 v[34:35], v[30:33], off
	global_store_dwordx4 v[34:35], v[26:29], off offset:64
	global_store_dwordx4 v[18:19], v[14:17], off
	global_store_dwordx4 v[18:19], v[10:13], off offset:64
	global_store_dwordx4 v[18:19], v[6:9], off offset:512
	global_store_dwordx4 v[18:19], v[2:5], off offset:576
	s_cbranch_vccnz .LBB0_167
	s_andn2_b64 vcc, exec, s[2:3]
	s_cbranch_vccnz .LBB0_166
	s_barrier
	s_branch .LBB0_166

; #define LAS __attribute__((address_space(3)))
; __device__ __forceinline__ void gdn_scan(const Args& c, int bh, int l, LAS unsigned char* lds) {
;     int tid_ = threadIdx.x; asm volatile("" : "+v"(tid_)); unsigned char* wsl = c.ws; asm volatile("" : "+s"(wsl)); int z_ = 0; asm volatile("" : "+s"(z_));
;     const int tid = tid_, lane = tid & 63, w = __builtin_amdgcn_readfirstlane(tid >> 6), r = lane & 15, q4 = lane >> 4;
;     const int b = bh >> 2, h = bh & 3;
;     LAS bf16* St = (LAS bf16*)lds;
;     LAS bf16* VNt = St + 128 * 136;
;     LAS bf16* Wl = VNt + 128 * 72;
;     LAS bf16* Ql = Wl + 64 * 136;
;     LAS bf16* Zl = Ql + 64 * 136;
;     LAS bf16* Al = Zl + 64 * 136;
;     LAS bf16* Kl = Al + 64 * 72;
;     LAS float* red = (LAS float*)(Kl + 128 * 72);
;     const int v = 16 * w + r;
;     const float nw = c.in[21 + z_][l * 128 + v];
; __device__ __forceinline__ void m2_phase(const Args& c, int l, LAS unsigned char* lds, int G, int mode, bool dry, int cidx) {
;     int tid_ = threadIdx.x; asm volatile("" : "+v"(tid_)); unsigned char* wsl = c.ws; asm volatile("" : "+s"(wsl)); int z_ = 0; asm volatile("" : "+s"(z_));
;     const int bx = blockIdx.x;
;     unsigned* rdone = ((unsigned*)(wsl + WS_CTL)) + 64 * (8 + cidx);
;     if (bx < 32) { if (mode & 1) { rwkv_scan(c, bx, l, lds, dry);
;             __threadfence(); __syncthreads(); if (tid_ == 0) __hip_atomic_fetch_add(rdone, 1u, __ATOMIC_RELAXED, __HIP_MEMORY_SCOPE_AGENT); } }
;     else if (bx < 64) { if (mode & 2) gdn_scan(c, bx - 32, l, lds); }
.LBB0_187:
	s_cmp_gt_i32 s12, 1
	s_mov_b64 s[2:3], -1
	s_cbranch_scc0 .LBB0_301
	s_cmp_lt_i32 s12, 3
	s_cbranch_scc1 .LBB0_298
	v_readlane_b32 s0, v247, 29
	s_cmp_eq_u32 s0, 3
	s_cbranch_scc0 .LBB0_297
	v_readlane_b32 s0, v252, 57
	v_readlane_b32 s1, v252, 58
	v_readlane_b32 s0, v250, 40
	v_readlane_b32 s2, v252, 59
	v_readlane_b32 s3, v252, 60
	v_readlane_b32 s1, v250, 41
	v_mov_b32_e32 v202, v179
	s_mov_b64 s[8:9], s[2:3]
	s_lshl_b64 s[30:31], s[0:1], 2
	v_readlane_b32 s0, v251, 56
	s_add_u32 s28, s8, s30
	v_readlane_b32 s1, v251, 57
	s_mov_b32 s10, s15
	s_addc_u32 s29, s9, s31
	s_mov_b64 s[2:3], -1
	s_and_b64 vcc, exec, s[0:1]
	s_cbranch_vccz .LBB0_230
	v_readlane_b32 s0, v251, 58
	v_readlane_b32 s1, v251, 59
	s_andn2_b64 vcc, exec, s[0:1]
	s_cbranch_vccnz .LBB0_229
	v_readlane_b32 s0, v252, 57
	v_mov_b32_e32 v4, v179
	v_readlane_b32 s1, v252, 58
	v_readlane_b32 s2, v252, 59
	v_readlane_b32 s3, v252, 60
	s_mov_b32 s4, 0
	s_ashr_i32 s5, s4, 31
	v_readfirstlane_b32 s1, v4
	s_ashr_i32 s6, s1, 2
	s_lshl_b64 s[4:5], s[4:5], 3
	v_readlane_b32 s12, v251, 0
	v_readlane_b32 s13, v251, 1
	s_add_u32 s4, s12, s4
	s_addc_u32 s5, s13, s5
	s_load_dwordx2 s[4:5], s[4:5], 0xa8
	v_bfi_b32 v38, -16, s6, v4
	v_readlane_b32 s6, v250, 42
	v_readlane_b32 s7, v250, 43
	v_readlane_b32 s14, v253, 26
	v_add_u32_e32 v2, s6, v38
	v_ashrrev_i32_e32 v3, 31, v2
	s_waitcnt lgkmcnt(0)
; __device__ __forceinline__ void gdn_scan(const Args& c, int bh, int l, LAS unsigned char* lds) {
;     ...
;     const bf16* UTb = (const bf16*)(wsl + WS_H); const bf16* GWb = (const bf16*)(wsl + WS_H + 16 * MiB); const bf16* QDb = (const bf16*)(wsl + WS_H + 32 * MiB);
;     const bf16* KDb = (const bf16*)(wsl + WS_H + 48 * MiB); const bf16* ATb = (const bf16*)(wsl + WS_AT); const float* GLb = (const float*)(wsl + WS_GL);
;     const bf16* Pz = (const bf16*)(wsl + WS_P) + GDN_BASE + 1536 + h * 128;
;     bf16* MX = (bf16*)(wsl + WS_MIXED) + 512 + h * 128;
;     f32x4 S[8];
; #pragma unroll
;     for (int ib = 0; ib < 8; ++ib) S[ib] = (f32x4){0.f, 0.f, 0.f, 0.f};
;     u32x4v pw[2], pq[2], pz[2], pk[2], pa; u32x2v pu[4]; float pgl;
;     const int r16 = tid >> 4, c16 = tid & 15, r8 = tid >> 3, c8 = tid & 7;
;     ...
;     GDN_PREFETCH(0);
	v_lshl_add_u64 v[2:3], v[2:3], 2, s[4:5]
	s_add_u32 s4, s2, 0x7800000
	s_addc_u32 s5, s3, 0
	s_add_u32 s12, s2, 0x9800000
	s_addc_u32 s13, s3, 0
	s_add_u32 s6, s2, 0x8800000
	s_addc_u32 s7, s3, 0
	v_and_b32_e32 v48, 15, v4
	s_add_u32 s16, s4, s14
	s_addc_u32 s17, s5, 0
	v_lshlrev_b32_e32 v0, 4, v48
	v_lshl_add_u64 v[10:11], s[16:17], 0, v[0:1]
	s_add_u32 s16, s6, s14
	s_addc_u32 s17, s7, 0
	v_ashrrev_i32_e32 v86, 4, v4
	v_lshl_add_u64 v[18:19], s[16:17], 0, v[0:1]
	v_readlane_b32 s16, v253, 23
	v_ashrrev_i32_e32 v87, 31, v86
	v_readlane_b32 s17, v253, 24
	v_readlane_b32 s11, v253, 25
	global_load_dword v130, v[2:3], off
	v_lshl_add_u64 v[12:13], v[86:87], 0, s[16:17]
	s_add_u32 s16, s2, s11
	s_addc_u32 s17, s3, 0
	v_lshl_add_u64 v[2:3], s[16:17], 0, v[0:1]
	s_mov_b64 s[18:19], 0xa801a80
	v_lshl_add_u64 v[88:89], v[2:3], 0, s[18:19]
	s_add_u32 s18, s12, s14
	v_lshlrev_b32_e32 v2, 4, v4
	s_addc_u32 s19, s13, 0
	v_and_b32_e32 v40, 0x70, v2
	v_mov_b32_e32 v41, v1
	v_lshl_add_u64 v[26:27], s[18:19], 0, v[40:41]
	v_mad_u64_u32 v[34:35], s[18:19], v12, s27, v[88:89]
	s_add_u32 s18, s2, 0x6800000
	s_addc_u32 s19, s3, 0
	v_ashrrev_i32_e32 v39, 3, v4
	s_add_u32 s20, s2, 0x100000
	v_lshlrev_b32_e32 v90, 6, v39
	s_addc_u32 s21, s3, 0
	v_readlane_b32 s24, v251, 62
	v_ashrrev_i32_e32 v91, 31, v90
	v_readlane_b32 s25, v251, 63
	s_add_u32 s24, s20, s24
	v_lshlrev_b32_e32 v14, 7, v86
	v_lshlrev_b64 v[42:43], 1, v[90:91]
	s_addc_u32 s25, s21, s25
	v_ashrrev_i32_e32 v15, 31, v14
	v_lshl_add_u64 v[28:29], s[24:25], 0, v[42:43]
	v_readlane_b32 s24, v252, 0
	v_lshlrev_b32_e32 v36, 6, v38
	v_lshlrev_b64 v[92:93], 1, v[14:15]
	v_add_u32_e32 v14, 0x1000, v14
	v_readlane_b32 s25, v252, 1
	s_add_u32 s24, s18, s24
	v_ashrrev_i32_e32 v37, 31, v36
	v_bfe_u32 v49, v4, 4, 2
	v_ashrrev_i32_e32 v15, 31, v14
	s_mov_b32 s11, 0x70000
	v_add_u32_e32 v96, 0x1000, v90
	s_addc_u32 s25, s19, s25
	v_lshlrev_b64 v[44:45], 1, v[36:37]
	v_mad_i32_i24 v35, v13, s27, v35
	v_lshlrev_b64 v[94:95], 1, v[14:15]
	v_add_co_u32_e32 v22, vcc, s11, v34
	v_ashrrev_i32_e32 v97, 31, v96
	v_lshl_add_u64 v[36:37], s[24:25], 0, v[44:45]
	v_lshlrev_b32_e32 v98, 3, v49
	v_mov_b32_e32 v99, v1
	v_readlane_b32 s24, v253, 0
	v_lshl_add_u64 v[2:3], v[10:11], 0, v[92:93]
	v_lshl_add_u64 v[6:7], v[18:19], 0, v[92:93]
	v_lshl_add_u64 v[12:13], v[26:27], 0, v[42:43]
	v_lshl_add_u64 v[14:15], v[10:11], 0, v[94:95]
	v_lshl_add_u64 v[18:19], v[18:19], 0, v[94:95]
	v_addc_co_u32_e32 v23, vcc, 0, v35, vcc
	v_lshl_add_u64 v[26:27], v[96:97], 1, v[26:27]
	v_lshl_add_u64 v[30:31], v[28:29], 0, v[40:41]
	v_lshl_add_u64 v[36:37], v[36:37], 0, v[98:99]
	v_readlane_b32 s25, v253, 1
	s_add_u32 s11, s2, s24
	flat_load_dwordx4 v[2:5], v[2:3]
	flat_load_dwordx4 v[6:9], v[6:7]
	flat_load_dwordx4 v[10:13], v[12:13]
	flat_load_dwordx4 v[14:17], v[14:15]
	flat_load_dwordx4 v[18:21], v[18:19]
	flat_load_dwordx4 v[22:25], v[22:23]
	flat_load_dwordx4 v[26:29], v[26:27]
	flat_load_dwordx4 v[30:33], v[30:31]
	flat_load_dwordx2 v[128:129], v[36:37]
	flat_load_dwordx2 v[126:127], v[36:37] offset:32
	flat_load_dwordx2 v[124:125], v[36:37] offset:64
	flat_load_dwordx2 v[122:123], v[36:37] offset:96
	s_addc_u32 s14, s3, s25
	v_mov_b32_e32 v36, s11
	s_mov_b32 s11, 0x900000
	v_mov_b32_e32 v37, s14
	v_add_co_u32_e32 v46, vcc, s11, v36
	s_movk_i32 s14, 0x90
	s_nop 0
	v_addc_co_u32_e32 v47, vcc, 0, v37, vcc
	flat_load_dwordx4 v[34:37], v[34:35]
	flat_load_dword v120, v[46:47]
	s_movk_i32 s25, 0x110
	v_mul_lo_u32 v51, v39, s14
	v_mul_lo_u32 v39, v38, s25
	v_add3_u32 v132, 0, v39, v98
	v_lshlrev_b32_e32 v39, 7, v38
	v_readlane_b32 s24, v253, 32
	v_lshl_add_u64 v[42:43], s[20:21], 0, v[42:43]
	v_sub_u32_e32 v133, v132, v39
	v_ashrrev_i32_e32 v39, 31, v38
	v_lshl_add_u64 v[102:103], v[42:43], 0, v[40:41]
	v_lshl_add_u64 v[104:105], s[4:5], 0, v[0:1]
	v_lshl_add_u32 v43, v38, 1, s24
	v_lshl_add_u64 v[38:39], v[38:39], 1, s[16:17]
	s_mov_b64 s[4:5], 0x18800400
	v_readlane_b32 s22, v253, 31
	s_and_b32 s1, s1, 0x3fffffc0
	v_lshl_add_u64 v[110:111], v[38:39], 0, s[4:5]
	v_mul_lo_u32 v38, v86, s25
	v_add_u32_e32 v46, s22, v0
	v_add_u32_e32 v47, s24, v0
	s_add_i32 s11, 0, 0x1c000
	v_readlane_b32 s14, v253, 33
	v_lshl_add_u64 v[106:107], s[6:7], 0, v[0:1]
	s_lshl_b32 s1, s1, 2
	v_readlane_b32 s6, v253, 34
	v_add3_u32 v134, 0, v0, v38
	v_add_u32_e32 v0, 0x2200, v38
	v_add_u32_e32 v50, s11, v40
	v_add3_u32 v131, s14, v51, v40
	v_lshl_add_u64 v[100:101], s[12:13], 0, v[40:41]
	v_lshl_add_u64 v[40:41], s[18:19], 0, v[44:45]
	s_add_i32 s1, s6, s1
	v_add_u32_e32 v137, v46, v0
	v_add_u32_e32 v138, v47, v0
	v_mul_u32_u24_e32 v0, 0x88, v48
	v_readlane_b32 s4, v252, 63
	v_lshl_add_u64 v[108:109], v[40:41], 0, v[98:99]
	v_lshlrev_b32_e32 v99, 4, v49
	v_lshlrev_b32_e32 v0, 1, v0
	v_lshl_or_b32 v39, v49, 2, 1
	s_add_u32 s2, s2, s4
	v_readlane_b32 s4, v253, 2
	v_readlane_b32 s5, v253, 5
	v_add_u32_e32 v40, s14, v99
	v_add_u32_e32 v41, s11, v99
	v_add_u32_e32 v135, v46, v38
	v_add_u32_e32 v136, v47, v38
	v_add3_u32 v139, 0, v99, v0
	v_add3_u32 v140, s22, v99, v0
	v_mul_u32_u24_e32 v0, 0x90, v48
	v_add_u32_e32 v145, s6, v99
	v_mul_u32_u24_e32 v38, 0x440, v49
	v_mul_u32_u24_e32 v39, 0x110, v39
	s_addc_u32 s3, s3, s4
	v_readlane_b32 s4, v253, 3
	v_mov_b32_e32 v42, 0
	s_mov_b32 s12, s5
	v_readlane_b32 s5, v252, 62
	s_mov_b32 s0, 0
	v_cmp_eq_u32_e32 vcc, 0, v48
	v_add_u32_e32 v141, 0x1100, v139
	v_add_u32_e32 v142, 0x1100, v140
	v_add_u32_e32 v143, 0x2200, v140
	v_add_u32_e32 v144, 0x3300, v140
	v_add_u32_e32 v146, 64, v145
	v_add_u32_e32 v147, 0x80, v145
	v_add_u32_e32 v148, 0xc0, v145
	v_lshl_add_u32 v149, v49, 13, s4
	v_add_u32_e32 v150, v50, v51
	v_add_u32_e32 v151, v40, v0
	v_add_u32_e32 v152, v41, v0
	v_add_u32_e32 v153, v43, v38
	v_add_u32_e32 v154, v43, v39
	v_readlane_b32 s4, v253, 6
	s_mov_b32 s14, s5
	v_mov_b32_e32 v43, v42
	v_mov_b32_e32 v44, v42
	v_mov_b32_e32 v45, v42
	v_mov_b32_e32 v50, v42
	v_mov_b32_e32 v51, v42
	v_mov_b32_e32 v52, v42
	v_mov_b32_e32 v53, v42
	v_mov_b32_e32 v46, v42
	v_mov_b32_e32 v47, v42
	v_mov_b32_e32 v48, v42
	v_mov_b32_e32 v49, v42
	v_mov_b32_e32 v38, v42
	v_mov_b32_e32 v39, v42
	v_mov_b32_e32 v40, v42
	v_mov_b32_e32 v41, v42
	v_mov_b32_e32 v54, v42
	v_mov_b32_e32 v55, v42
	v_mov_b32_e32 v56, v42
	v_mov_b32_e32 v57, v42
	v_mov_b32_e32 v58, v42
	v_mov_b32_e32 v59, v42
	v_mov_b32_e32 v60, v42
	v_mov_b32_e32 v61, v42
	v_mov_b32_e32 v62, v42
	v_mov_b32_e32 v63, v42
	v_mov_b32_e32 v64, v42
	v_mov_b32_e32 v65, v42
	v_mov_b32_e32 v66, v42
	v_mov_b32_e32 v67, v42
	v_mov_b32_e32 v68, v42
	v_mov_b32_e32 v69, v42
	s_waitcnt vmcnt(0) lgkmcnt(0)
	v_mov_b64_e32 v[112:113], v[122:123]
	v_mov_b64_e32 v[114:115], v[124:125]
	v_mov_b64_e32 v[116:117], v[126:127]
	v_mov_b64_e32 v[118:119], v[128:129]
	s_branch .LBB0_194

; #define LAS __attribute__((address_space(3)))
; __device__ __forceinline__ unsigned pk2(float lo, float hi) { f32x2_t v = {lo, hi}; bf16x2_t b = __builtin_convertvector(v, bf16x2_t); return __builtin_bit_cast(unsigned, b); }
; __device__ __forceinline__ void gdn_scan(const Args& c, int bh, int l, LAS unsigned char* lds) {
;     ...
;     for (int ch = 0; ch < 32; ++ch) {
;         const size_t tok0 = (size_t)b * T + 64 * ch;
;         __syncthreads();
; #pragma unroll
;         for (int i = 0; i < 2; ++i) {
;             *(LAS u32x4v*)(Wl + (r16 + 32 * i) * 136 + c16 * 8) = pw[i]; *(LAS u32x4v*)(Ql + (r16 + 32 * i) * 136 + c16 * 8) = pq[i];
;             *(LAS u32x4v*)(Zl + (r16 + 32 * i) * 136 + c16 * 8) = pz[i]; *(LAS u32x4v*)(Kl + (r8 + 64 * i) * 72 + c8 * 8) = pk[i];
;         }
;         *(LAS u32x4v*)(Al + r8 * 72 + c8 * 8) = pa;
;         u32x2v uc[4];
; #pragma unroll
;         for (int tb = 0; tb < 4; ++tb) uc[tb] = pu[tb];
;         const float gl = pgl;
; #pragma unroll
;         for (int ib = 0; ib < 8; ++ib) { u32x2v o; o.x = pk2(S[ib][0], S[ib][1]); o.y = pk2(S[ib][2], S[ib][3]); *(LAS u32x2v*)(St + v * 136 + 16 * ib + 4 * q4) = o; }
;         if (ch + 1 < 32) GDN_PREFETCH(ch + 1);
.LBB0_194:
	v_cvt_pk_bf16_f32 v70, v38, v39
	v_cvt_pk_bf16_f32 v71, v40, v41
	v_cvt_pk_bf16_f32 v72, v46, v47
	v_cvt_pk_bf16_f32 v73, v48, v49
	s_barrier
	ds_write_b128 v134, v[2:5] offset:53248
	ds_write_b128 v135, v[6:9]
	ds_write_b128 v136, v[34:37]
	ds_write_b128 v150, v[10:13]
	ds_write_b128 v134, v[14:17] offset:61952
	ds_write_b128 v137, v[18:21]
	ds_write_b128 v138, v[22:25]
	ds_write_b128 v150, v[26:29] offset:9216
	ds_write_b128 v131, v[30:33]
	ds_write2_b64 v132, v[70:71], v[72:73] offset1:4
	v_cvt_pk_bf16_f32 v70, v50, v51
	v_cvt_pk_bf16_f32 v71, v52, v53
	v_cvt_pk_bf16_f32 v72, v42, v43
	v_cvt_pk_bf16_f32 v73, v44, v45
	ds_write2_b64 v132, v[70:71], v[72:73] offset0:8 offset1:12
	v_cvt_pk_bf16_f32 v70, v54, v55
	v_cvt_pk_bf16_f32 v71, v56, v57
	v_cvt_pk_bf16_f32 v72, v58, v59
	v_cvt_pk_bf16_f32 v73, v60, v61
	ds_write2_b64 v132, v[70:71], v[72:73] offset0:16 offset1:20
	v_cvt_pk_bf16_f32 v70, v62, v63
	v_cvt_pk_bf16_f32 v71, v64, v65
	v_cvt_pk_bf16_f32 v72, v66, v67
	v_cvt_pk_bf16_f32 v73, v68, v69
	s_cmp_eq_u32 s0, 0x3e0000
	v_mov_b32_e32 v155, v120
	ds_write2_b64 v132, v[70:71], v[72:73] offset0:24 offset1:28
	s_cbranch_scc1 .LBB0_196
	s_mov_b32 s5, s15
	s_lshl_b64 s[6:7], s[4:5], 1
	v_lshl_add_u64 v[12:13], s[14:15], 0, v[86:87]
	v_lshl_add_u64 v[10:11], v[104:105], 0, s[6:7]
	v_lshl_add_u64 v[18:19], v[106:107], 0, s[6:7]
	v_lshl_add_u64 v[26:27], v[100:101], 0, s[6:7]
	v_mad_u64_u32 v[20:21], s[6:7], v12, s27, v[88:89]
	s_mov_b32 s5, 0x70000
	v_mad_i32_i24 v21, v13, s27, v21
	v_add_co_u32_e64 v22, s[6:7], s5, v20
	s_mov_b32 s13, s15
	s_nop 0
	v_addc_co_u32_e64 v23, s[6:7], 0, v21, s[6:7]
	s_lshl_b64 s[6:7], s[12:13], 13
	s_nop 0
	v_lshl_add_u64 v[30:31], v[102:103], 0, s[6:7]
	s_lshl_b64 s[6:7], s[12:13], 14
	v_lshl_add_u64 v[2:3], v[10:11], 0, v[92:93]
	v_lshl_add_u64 v[6:7], v[18:19], 0, v[92:93]
	v_lshl_add_u64 v[12:13], v[90:91], 1, v[26:27]
	v_lshl_add_u64 v[14:15], v[10:11], 0, v[94:95]
	v_lshl_add_u64 v[18:19], v[18:19], 0, v[94:95]
	v_lshl_add_u64 v[26:27], v[96:97], 1, v[26:27]
	v_lshl_add_u64 v[70:71], v[108:109], 0, s[6:7]
	flat_load_dwordx4 v[2:5], v[2:3]
	flat_load_dwordx4 v[6:9], v[6:7]
	flat_load_dwordx4 v[34:37], v[20:21]
	flat_load_dwordx4 v[10:13], v[12:13]
	flat_load_dwordx4 v[14:17], v[14:15]
	flat_load_dwordx4 v[18:21], v[18:19]
	flat_load_dwordx4 v[22:25], v[22:23]
	flat_load_dwordx4 v[26:29], v[26:27]
	flat_load_dwordx4 v[30:33], v[30:31]
	flat_load_dwordx2 v[118:119], v[70:71]
	flat_load_dwordx2 v[116:117], v[70:71] offset:32
	flat_load_dwordx2 v[114:115], v[70:71] offset:64
	flat_load_dwordx2 v[112:113], v[70:71] offset:96
	v_mov_b64_e32 v[70:71], s[2:3]
	flat_load_dword v155, v[70:71]

; #define LAS __attribute__((address_space(3)))
; #define PF_AR(N_) do { const size_t cq_ = CQ_(N_); const bf16* ua = AHb + cq_ * 1024; const bf16* ur = RHb + cq_ * 1024; pA[0] = GLD(bf16x8, ua, oA); pA[1] = GLD(bf16x8, ua, oA + 64u); pR[0] = GLD(bf16x8, ur, oA); pR[1] = GLD(bf16x8, ur, oA + 64u); } while (0)
; #define PF_BG(N_) do { const size_t cq_ = CQ_(N_); const bf16* ub = BKb + cq_ * 2048; _Pragma("unroll") for (int jb = 0; jb < 4; ++jb) pB[jb] = GLD(bf16x8, ub, oB + (unsigned)jb * 1024u); pG = GLD(float, G15b + cq_ * 64, oG); } while (0)
; __device__ __forceinline__ void rwkv_scan(const Args& c, int bx, int l, LAS unsigned char* lds, bool dry) {
;     int tid_ = threadIdx.x; asm volatile("" : "+v"(tid_)); unsigned char* wsl = c.ws; asm volatile("" : "+s"(wsl)); int z_ = 0; asm volatile("" : "+s"(z_));
;     const int tid = tid_, L = tid & 63, w = __builtin_amdgcn_readfirstlane(tid >> 6), r = L & 15, q4 = L >> 4;
;     const int hh = bx * 2 + (w >> 2), wq = w & 3, b = hh >> 3, h = hh & 7;
;     LAS unsigned char* wl = lds + w * 5376;
;     LAS bf16* St = (LAS bf16*)wl;
;     LAS bf16* UVl = (LAS bf16*)wl;
;     LAS float* Xl = (LAS float*)(wl + 2304);
;     LAS float* Nl = (LAS float*)(wl + 3392);
;     LAS float* Gl = (LAS float*)(wl + 4416);
;     LAS bf16* XRl = (LAS bf16*)(wl + 4672);
;     const bf16* AHb = (const bf16*)(wsl + WS_RW); const bf16* RHb = (const bf16*)(wsl + WS_RW + 16 * MiB); const bf16* BKb = (const bf16*)(wsl + WS_RW + 32 * MiB);
;     const float* NMb = (const float*)(wsl + WS_RW + 64 * MiB); const bf16* NRb = (const bf16*)(wsl + WS_RW + 98 * MiB); const float* G15b = (const float*)(wsl + WS_RW + 96 * MiB);
;     const bf16* VNb = (const bf16*)(wsl + WS_WR0); const bf16* VBb = (const bf16*)(wsl + WS_WR1);
;     float* Yb = (float*)(wsl + WS_P) + (size_t)b * T * (PW / 2) + h * 64 + 16 * wq;
;     f32x4 ST[4];
; #pragma unroll
;     for (int jb = 0; jb < 4; ++jb) ST[jb] = (f32x4){0.f, 0.f, 0.f, 0.f};
;     bf16x8 pA[2], pR[2], pB[4], pNR; f32x4 pN; u32x2v pC; u32x4v pVB[2]; float pG;
;     const int row = L & 15;
;     ...
;     const unsigned oA = (unsigned)(r * 64 + q4 * 8) * 2u, oB = (unsigned)(r * 32 + q4 * 8) * 2u, oC = (unsigned)(r * 64 + 16 * wq + 4 * q4) * 2u, oN = (unsigned)L * 16u, oV = (unsigned)(16 * wq + row) * 32u, oG = (unsigned)L * 4u;
;     ...
;     PF_AR(0); PF_C(0); PF_BG(0); PF_N(0); PF_NR(0); PF_VB(0);
.LBB0_230:
	s_andn2_b64 vcc, exec, s[2:3]
	s_cbranch_vccnz .LBB0_236
	v_readlane_b32 s0, v252, 57
	v_mov_b32_e32 v2, v179
	v_readlane_b32 s2, v252, 59
	v_readlane_b32 s3, v252, 60
	s_mov_b32 s0, s15
	v_readlane_b32 s4, v251, 60
	v_readfirstlane_b32 s14, v2
	s_ashr_i32 s0, s14, 8
	s_add_i32 s0, s0, s4
	s_ashr_i32 s4, s0, 3
	v_readlane_b32 s1, v252, 58
	s_ashr_i32 s5, s4, 31
	s_ashr_i32 s1, s14, 6
	s_and_b32 s22, s0, 7
	s_lshl_b64 s[12:13], s[4:5], 10
	v_and_b32_e32 v137, 15, v2
	s_mul_i32 s0, s1, 0x1500
	s_lshl_b32 s1, s1, 4
	v_bfe_u32 v45, v2, 4, 2
	s_or_b32 s12, s12, s22
	s_add_i32 s0, s0, 0
	s_and_b32 s1, s1, 48
	v_lshlrev_b32_e32 v3, 6, v137
	v_lshlrev_b32_e32 v154, 3, v45
	s_lshl_b64 s[16:17], s[12:13], 10
	s_lshl_b64 s[18:19], s[12:13], 11
	v_or_b32_e32 v0, v154, v3
	v_lshlrev_b32_e32 v141, 2, v45
	s_add_u32 s18, s2, s18
	v_and_b32_e32 v44, 63, v2
	v_lshlrev_b32_e32 v0, 1, v0
	v_and_b32_e32 v46, 48, v2
	v_or3_b32 v2, v3, s1, v141
	s_addc_u32 s19, s3, s19
	v_or_b32_e32 v34, v3, v46
	v_lshlrev_b32_e32 v36, 1, v2
	v_lshl_add_u64 v[2:3], s[18:19], 0, v[0:1]
	s_mov_b32 s11, 0x1d800000
	s_mov_b64 s[20:21], 0x1d800000
	v_add_co_u32_e32 v6, vcc, s11, v2
	v_lshl_add_u64 v[4:5], v[2:3], 0, s[20:21]
	s_nop 0
	v_addc_co_u32_e32 v7, vcc, 0, v3, vcc
	s_mov_b64 s[20:21], 0x1e800000
	s_mov_b32 s11, 0x1e800000
	flat_load_dwordx4 v[26:29], v[6:7]
	flat_load_dwordx4 v[22:25], v[4:5] offset:64
	v_lshl_add_u64 v[4:5], v[2:3], 0, s[20:21]
	v_add_co_u32_e32 v2, vcc, s11, v2
	v_mov_b32_e32 v37, v1
	s_nop 0
	v_addc_co_u32_e32 v3, vcc, 0, v3, vcc
	s_lshl_b64 s[20:21], s[12:13], 8
	flat_load_dwordx4 v[18:21], v[2:3]
	flat_load_dwordx4 v[14:17], v[4:5] offset:64
	v_lshl_add_u64 v[2:3], s[18:19], 0, v[36:37]
	s_mov_b32 s11, 0x25800000
	s_add_u32 s20, s2, s20
	v_lshlrev_b32_e32 v38, 2, v44
	v_add_co_u32_e32 v2, vcc, s11, v2
	s_addc_u32 s21, s3, s21
	v_mov_b32_e32 v39, v1
	s_lshl_b64 s[12:13], s[12:13], 12
	v_addc_co_u32_e32 v3, vcc, 0, v3, vcc
	v_lshl_add_u64 v[4:5], s[20:21], 0, v[38:39]
	s_mov_b32 s11, 0x23800000
	s_add_u32 s12, s2, s12
	v_lshlrev_b32_e32 v40, 4, v44
	v_add_co_u32_e32 v4, vcc, s11, v4
	s_addc_u32 s13, s3, s13
	v_mov_b32_e32 v41, v1
	v_addc_co_u32_e32 v5, vcc, 0, v5, vcc
	flat_load_dwordx2 v[114:115], v[2:3]
	flat_load_dword v153, v[4:5]
	v_lshl_add_u64 v[2:3], s[12:13], 0, v[40:41]
	s_mov_b32 s11, 0x21800000
	s_add_u32 s12, s2, s16
	v_mov_b32_e32 v35, v1
	v_add_co_u32_e32 v2, vcc, s11, v2
	s_addc_u32 s13, s3, s17
	v_or_b32_e32 v8, s1, v137
	v_addc_co_u32_e32 v3, vcc, 0, v3, vcc
	v_lshl_add_u64 v[4:5], s[12:13], 0, v[34:35]
	s_mov_b32 s11, 0x23a00000
	v_lshlrev_b32_e32 v42, 5, v8
	v_add_co_u32_e32 v4, vcc, s11, v4
	v_mov_b32_e32 v43, v1
	s_nop 0
	v_addc_co_u32_e32 v5, vcc, 0, v5, vcc
	v_lshl_add_u64 v[6:7], s[18:19], 0, v[42:43]
	s_mov_b64 s[12:13], 0x27800000
	s_mov_b32 s11, 0x27800000
	v_lshl_add_u64 v[8:9], v[6:7], 0, s[12:13]
	v_add_co_u32_e32 v6, vcc, s11, v6
	flat_load_dwordx4 v[30:33], v[2:3]
	flat_load_dwordx4 v[2:5], v[4:5]
	v_addc_co_u32_e32 v7, vcc, 0, v7, vcc
	flat_load_dwordx4 v[10:13], v[6:7]
	flat_load_dwordx4 v[6:9], v[8:9] offset:16
	v_mov_b32_e32 v37, s0
	s_movk_i32 s11, 0x90
	v_mad_u32_u24 v37, v137, s11, v37
	s_movk_i32 s12, 0xff74
	v_add_u32_e32 v155, v37, v154
	s_lshl_b32 s11, s22, 12
	v_mad_i32_i24 v37, v137, s12, v37
	s_lshl_b64 s[12:13], s[4:5], 22
	s_lshl_b32 s18, s22, 10
	s_or_b32 s11, s12, s11
	v_or_b32_e32 v116, s11, v34
	s_add_u32 s11, s11, 0x21808000
	s_mul_i32 s7, s4, 0x1c00000
	s_addc_u32 s12, s13, 0
	s_mul_hi_i32 s6, s4, 0x1c00000
	v_or_b32_e32 v118, s11, v40
	s_add_u32 s11, s7, 0xa800000
	v_add_u32_e32 v156, s0, v40
	v_mul_i32_i24_e32 v43, -12, v44
	v_mul_u32_u24_e32 v44, 0x110, v45
	v_mov_b32_e32 v119, s12
	s_addc_u32 s12, s6, 0
	v_mul_hi_u32_u24_e32 v40, 0x3800, v137
	v_mul_u32_u24_e32 v45, 0x3800, v137
	v_or_b32_e32 v121, s12, v40
	v_or_b32_e32 v40, s11, v45
	s_lshl_b32 s11, s22, 8
	v_or_b32_e32 v40, s11, v40
	s_and_b32 s12, s14, 0xc0
	v_mov_b32_e32 v117, s13
	v_or3_b32 v120, v40, s12, v46
	s_lshl_b64 s[12:13], s[4:5], 21
	s_lshl_b32 s14, s22, 11
	s_lshl_b64 s[16:17], s[4:5], 20
	s_or_b32 s12, s12, s14
	s_or_b32 s14, s16, s18
	s_add_u32 s14, s14, 0x23a02000
	s_addc_u32 s16, s17, 0
	s_lshl_b64 s[4:5], s[4:5], 18
	s_or_b32 s4, s4, s11
	s_add_u32 s4, s4, 0x23800800
	s_addc_u32 s5, s5, 0
	v_add_u32_e32 v157, s0, v46
	v_or_b32_e32 v126, s4, v38
	s_add_u32 s4, s12, 0x25804000
	v_mul_u32_u24_e32 v35, 0x90, v137
	v_sub_u32_e32 v158, v157, v154
	v_mul_u32_u24_e32 v39, 40, v137
	v_mul_u32_u24_e32 v41, 0x44, v137
	v_or_b32_e32 v124, s14, v34
	v_mov_b32_e32 v127, s5
	s_addc_u32 s5, s13, 0
	v_mov_b32_e32 v34, 0
	v_mul_u32_u24_e32 v160, 0x50, v137
	v_or_b32_e32 v122, s12, v42
	v_mov_b32_e32 v123, s13
	v_mov_b32_e32 v125, s16
	v_or_b32_e32 v128, s12, v0
	v_mov_b32_e32 v129, s13
	v_or_b32_e32 v130, s4, v36
	v_mov_b32_e32 v131, s5
	s_movk_i32 s4, 0x7f
	v_add_u32_e32 v159, v157, v35
	v_add_u32_e32 v161, v37, v44
	v_add_u32_e32 v147, v158, v39
	v_add_u32_e32 v162, s0, v41
	v_add_u32_e32 v151, v156, v43
	v_mov_b32_e32 v35, v34
	v_mov_b32_e32 v36, v34
	v_mov_b32_e32 v37, v34
	v_mov_b32_e32 v42, v34
	v_mov_b32_e32 v43, v34
	v_mov_b32_e32 v44, v34
	v_mov_b32_e32 v45, v34
	v_mov_b32_e32 v46, v34
	v_mov_b32_e32 v47, v34
	v_mov_b32_e32 v48, v34
	v_mov_b32_e32 v49, v34
	v_mov_b32_e32 v38, v34
	v_mov_b32_e32 v39, v34
	v_mov_b32_e32 v40, v34
	v_mov_b32_e32 v41, v34
	v_mov_b32_e32 v0, v34
	v_mov_b32_e32 v68, v34
	v_mov_b32_e32 v69, v34
	s_mov_b64 s[16:17], 0x2000
	s_mov_b64 s[18:19], 0x8000
	s_mov_b64 s[20:21], 0x4000
	s_waitcnt vmcnt(0)
; #define LAS __attribute__((address_space(3)))
; #define MFMA16(a, b, c) __builtin_amdgcn_mfma_f32_16x16x32_bf16(a, b, c, 0, 0, 0)
; __device__ __forceinline__ unsigned pk2(float lo, float hi) { f32x2_t v = {lo, hi}; bf16x2_t b = __builtin_convertvector(v, bf16x2_t); return __builtin_bit_cast(unsigned, b); }
; #define PF_AR(N_) do { const size_t cq_ = CQ_(N_); const bf16* ua = AHb + cq_ * 1024; const bf16* ur = RHb + cq_ * 1024; pA[0] = GLD(bf16x8, ua, oA); pA[1] = GLD(bf16x8, ua, oA + 64u); pR[0] = GLD(bf16x8, ur, oA); pR[1] = GLD(bf16x8, ur, oA + 64u); } while (0)
; #define PF_N(N_) do { pN = GLD(f32x4, NMb + CQ_(N_) * 1024, oN); } while (0)
; #define PF_C(N_) do { pC = GLD(u32x2v, VNb + CQ_(N_) * 1024, oC); } while (0)
; __device__ __forceinline__ void rwkv_scan(const Args& c, int bx, int l, LAS unsigned char* lds, bool dry) {
;     ...
;     for (int n = 0; n < T / 16; ++n) {
;         const bool more = (n + 1 < T / 16);
;         *(LAS f32x4*)(Nl + L * 4) = pN;
;         if (more) PF_N(n + 1);
; #pragma unroll
;         for (int jb = 0; jb < 4; ++jb) { u32x2v o; o.x = pk2(ST[jb][0], ST[jb][1]); o.y = pk2(ST[jb][2], ST[jb][3]); *(LAS u32x2v*)(St + r * 72 + 16 * jb + 4 * q4) = o; }
;         FENCE();
;         {
;             f32x4 xa = (f32x4){bflo(pC.x), bfhi(pC.x), bflo(pC.y), bfhi(pC.y)}, xr = (f32x4){0.f, 0.f, 0.f, 0.f};
; #pragma unroll
;             for (int ks = 0; ks < 2; ++ks) { const bf16x8 fs = *(const LAS bf16x8*)(St + r * 72 + ks * 32 + q4 * 8); xa = MFMA16(fs, pA[ks], xa); xr = MFMA16(fs, pR[ks], xr); }
; #pragma unroll
;             for (int e = 0; e < 4; ++e) Xl[(4 * q4 + e) * 17 + r] = xa[e];
;             u32x2v xo; xo.x = pk2(xr[0], xr[1]); xo.y = pk2(xr[2], xr[3]); *(LAS u32x2v*)(XRl + r * 20 + 4 * q4) = xo;
;         }
;         if (more) { PF_AR(n + 1); PF_C(n + 1); }
;         FENCE();
;         float uu[16];
;         {
;             const LAS float* xrow = Xl + row * 17;
; #pragma unroll
;             for (int t = 0; t < 16; ++t) uu[t] = xrow[t];
; #pragma unroll
;             for (int s0 = 0; s0 < 15; ++s0) {
; #pragma unroll
;                 for (int t4 = (s0 + 1) & ~3; t4 < 16; t4 += 4) {
;                     const f32x4 nab = *(const LAS f32x4*)(Nl + s0 * 16 + t4);
; #pragma unroll
;                     for (int e = 0; e < 4; ++e) if (t4 + e > s0) uu[t4 + e] += uu[s0] * nab[e];
;                 }
;             }
;         }
.LBB0_232:
	v_lshl_add_u64 v[50:51], s[2:3], 0, v[116:117]
	s_mov_b32 s5, 0x1f800000
	v_add_co_u32_e32 v50, vcc, s5, v50
	v_cvt_pk_bf16_f32 v66, v42, v43
	s_nop 0
	v_addc_co_u32_e32 v51, vcc, 0, v51, vcc
	global_load_dwordx4 v[62:65], v[50:51], off
	global_load_dwordx4 v[58:61], v[50:51], off offset:1024
	global_load_dwordx4 v[54:57], v[50:51], off offset:2048
	global_load_dwordx4 v[50:53], v[50:51], off offset:3072
	s_waitcnt vmcnt(14) lgkmcnt(0)
	ds_write_b128 v156, v[30:33] offset:3392
	v_lshl_add_u64 v[30:31], s[2:3], 0, v[118:119]
	v_cvt_pk_bf16_f32 v67, v44, v45
	v_cvt_pk_bf16_f32 v70, v46, v47
	v_cvt_pk_bf16_f32 v71, v48, v49
	global_load_dwordx4 v[30:33], v[30:31], off
	ds_write2_b64 v155, v[66:67], v[70:71] offset1:4
	v_cvt_pk_bf16_f32 v66, v38, v39
	v_cvt_pk_bf16_f32 v67, v40, v41
	v_cvt_pk_bf16_f32 v70, v34, v0
	v_cvt_pk_bf16_f32 v71, v68, v69
	ds_write2_b64 v155, v[66:67], v[70:71] offset0:8 offset1:12
	ds_read_b128 v[70:73], v159
	s_waitcnt vmcnt(10)
	v_lshlrev_b32_e32 v66, 16, v114
	v_and_b32_e32 v67, 0xffff0000, v114
	v_lshlrev_b32_e32 v68, 16, v115
	v_and_b32_e32 v69, 0xffff0000, v115
	s_waitcnt lgkmcnt(0)
	v_mfma_f32_16x16x32_bf16 v[18:21], v[70:73], v[18:21], 0
	v_add_u32_e32 v163, 0x800, v161
	s_mov_b32 s5, 0x1d804000
	v_add_u32_e32 v164, 0x900, v162
	v_mfma_f32_16x16x32_bf16 v[26:29], v[70:73], v[26:29], v[66:69]
	v_mov_b32_e32 v172, s0
	v_add_u32_e32 v165, 0x908, v162
	v_add_u32_e32 v166, 0x938, v162
	ds_read_b128 v[66:69], v159 offset:64
	s_waitcnt lgkmcnt(0)
	v_mfma_f32_16x16x32_bf16 v[14:17], v[66:69], v[14:17], v[18:21]
	v_add_u32_e32 v168, 0x910, v162
	v_add_u32_e32 v167, 0x918, v162
	v_add_u32_e32 v169, 0x920, v162
	v_mfma_f32_16x16x32_bf16 v[22:25], v[66:69], v[22:25], v[26:29]
	s_nop 3
	v_cvt_pk_bf16_f32 v14, v14, v15
	v_cvt_pk_bf16_f32 v15, v16, v17
	s_nop 1
	ds_write2_b32 v163, v22, v23 offset0:64 offset1:81
	ds_write2_b32 v163, v24, v25 offset0:98 offset1:115
	ds_write_b64 v147, v[14:15] offset:4672
	v_lshl_add_u64 v[14:15], s[2:3], 0, v[128:129]
	v_add_co_u32_e32 v16, vcc, s5, v14
	s_mov_b32 s5, 0x1e804000
	s_nop 0
	v_addc_co_u32_e32 v17, vcc, 0, v15, vcc
	v_add_co_u32_e32 v14, vcc, s5, v14
	v_lshl_add_u64 v[66:67], s[2:3], 0, v[130:131]
	s_nop 0
	v_addc_co_u32_e32 v15, vcc, 0, v15, vcc
	global_load_dwordx4 v[26:29], v[16:17], off
	global_load_dwordx4 v[22:25], v[16:17], off offset:64
	global_load_dwordx4 v[18:21], v[14:15], off
	global_load_dwordx4 v[14:17], v[14:15], off offset:64
	v_add_u32_e32 v170, 0x928, v162
	global_load_dwordx2 v[114:115], v[66:67], off
	ds_read2_b32 v[132:133], v164 offset1:1
	ds_read_b128 v[70:73], v172 offset:3392
	ds_read_b128 v[80:83], v172 offset:3408
	ds_read_b128 v[96:99], v172 offset:3424
	ds_read_b128 v[66:69], v172 offset:3440
	v_add_u32_e32 v171, 0x930, v162
	s_mov_b32 s5, 0x27804000
	s_mov_b64 s[12:13], 0x38000
	s_waitcnt lgkmcnt(0)
	v_fma_f32 v0, v132, v71, v133
	ds_read2_b32 v[70:71], v165 offset1:1
	s_add_i32 s4, s4, -1
	v_lshl_add_u64 v[116:117], v[116:117], 0, s[18:19]
	v_lshl_add_u64 v[118:119], v[118:119], 0, s[18:19]
	v_lshl_add_u64 v[128:129], v[128:129], 0, s[20:21]
	s_waitcnt lgkmcnt(0)
	v_pk_fma_f32 v[70:71], v[132:133], v[72:73], v[70:71] op_sel_hi:[0,1,1]
	v_add_u32_e32 v72, 0x800, v172
	ds_read2_b64 v[84:87], v72 offset0:177 offset1:211
	ds_read_b128 v[88:91], v172 offset:3472
	ds_read_b128 v[100:103], v172 offset:3488
	ds_read_b128 v[72:75], v172 offset:3504
	v_lshl_add_u64 v[130:131], v[130:131], 0, s[20:21]
	s_cmp_lg_u32 s4, 0
	s_waitcnt lgkmcnt(0)
	v_pk_fma_f32 v[134:135], v[0:1], v[84:85], v[70:71] op_sel_hi:[0,1,1]
	ds_read2_b32 v[70:71], v166 offset1:1
	s_waitcnt lgkmcnt(0)
	v_pk_fma_f32 v[68:69], v[132:133], v[68:69], v[70:71] op_sel_hi:[0,1,1]
	v_pk_fma_f32 v[142:143], v[0:1], v[74:75], v[68:69] op_sel_hi:[0,1,1]
	ds_read_b128 v[68:71], v172 offset:3520
	s_waitcnt lgkmcnt(0)
	v_fma_f32 v136, v134, v71, v135
	ds_read_b128 v[92:95], v172 offset:3536
	ds_read_b128 v[104:107], v172 offset:3552
	ds_read_b128 v[68:71], v172 offset:3568
	ds_read_b128 v[108:111], v172 offset:3600
	ds_read2_b32 v[74:75], v168 offset1:1
	s_waitcnt lgkmcnt(0)
	v_pk_fma_f32 v[74:75], v[132:133], v[80:81], v[74:75] op_sel_hi:[0,1,1]
	v_pk_fma_f32 v[74:75], v[0:1], v[88:89], v[74:75] op_sel_hi:[0,1,1]
	v_pk_fma_f32 v[74:75], v[134:135], v[92:93], v[74:75] op_sel_hi:[0,1,1]
	v_pk_fma_f32 v[138:139], v[136:137], v[108:109], v[74:75] op_sel_hi:[0,1,1]
	ds_read_b128 v[174:177], v172 offset:3616
	ds_read_b128 v[74:77], v172 offset:3632
	ds_read_b128 v[184:187], v172 offset:3664
	ds_read_b128 v[204:207], v172 offset:3680
	ds_read_b128 v[78:81], v172 offset:3696
	ds_read2_b32 v[84:85], v167 offset1:1
	s_waitcnt lgkmcnt(0)
	v_fma_f32 v140, v138, v185, v139
	v_pk_fma_f32 v[82:83], v[132:133], v[82:83], v[84:85] op_sel_hi:[0,1,1]
	v_pk_fma_f32 v[82:83], v[0:1], v[90:91], v[82:83] op_sel_hi:[0,1,1]
	v_pk_fma_f32 v[82:83], v[134:135], v[94:95], v[82:83] op_sel_hi:[0,1,1]
	v_pk_fma_f32 v[82:83], v[136:137], v[110:111], v[82:83] op_sel_hi:[0,1,1]
	v_pk_fma_f32 v[82:83], v[138:139], v[186:187], v[82:83] op_sel_hi:[0,1,1]
	v_pk_fma_f32 v[144:145], v[140:141], v[86:87], v[82:83] op_sel_hi:[0,1,1]
	ds_read_b128 v[108:111], v172 offset:3744
	ds_read_b128 v[82:85], v172 offset:3760
	ds_read_b128 v[86:89], v172 offset:3792
	s_waitcnt lgkmcnt(0)
	v_fma_f32 v146, v144, v89, v145
	ds_read_b128 v[184:187], v172 offset:3808
	ds_read_b128 v[86:89], v172 offset:3824
	ds_read_b128 v[208:211], v172 offset:3872
	ds_read2_b32 v[90:91], v169 offset1:1
	s_waitcnt lgkmcnt(0)
; #define LAS __attribute__((address_space(3)))
; #define MFMA16(a, b, c) __builtin_amdgcn_mfma_f32_16x16x32_bf16(a, b, c, 0, 0, 0)
; __device__ __forceinline__ unsigned pk2(float lo, float hi) { f32x2_t v = {lo, hi}; bf16x2_t b = __builtin_convertvector(v, bf16x2_t); return __builtin_bit_cast(unsigned, b); }
; #define PF_BG(N_) do { const size_t cq_ = CQ_(N_); const bf16* ub = BKb + cq_ * 2048; _Pragma("unroll") for (int jb = 0; jb < 4; ++jb) pB[jb] = GLD(bf16x8, ub, oB + (unsigned)jb * 1024u); pG = GLD(float, G15b + cq_ * 64, oG); } while (0)
; #define PF_NR(N_) do { pNR = GLD(bf16x8, NRb + CQ_(N_) * 512, oB); } while (0)
; #define PF_VB(N_) do { const bf16* uv = VBb + CQ_(N_) * 1024; pVB[0] = GLD(u32x4v, uv, oV); pVB[1] = GLD(u32x4v, uv, oV + 16u); } while (0)
; #define FENCE() asm volatile("" ::: "memory")
; __device__ __forceinline__ void rwkv_scan(const Args& c, int bx, int l, LAS unsigned char* lds, bool dry) {
;     ...
;             for (int s0 = 0; s0 < 15; ++s0) {
; #pragma unroll
;                 for (int t4 = (s0 + 1) & ~3; t4 < 16; t4 += 4) {
;                     const f32x4 nab = *(const LAS f32x4*)(Nl + s0 * 16 + t4);
; #pragma unroll
;                     for (int e = 0; e < 4; ++e) if (t4 + e > s0) uu[t4 + e] += uu[s0] * nab[e];
;                 }
;             }
;         }
;         FENCE();
; #pragma unroll
;         for (int g = 0; g < 2; ++g) { u32x4v o; o.x = pk2(uu[8 * g], uu[8 * g + 1]); o.y = pk2(uu[8 * g + 2], uu[8 * g + 3]); o.z = pk2(uu[8 * g + 4], uu[8 * g + 5]); o.w = pk2(uu[8 * g + 6], uu[8 * g + 7]); *(LAS u32x4v*)(UVl + row * 40 + 8 * g) = o;
;             *(LAS u32x4v*)(UVl + row * 40 + 16 + 8 * g) = pVB[g]; }
;         Gl[L] = pG;
;         FENCE();
;         {
;             const bf16x8 fu = *(const LAS bf16x8*)(UVl + r * 40 + q4 * 8);
; #pragma unroll
;             for (int jb = 0; jb < 4; ++jb) { const f32x4 cG = *(const LAS f32x4*)(Gl + 16 * jb + 4 * q4); ST[jb] = MFMA16(pB[jb], fu, ST[jb] * cG); }
;             const u32x2v xo = *(const LAS u32x2v*)(XRl + r * 20 + 4 * q4);
;             const f32x4 yv = MFMA16(fu, pNR, ((f32x4){bflo(xo.x), bfhi(xo.x), bflo(xo.y), bfhi(xo.y)}));
;             if (!dry) *(f32x4*)(Yb + ((size_t)n * 16 + r) * (PW / 2) + 4 * q4) = yv;
;         }
;         FENCE();
;         if (more) { PF_BG(n + 1); PF_NR(n + 1); PF_VB(n + 1); }
	v_pk_fma_f32 v[90:91], v[132:133], v[96:97], v[90:91] op_sel_hi:[0,1,1]
	v_pk_fma_f32 v[90:91], v[0:1], v[100:101], v[90:91] op_sel_hi:[0,1,1]
	v_pk_fma_f32 v[90:91], v[134:135], v[104:105], v[90:91] op_sel_hi:[0,1,1]
	v_pk_fma_f32 v[90:91], v[136:137], v[174:175], v[90:91] op_sel_hi:[0,1,1]
	v_pk_fma_f32 v[90:91], v[138:139], v[204:205], v[90:91] op_sel_hi:[0,1,1]
	v_pk_fma_f32 v[90:91], v[140:141], v[108:109], v[90:91] op_sel_hi:[0,1,1]
	v_pk_fma_f32 v[90:91], v[144:145], v[184:185], v[90:91] op_sel_hi:[0,1,1]
	v_pk_fma_f32 v[148:149], v[146:147], v[208:209], v[90:91] op_sel_hi:[0,1,1]
	ds_read_b128 v[90:93], v172 offset:3888
	ds_read_b128 v[212:215], v172 offset:3936
	ds_read_b128 v[94:97], v172 offset:3952
	ds_read2_b32 v[100:101], v170 offset1:1
	s_waitcnt lgkmcnt(0)
	v_fma_f32 v150, v148, v213, v149
	v_pk_fma_f32 v[98:99], v[132:133], v[98:99], v[100:101] op_sel_hi:[0,1,1]
	v_pk_fma_f32 v[98:99], v[0:1], v[102:103], v[98:99] op_sel_hi:[0,1,1]
	v_pk_fma_f32 v[98:99], v[134:135], v[106:107], v[98:99] op_sel_hi:[0,1,1]
	v_pk_fma_f32 v[98:99], v[136:137], v[176:177], v[98:99] op_sel_hi:[0,1,1]
	v_pk_fma_f32 v[98:99], v[138:139], v[206:207], v[98:99] op_sel_hi:[0,1,1]
	v_pk_fma_f32 v[98:99], v[140:141], v[110:111], v[98:99] op_sel_hi:[0,1,1]
	v_pk_fma_f32 v[98:99], v[144:145], v[186:187], v[98:99] op_sel_hi:[0,1,1]
	v_pk_fma_f32 v[98:99], v[146:147], v[210:211], v[98:99] op_sel_hi:[0,1,1]
	v_pk_fma_f32 v[102:103], v[148:149], v[214:215], v[98:99] op_sel_hi:[0,1,1]
	v_add_u32_e32 v98, 0xc00, v172
	ds_read2_b64 v[98:101], v98 offset0:117 offset1:151
	s_waitcnt lgkmcnt(0)
	v_pk_fma_f32 v[98:99], v[150:151], v[98:99], v[102:103] op_sel_hi:[0,1,1]
	ds_read_b128 v[102:105], v172 offset:4016
	ds_read_b128 v[106:109], v172 offset:4064
	s_waitcnt lgkmcnt(0)
	v_fma_f32 v152, v98, v109, v99
	ds_read_b128 v[106:109], v172 offset:4080
	ds_read_b128 v[110:113], v172 offset:4144
	ds_read2_b32 v[174:175], v171 offset1:1
	s_waitcnt lgkmcnt(0)
	v_pk_fma_f32 v[66:67], v[132:133], v[66:67], v[174:175] op_sel_hi:[0,1,1]
	v_pk_fma_f32 v[66:67], v[0:1], v[72:73], v[66:67] op_sel_hi:[0,1,1]
	v_pk_fma_f32 v[66:67], v[134:135], v[68:69], v[66:67] op_sel_hi:[0,1,1]
	v_pk_fma_f32 v[66:67], v[136:137], v[74:75], v[66:67] op_sel_hi:[0,1,1]
	v_pk_fma_f32 v[66:67], v[138:139], v[78:79], v[66:67] op_sel_hi:[0,1,1]
	v_pk_fma_f32 v[66:67], v[140:141], v[82:83], v[66:67] op_sel_hi:[0,1,1]
	v_pk_fma_f32 v[66:67], v[144:145], v[86:87], v[66:67] op_sel_hi:[0,1,1]
	v_pk_fma_f32 v[66:67], v[146:147], v[90:91], v[66:67] op_sel_hi:[0,1,1]
	v_pk_fma_f32 v[66:67], v[148:149], v[94:95], v[66:67] op_sel_hi:[0,1,1]
	v_pk_fma_f32 v[66:67], v[150:151], v[102:103], v[66:67] op_sel_hi:[0,1,1]
	v_pk_fma_f32 v[66:67], v[98:99], v[106:107], v[66:67] op_sel_hi:[0,1,1]
	v_pk_fma_f32 v[72:73], v[152:153], v[110:111], v[66:67] op_sel_hi:[0,1,1]
	ds_read_b128 v[66:69], v172 offset:4208
	s_waitcnt lgkmcnt(0)
	v_fma_f32 v74, v67, v72, v73
	v_pk_fma_f32 v[66:67], v[134:135], v[70:71], v[142:143] op_sel_hi:[0,1,1]
	v_pk_fma_f32 v[66:67], v[136:137], v[76:77], v[66:67] op_sel_hi:[0,1,1]
	v_pk_fma_f32 v[66:67], v[138:139], v[80:81], v[66:67] op_sel_hi:[0,1,1]
	v_pk_fma_f32 v[66:67], v[140:141], v[84:85], v[66:67] op_sel_hi:[0,1,1]
	v_pk_fma_f32 v[66:67], v[144:145], v[88:89], v[66:67] op_sel_hi:[0,1,1]
	v_pk_fma_f32 v[66:67], v[146:147], v[92:93], v[66:67] op_sel_hi:[0,1,1]
	v_pk_fma_f32 v[66:67], v[148:149], v[96:97], v[66:67] op_sel_hi:[0,1,1]
	v_pk_fma_f32 v[66:67], v[150:151], v[104:105], v[66:67] op_sel_hi:[0,1,1]
	v_pk_fma_f32 v[66:67], v[98:99], v[108:109], v[66:67] op_sel_hi:[0,1,1]
	v_pk_fma_f32 v[66:67], v[152:153], v[112:113], v[66:67] op_sel_hi:[0,1,1]
	v_pk_fma_f32 v[66:67], v[68:69], v[72:73], v[66:67] op_sel_hi:[1,0,1]
	v_cvt_pk_bf16_f32 v70, v138, v140
	v_pk_fma_f32 v[76:77], v[100:101], v[74:75], v[66:67] op_sel_hi:[1,0,1]
	ds_read_b128 v[66:69], v172 offset:4336
	s_waitcnt vmcnt(10) lgkmcnt(0)
	v_cvt_pk_bf16_f32 v68, v132, v0
	v_cvt_pk_bf16_f32 v71, v144, v146
	v_add_u32_e32 v66, s0, v160
	v_fma_f32 v67, v69, v76, v77
	v_cvt_pk_bf16_f32 v69, v134, v136
	ds_write_b128 v66, v[68:71]
	ds_write_b128 v66, v[10:13] offset:32
	v_cvt_pk_bf16_f32 v10, v148, v150
	v_cvt_pk_bf16_f32 v11, v98, v152
	v_cvt_pk_bf16_f32 v12, v72, v74
	v_cvt_pk_bf16_f32 v13, v76, v67
	ds_write_b128 v66, v[10:13] offset:16
	ds_write_b128 v66, v[6:9] offset:48
	ds_write_b32 v151, v153 offset:4416
	v_add_u32_e32 v67, v157, v160
	v_add_u32_e32 v0, v158, v154
	ds_read_b128 v[6:9], v67
	ds_read_b128 v[10:13], v0 offset:4416
	s_waitcnt vmcnt(6) lgkmcnt(0)
	v_pk_mul_f32 v[10:11], v[42:43], v[10:11]
	v_pk_mul_f32 v[12:13], v[44:45], v[12:13]
	s_nop 1
	v_mfma_f32_16x16x32_bf16 v[42:45], v[62:65], v[6:9], v[10:13]
	s_nop 2
	ds_read_b128 v[10:13], v0 offset:4480
	s_waitcnt lgkmcnt(0)
	v_pk_mul_f32 v[10:11], v[46:47], v[10:11]
	v_pk_mul_f32 v[12:13], v[48:49], v[12:13]
	s_nop 1
	v_mfma_f32_16x16x32_bf16 v[46:49], v[58:61], v[6:9], v[10:13]
	s_nop 2
	ds_read_b128 v[10:13], v0 offset:4544
	s_waitcnt lgkmcnt(0)
	v_pk_mul_f32 v[10:11], v[38:39], v[10:11]
	v_pk_mul_f32 v[12:13], v[40:41], v[12:13]
	s_nop 1
	v_mfma_f32_16x16x32_bf16 v[38:41], v[54:57], v[6:9], v[10:13]
	s_nop 2
	ds_read_b128 v[10:13], v0 offset:4608
	s_waitcnt lgkmcnt(0)
	v_pk_mul_f32 v[10:11], v[34:35], v[10:11]
	v_pk_mul_f32 v[12:13], v[36:37], v[12:13]
	s_nop 1
	v_mfma_f32_16x16x32_bf16 v[34:37], v[50:53], v[6:9], v[10:13]
	s_nop 2
	ds_read_b64 v[12:13], v147 offset:4672
	s_waitcnt lgkmcnt(0)
	v_lshlrev_b32_e32 v10, 16, v12
	v_and_b32_e32 v11, 0xffff0000, v12
	v_lshlrev_b32_e32 v12, 16, v13
	v_and_b32_e32 v13, 0xffff0000, v13
	v_mov_b32_e32 v0, v35
	v_mov_b32_e32 v68, v36
	v_mfma_f32_16x16x32_bf16 v[2:5], v[6:9], v[2:5], v[10:13]
	v_lshl_add_u64 v[6:7], s[2:3], 0, v[120:121]
	v_lshl_add_u64 v[120:121], v[120:121], 0, s[12:13]
	s_mov_b64 s[12:13], 0x800
	v_mov_b32_e32 v69, v37
	s_nop 3
	global_store_dwordx4 v[6:7], v[2:5], off
	v_lshl_add_u64 v[6:7], s[2:3], 0, v[122:123]
	v_add_co_u32_e32 v6, vcc, s5, v6
	v_lshl_add_u64 v[2:3], s[2:3], 0, v[126:127]
	global_load_dword v153, v[2:3], off
	v_lshl_add_u64 v[2:3], s[2:3], 0, v[124:125]
	v_addc_co_u32_e32 v7, vcc, 0, v7, vcc
	global_load_dwordx4 v[2:5], v[2:3], off
	global_load_dwordx4 v[10:13], v[6:7], off
	global_load_dwordx4 v[6:9], v[6:7], off offset:16
	v_lshl_add_u64 v[122:123], v[122:123], 0, s[20:21]
	v_lshl_add_u64 v[124:125], v[124:125], 0, s[16:17]
	v_lshl_add_u64 v[126:127], v[126:127], 0, s[12:13]
	s_cbranch_scc1 .LBB0_232
; #define LAS __attribute__((address_space(3)))
; #define MFMA16(a, b, c) __builtin_amdgcn_mfma_f32_16x16x32_bf16(a, b, c, 0, 0, 0)
; __device__ __forceinline__ unsigned pk2(float lo, float hi) { f32x2_t v = {lo, hi}; bf16x2_t b = __builtin_convertvector(v, bf16x2_t); return __builtin_bit_cast(unsigned, b); }
; #define PF_AR(N_) do { const size_t cq_ = CQ_(N_); const bf16* ua = AHb + cq_ * 1024; const bf16* ur = RHb + cq_ * 1024; pA[0] = GLD(bf16x8, ua, oA); pA[1] = GLD(bf16x8, ua, oA + 64u); pR[0] = GLD(bf16x8, ur, oA); pR[1] = GLD(bf16x8, ur, oA + 64u); } while (0)
; #define PF_N(N_) do { pN = GLD(f32x4, NMb + CQ_(N_) * 1024, oN); } while (0)
; #define PF_C(N_) do { pC = GLD(u32x2v, VNb + CQ_(N_) * 1024, oC); } while (0)
; __device__ __forceinline__ void rwkv_scan(const Args& c, int bx, int l, LAS unsigned char* lds, bool dry) {
;     ...
;     for (int n = 0; n < T / 16; ++n) {
;         const bool more = (n + 1 < T / 16);
;         *(LAS f32x4*)(Nl + L * 4) = pN;
;         if (more) PF_N(n + 1);
; #pragma unroll
;         for (int jb = 0; jb < 4; ++jb) { u32x2v o; o.x = pk2(ST[jb][0], ST[jb][1]); o.y = pk2(ST[jb][2], ST[jb][3]); *(LAS u32x2v*)(St + r * 72 + 16 * jb + 4 * q4) = o; }
;         FENCE();
;         {
;             f32x4 xa = (f32x4){bflo(pC.x), bfhi(pC.x), bflo(pC.y), bfhi(pC.y)}, xr = (f32x4){0.f, 0.f, 0.f, 0.f};
; #pragma unroll
;             for (int ks = 0; ks < 2; ++ks) { const bf16x8 fs = *(const LAS bf16x8*)(St + r * 72 + ks * 32 + q4 * 8); xa = MFMA16(fs, pA[ks], xa); xr = MFMA16(fs, pR[ks], xr); }
; #pragma unroll
;             for (int e = 0; e < 4; ++e) Xl[(4 * q4 + e) * 17 + r] = xa[e];
;             u32x2v xo; xo.x = pk2(xr[0], xr[1]); xo.y = pk2(xr[2], xr[3]); *(LAS u32x2v*)(XRl + r * 20 + 4 * q4) = xo;
;         }
;         if (more) { PF_AR(n + 1); PF_C(n + 1); }
;         FENCE();
;         float uu[16];
;         {
;             const LAS float* xrow = Xl + row * 17;
; #pragma unroll
;             for (int t = 0; t < 16; ++t) uu[t] = xrow[t];
; #pragma unroll
;             for (int s0 = 0; s0 < 15; ++s0) {
; #pragma unroll
;                 for (int t4 = (s0 + 1) & ~3; t4 < 16; t4 += 4) {
;                     const f32x4 nab = *(const LAS f32x4*)(Nl + s0 * 16 + t4);
; #pragma unroll
;                     for (int e = 0; e < 4; ++e) if (t4 + e > s0) uu[t4 + e] += uu[s0] * nab[e];
;                 }
;             }
;         }
	s_waitcnt vmcnt(0)
	ds_write_b128 v156, v[30:33] offset:3392
	v_cvt_pk_bf16_f32 v30, v42, v43
	v_cvt_pk_bf16_f32 v31, v44, v45
	v_cvt_pk_bf16_f32 v32, v46, v47
	v_cvt_pk_bf16_f32 v33, v48, v49
	ds_write2_b64 v155, v[30:31], v[32:33] offset1:4
	v_cvt_pk_bf16_f32 v30, v38, v39
	v_cvt_pk_bf16_f32 v31, v40, v41
	v_cvt_pk_bf16_f32 v32, v34, v35
	v_cvt_pk_bf16_f32 v33, v36, v37
	ds_write2_b64 v155, v[30:31], v[32:33] offset0:8 offset1:12
	ds_read_b128 v[30:33], v159
	v_lshlrev_b32_e32 v34, 16, v114
	v_and_b32_e32 v35, 0xffff0000, v114
	v_lshlrev_b32_e32 v36, 16, v115
	v_and_b32_e32 v37, 0xffff0000, v115
	s_waitcnt lgkmcnt(0)
	v_mfma_f32_16x16x32_bf16 v[18:21], v[30:33], v[18:21], 0
	v_mov_b32_e32 v51, s0
	v_add_u32_e32 v0, 0x800, v51
	s_add_u32 s2, s2, s7
	v_mfma_f32_16x16x32_bf16 v[26:29], v[30:33], v[26:29], v[34:37]
	s_addc_u32 s3, s3, s6
	s_add_u32 s2, s2, s11
	s_addc_u32 s3, s3, 0
	ds_read_b128 v[34:37], v159 offset:64
	s_waitcnt lgkmcnt(0)
	v_mfma_f32_16x16x32_bf16 v[14:17], v[34:37], v[14:17], v[18:21]
	s_lshl_b32 s1, s1, 2
	s_add_u32 s0, s2, s1
	s_addc_u32 s1, s3, 0
	v_mfma_f32_16x16x32_bf16 v[22:25], v[34:37], v[22:25], v[26:29]
	s_nop 3
	v_cvt_pk_bf16_f32 v14, v14, v15
	v_cvt_pk_bf16_f32 v15, v16, v17
	s_nop 1
	ds_write2_b32 v163, v22, v23 offset0:64 offset1:81
	ds_write2_b32 v163, v24, v25 offset0:98 offset1:115
	ds_write_b64 v147, v[14:15] offset:4672
	ds_read2_b32 v[44:45], v164 offset1:1
	ds_read_b128 v[18:21], v51 offset:3392
	ds_read_b128 v[30:33], v51 offset:3408
	ds_read2_b32 v[22:23], v165 offset1:1
	ds_read2_b64 v[40:43], v0 offset0:177 offset1:211
	ds_read_b128 v[36:39], v51 offset:3424
	ds_read_b128 v[14:17], v51 offset:3440
	s_waitcnt lgkmcnt(5)
	v_fma_f32 v0, v44, v19, v45
	s_waitcnt lgkmcnt(3)
	v_pk_fma_f32 v[18:19], v[44:45], v[20:21], v[22:23] op_sel_hi:[0,1,1]
	s_waitcnt lgkmcnt(2)
	v_pk_fma_f32 v[46:47], v[0:1], v[40:41], v[18:19] op_sel_hi:[0,1,1]
	ds_read2_b32 v[26:27], v166 offset1:1
	ds_read_b128 v[18:21], v51 offset:3504
	ds_read_b128 v[22:25], v51 offset:3520
	ds_read_b128 v[54:57], v51 offset:3472
	ds_read_b128 v[60:63], v51 offset:3488
	s_waitcnt lgkmcnt(4)
	v_pk_fma_f32 v[16:17], v[44:45], v[16:17], v[26:27] op_sel_hi:[0,1,1]
	s_waitcnt lgkmcnt(3)
	v_pk_fma_f32 v[52:53], v[0:1], v[20:21], v[16:17] op_sel_hi:[0,1,1]
	s_waitcnt lgkmcnt(2)
	v_fma_f32 v16, v46, v25, v47
	ds_read2_b32 v[24:25], v168 offset1:1
	ds_read_b128 v[68:71], v51 offset:3536
	ds_read_b128 v[72:75], v51 offset:3552
	ds_read_b128 v[20:23], v51 offset:3568
	ds_read_b128 v[76:79], v51 offset:3600
	s_waitcnt lgkmcnt(4)
	v_pk_fma_f32 v[24:25], v[44:45], v[30:31], v[24:25] op_sel_hi:[0,1,1]
	v_pk_fma_f32 v[24:25], v[0:1], v[54:55], v[24:25] op_sel_hi:[0,1,1]
	s_waitcnt lgkmcnt(3)
	v_pk_fma_f32 v[24:25], v[46:47], v[68:69], v[24:25] op_sel_hi:[0,1,1]
	ds_read_b128 v[80:83], v51 offset:3664
	s_waitcnt lgkmcnt(1)
	v_pk_fma_f32 v[48:49], v[16:17], v[76:77], v[24:25] op_sel_hi:[0,1,1]
	ds_read_b128 v[84:87], v51 offset:3616
	ds_read2_b32 v[34:35], v167 offset1:1
	ds_read_b128 v[24:27], v51 offset:3632
	ds_read_b128 v[88:91], v51 offset:3680
	ds_read_b128 v[28:31], v51 offset:3696
	s_waitcnt lgkmcnt(5)
	v_fma_f32 v50, v48, v81, v49
	s_waitcnt lgkmcnt(3)
	v_pk_fma_f32 v[32:33], v[44:45], v[32:33], v[34:35] op_sel_hi:[0,1,1]
	v_pk_fma_f32 v[32:33], v[0:1], v[56:57], v[32:33] op_sel_hi:[0,1,1]
	v_pk_fma_f32 v[32:33], v[46:47], v[70:71], v[32:33] op_sel_hi:[0,1,1]
	v_pk_fma_f32 v[32:33], v[16:17], v[78:79], v[32:33] op_sel_hi:[0,1,1]
	v_pk_fma_f32 v[32:33], v[48:49], v[82:83], v[32:33] op_sel_hi:[0,1,1]
	ds_read_b128 v[54:57], v51 offset:3792
	s_waitcnt lgkmcnt(0)
	v_pk_fma_f32 v[54:55], v[50:51], v[42:43], v[32:33] op_sel_hi:[0,1,1]
	ds_read_b128 v[68:71], v51 offset:3744
	ds_read_b128 v[32:35], v51 offset:3760
	ds_read2_b32 v[58:59], v169 offset1:1
	ds_read_b128 v[76:79], v51 offset:3808
	ds_read_b128 v[40:43], v51 offset:3824
	ds_read_b128 v[80:83], v51 offset:3872
	ds_read2_b32 v[64:65], v170 offset1:1
	v_fma_f32 v56, v54, v57, v55
	ds_read_b128 v[92:95], v51 offset:3936
	ds_read_b128 v[96:99], v51 offset:3888
	s_waitcnt lgkmcnt(6)
	v_pk_fma_f32 v[36:37], v[44:45], v[36:37], v[58:59] op_sel_hi:[0,1,1]
	v_pk_fma_f32 v[36:37], v[0:1], v[60:61], v[36:37] op_sel_hi:[0,1,1]
	v_pk_fma_f32 v[36:37], v[46:47], v[72:73], v[36:37] op_sel_hi:[0,1,1]
	v_pk_fma_f32 v[36:37], v[16:17], v[84:85], v[36:37] op_sel_hi:[0,1,1]
	v_pk_fma_f32 v[36:37], v[48:49], v[88:89], v[36:37] op_sel_hi:[0,1,1]
	v_pk_fma_f32 v[36:37], v[50:51], v[68:69], v[36:37] op_sel_hi:[0,1,1]
	s_waitcnt lgkmcnt(5)
; #define LAS __attribute__((address_space(3)))
; #define MFMA16(a, b, c) __builtin_amdgcn_mfma_f32_16x16x32_bf16(a, b, c, 0, 0, 0)
; __device__ __forceinline__ unsigned pk2(float lo, float hi) { f32x2_t v = {lo, hi}; bf16x2_t b = __builtin_convertvector(v, bf16x2_t); return __builtin_bit_cast(unsigned, b); }
; #define FENCE() asm volatile("" ::: "memory")
; __device__ __forceinline__ void rwkv_scan(const Args& c, int bx, int l, LAS unsigned char* lds, bool dry) {
;     ...
;             for (int s0 = 0; s0 < 15; ++s0) {
; #pragma unroll
;                 for (int t4 = (s0 + 1) & ~3; t4 < 16; t4 += 4) {
;                     const f32x4 nab = *(const LAS f32x4*)(Nl + s0 * 16 + t4);
; #pragma unroll
;                     for (int e = 0; e < 4; ++e) if (t4 + e > s0) uu[t4 + e] += uu[s0] * nab[e];
;                 }
;             }
;         }
;         FENCE();
; #pragma unroll
;         for (int g = 0; g < 2; ++g) { u32x4v o; o.x = pk2(uu[8 * g], uu[8 * g + 1]); o.y = pk2(uu[8 * g + 2], uu[8 * g + 3]); o.z = pk2(uu[8 * g + 4], uu[8 * g + 5]); o.w = pk2(uu[8 * g + 6], uu[8 * g + 7]); *(LAS u32x4v*)(UVl + row * 40 + 8 * g) = o;
;             *(LAS u32x4v*)(UVl + row * 40 + 16 + 8 * g) = pVB[g]; }
;         Gl[L] = pG;
;         FENCE();
;         {
;             const bf16x8 fu = *(const LAS bf16x8*)(UVl + r * 40 + q4 * 8);
; #pragma unroll
;             for (int jb = 0; jb < 4; ++jb) { const f32x4 cG = *(const LAS f32x4*)(Gl + 16 * jb + 4 * q4); ST[jb] = MFMA16(pB[jb], fu, ST[jb] * cG); }
;             const u32x2v xo = *(const LAS u32x2v*)(XRl + r * 20 + 4 * q4);
;             const f32x4 yv = MFMA16(fu, pNR, ((f32x4){bflo(xo.x), bfhi(xo.x), bflo(xo.y), bfhi(xo.y)}));
;             if (!dry) *(f32x4*)(Yb + ((size_t)n * 16 + r) * (PW / 2) + 4 * q4) = yv;
; __device__ __forceinline__ void m2_phase(const Args& c, int l, LAS unsigned char* lds, int G, int mode, bool dry, int cidx) {
;     ...
;     if (bx < 32) { if (mode & 1) { rwkv_scan(c, bx, l, lds, dry);
;             __threadfence(); __syncthreads(); if (tid_ == 0) __hip_atomic_fetch_add(rdone, 1u, __ATOMIC_RELAXED, __HIP_MEMORY_SCOPE_AGENT); } }
	v_pk_fma_f32 v[36:37], v[54:55], v[76:77], v[36:37] op_sel_hi:[0,1,1]
	s_waitcnt lgkmcnt(3)
	v_pk_fma_f32 v[58:59], v[56:57], v[80:81], v[36:37] op_sel_hi:[0,1,1]
	s_waitcnt lgkmcnt(2)
	v_pk_fma_f32 v[36:37], v[44:45], v[38:39], v[64:65] op_sel_hi:[0,1,1]
	v_pk_fma_f32 v[36:37], v[0:1], v[62:63], v[36:37] op_sel_hi:[0,1,1]
	v_pk_fma_f32 v[36:37], v[46:47], v[74:75], v[36:37] op_sel_hi:[0,1,1]
	v_pk_fma_f32 v[36:37], v[16:17], v[86:87], v[36:37] op_sel_hi:[0,1,1]
	v_pk_fma_f32 v[36:37], v[48:49], v[90:91], v[36:37] op_sel_hi:[0,1,1]
	v_pk_fma_f32 v[62:63], v[50:51], v[70:71], v[36:37] op_sel_hi:[0,1,1]
	v_pk_fma_f32 v[62:63], v[54:55], v[78:79], v[62:63] op_sel_hi:[0,1,1]
	ds_read_b128 v[100:103], v51 offset:3952
	v_add_u32_e32 v17, 0xc00, v51
	v_pk_fma_f32 v[68:69], v[56:57], v[82:83], v[62:63] op_sel_hi:[0,1,1]
	ds_read_b128 v[62:65], v51 offset:4064
	ds_read2_b64 v[36:39], v17 offset0:117 offset1:151
	s_waitcnt lgkmcnt(1)
	v_pk_fma_f32 v[62:63], v[58:59], v[94:95], v[68:69] op_sel_hi:[0,1,1]
	ds_read2_b32 v[76:77], v171 offset1:1
	ds_read_b128 v[68:71], v51 offset:4016
	v_fma_f32 v60, v58, v93, v59
	s_waitcnt lgkmcnt(2)
	v_pk_fma_f32 v[36:37], v[60:61], v[36:37], v[62:63] op_sel_hi:[0,1,1]
	s_waitcnt lgkmcnt(1)
	v_pk_fma_f32 v[14:15], v[44:45], v[14:15], v[76:77] op_sel_hi:[0,1,1]
	v_pk_fma_f32 v[14:15], v[0:1], v[18:19], v[14:15] op_sel_hi:[0,1,1]
	v_pk_fma_f32 v[14:15], v[46:47], v[20:21], v[14:15] op_sel_hi:[0,1,1]
	v_pk_fma_f32 v[14:15], v[16:17], v[24:25], v[14:15] op_sel_hi:[0,1,1]
	v_pk_fma_f32 v[14:15], v[48:49], v[28:29], v[14:15] op_sel_hi:[0,1,1]
	v_pk_fma_f32 v[14:15], v[50:51], v[32:33], v[14:15] op_sel_hi:[0,1,1]
	v_fma_f32 v78, v36, v65, v37
	ds_read_b128 v[62:65], v51 offset:4080
	ds_read_b128 v[72:75], v51 offset:4144
	v_pk_fma_f32 v[14:15], v[54:55], v[40:41], v[14:15] op_sel_hi:[0,1,1]
	v_pk_fma_f32 v[14:15], v[56:57], v[96:97], v[14:15] op_sel_hi:[0,1,1]
	v_pk_fma_f32 v[14:15], v[58:59], v[100:101], v[14:15] op_sel_hi:[0,1,1]
	s_waitcnt lgkmcnt(2)
	v_pk_fma_f32 v[14:15], v[60:61], v[68:69], v[14:15] op_sel_hi:[0,1,1]
	s_waitcnt lgkmcnt(1)
	v_pk_fma_f32 v[14:15], v[36:37], v[62:63], v[14:15] op_sel_hi:[0,1,1]
	s_waitcnt lgkmcnt(0)
	v_pk_fma_f32 v[28:29], v[78:79], v[72:73], v[14:15] op_sel_hi:[0,1,1]
	v_pk_fma_f32 v[14:15], v[46:47], v[22:23], v[52:53] op_sel_hi:[0,1,1]
	v_pk_fma_f32 v[14:15], v[16:17], v[26:27], v[14:15] op_sel_hi:[0,1,1]
	v_pk_fma_f32 v[14:15], v[48:49], v[30:31], v[14:15] op_sel_hi:[0,1,1]
	v_pk_fma_f32 v[14:15], v[50:51], v[34:35], v[14:15] op_sel_hi:[0,1,1]
	v_pk_fma_f32 v[14:15], v[54:55], v[42:43], v[14:15] op_sel_hi:[0,1,1]
	ds_read_b128 v[18:21], v51 offset:4208
	ds_read_b128 v[22:25], v51 offset:4336
	v_pk_fma_f32 v[14:15], v[56:57], v[98:99], v[14:15] op_sel_hi:[0,1,1]
	v_pk_fma_f32 v[14:15], v[58:59], v[102:103], v[14:15] op_sel_hi:[0,1,1]
	v_pk_fma_f32 v[14:15], v[60:61], v[70:71], v[14:15] op_sel_hi:[0,1,1]
	v_pk_fma_f32 v[14:15], v[36:37], v[64:65], v[14:15] op_sel_hi:[0,1,1]
	v_pk_fma_f32 v[14:15], v[78:79], v[74:75], v[14:15] op_sel_hi:[0,1,1]
	s_waitcnt lgkmcnt(1)
	v_fma_f32 v18, v19, v28, v29
	v_pk_fma_f32 v[14:15], v[20:21], v[28:29], v[14:15] op_sel_hi:[1,0,1]
	v_cvt_pk_bf16_f32 v17, v54, v56
	v_pk_fma_f32 v[20:21], v[38:39], v[18:19], v[14:15] op_sel_hi:[1,0,1]
	v_cvt_pk_bf16_f32 v14, v44, v0
	s_waitcnt lgkmcnt(0)
	v_fma_f32 v19, v25, v20, v21
	v_cvt_pk_bf16_f32 v15, v46, v16
	v_cvt_pk_bf16_f32 v16, v48, v50
	ds_write_b128 v66, v[14:17]
	ds_write_b128 v66, v[10:13] offset:32
	v_cvt_pk_bf16_f32 v10, v58, v60
	v_cvt_pk_bf16_f32 v11, v36, v78
	v_cvt_pk_bf16_f32 v12, v28, v18
	v_cvt_pk_bf16_f32 v13, v20, v19
	ds_write_b128 v66, v[10:13] offset:16
	ds_write_b128 v66, v[6:9] offset:48
	ds_write_b32 v151, v153 offset:4416
	ds_read_b128 v[6:9], v67
	ds_read_b64 v[12:13], v147 offset:4672
	v_lshlrev_b32_e32 v0, 2, v141
	v_lshl_add_u64 v[14:15], s[0:1], 0, v[0:1]
	v_mul_u32_u24_e32 v0, 0xe00, v137
	v_lshlrev_b32_e32 v0, 2, v0
	s_waitcnt lgkmcnt(0)
	v_lshlrev_b32_e32 v10, 16, v12
	v_and_b32_e32 v11, 0xffff0000, v12
	v_lshlrev_b32_e32 v12, 16, v13
	v_and_b32_e32 v13, 0xffff0000, v13
	s_nop 1
	v_mfma_f32_16x16x32_bf16 v[2:5], v[6:9], v[2:5], v[10:13]
	v_lshl_add_u64 v[6:7], v[14:15], 0, v[0:1]
	v_add_co_u32_e32 v6, vcc, 0xc3c8000, v6
	s_nop 1
	v_addc_co_u32_e32 v7, vcc, 0, v7, vcc
	s_nop 2
	flat_store_dwordx4 v[6:7], v[2:5]
	v_cmp_eq_u32_e32 vcc, 0, v202
	buffer_wbl2 sc1
	s_waitcnt vmcnt(0) lgkmcnt(0)
	buffer_inv sc1
	s_barrier
	s_and_saveexec_b64 s[2:3], vcc
	s_cbranch_execz .LBB0_235
	v_mov_b64_e32 v[2:3], s[28:29]
	flat_atomic_add v[2:3], v191 offset:2048

; #define LAS __attribute__((address_space(3)))
; __device__ __forceinline__ void attn_unit(const Args& c, int l, int b, int h, int qb, float lam, float lam_init, LAS unsigned char* lds) {
;     int tid_ = threadIdx.x; asm volatile("" : "+v"(tid_)); unsigned char* wsl = c.ws; asm volatile("" : "+s"(wsl)); int z_ = 0; asm volatile("" : "+s"(z_));
;     const int tid = tid_, lane = tid & 63, w = __builtin_amdgcn_readfirstlane(tid >> 6), r = lane & 15, q4 = lane >> 4;
;     LAS bf16* Kt = (LAS bf16*)lds;
;     LAS bf16* Vs = Kt + 128 * 136;
;     const bf16* P = ((bf16*)(wsl + WS_P));
;     const size_t seq0 = (size_t)b * T;
;     const int QC = DIFF_BASE + h * 128, KC = DIFF_BASE + 1024 + h * 128, VC = DIFF_BASE + 2048 + h * 128;
;     const float* qnw = c.in[22 + z_] + l * 64; const float* knw = c.in[23 + z_] + l * 64;
;     bf16x8 qf[2][2];
;     {
;         const bf16* qrow = P + (seq0 + 128 * qb + 16 * w + r) * PW + QC;
; #pragma unroll
;         for (int m = 0; m < 2; ++m) {
;             float f[16];
;             unpack8(*(const u32x4v*)(qrow + m * 64 + q4 * 8), f); unpack8(*(const u32x4v*)(qrow + m * 64 + 32 + q4 * 8), f + 8);
;             float ss = 0.f;
; #pragma unroll
;             for (int e = 0; e < 16; ++e) ss += f[e] * f[e];
;             ss += __shfl_xor(ss, 16); ss += __shfl_xor(ss, 32);
;             const float sc = rsqrtf(ss * (1.f / 64.f) + 1e-6f) * (0.125f * 1.4426950408889634f);
; #pragma unroll
;             for (int ks = 0; ks < 2; ++ks) { u32x4v o; const float* g = f + 8 * ks; const float* wn = qnw + ks * 32 + q4 * 8;
;                 o.x = pk2(g[0] * sc * wn[0], g[1] * sc * wn[1]); o.y = pk2(g[2] * sc * wn[2], g[3] * sc * wn[3]); o.z = pk2(g[4] * sc * wn[4], g[5] * sc * wn[5]); o.w = pk2(g[6] * sc * wn[6], g[7] * sc * wn[7]);
;                 qf[m][ks] = __builtin_bit_cast(bf16x8, o); }
;         }
;     }
;     f32x4 O[2][8];
; #pragma unroll
;     for (int m = 0; m < 2; ++m)
; #pragma unroll
;         for (int vb = 0; vb < 8; ++vb) O[m][vb] = (f32x4){0.f, 0.f, 0.f, 0.f};
;     float mrow[2] = {-INFINITY, -INFINITY}, lrow[2] = {0.f, 0.f};
;     const int NT = qb + 1;
;     const int skey = tid >> 3, part = tid & 7;
;     const float* kwp = knw + (part & 3) * 16;
;     u32x4v gk0[2], gk1[2], gv0[2], gv1[2];
;     ...
;     ATT_FETCH(0);
.Lattn_prio_skip:
	s_add_u32 s12, s8, s30
	s_addc_u32 s13, s9, s31
	s_ashr_i32 s4, s4, 2
	s_lshl_b32 s7, s22, 7
	s_and_b32 s8, s4, -16
	s_add_i32 s5, s7, s18
	s_ashr_i32 s4, s8, 31
	s_add_u32 s5, s8, s5
	v_or_b32_e32 v184, s5, v107
	s_addc_u32 s9, s4, 0
	v_mad_u64_u32 v[2:3], s[4:5], v184, s27, v[18:19]
	v_mad_i32_i24 v3, s9, v196, v3
	s_lshl_b32 s4, s19, 1
	s_mov_b32 s5, s15
	v_lshl_add_u64 v[2:3], v[2:3], 0, s[4:5]
	v_lshlrev_b32_e32 v0, 4, v108
	v_lshl_add_u64 v[2:3], v[2:3], 0, v[0:1]
	s_movk_i32 s5, 0x1000
	v_add_co_u32_e32 v2, vcc, s5, v2
	v_lshlrev_b32_e32 v14, 5, v108
	s_nop 0
	v_addc_co_u32_e32 v3, vcc, 0, v3, vcc
	flat_load_dwordx4 v[26:29], v[2:3] offset:3904
	flat_load_dwordx4 v[30:33], v[2:3] offset:4032
	flat_load_dwordx4 v[34:37], v[2:3] offset:3840
	flat_load_dwordx4 v[38:41], v[2:3] offset:3968
	global_load_dwordx4 v[2:5], v14, s[12:13] offset:144
	global_load_dwordx4 v[6:9], v14, s[12:13] offset:128
	global_load_dwordx4 v[10:13], v14, s[12:13] offset:16
	global_load_dwordx4 v[14:17], v14, s[12:13]
	v_ashrrev_i32_e32 v186, 3, v106
	s_lshl_b32 s20, s0, 1
	s_mov_b32 s21, s15
	s_lshl_b32 s28, s1, 1
	s_mov_b32 s29, s15
	v_lshlrev_b32_e32 v126, 4, v106
	v_add_u32_e32 v127, s18, v186
	v_and_b32_e32 v126, 0x70, v126
	v_mad_i64_i32 v[128:129], s[12:13], v127, s27, v[18:19]
	v_lshlrev_b32_e32 v130, 1, v126
	v_mov_b32_e32 v131, 0
	v_lshl_add_u64 v[132:133], v[128:129], 0, s[20:21]
	v_lshl_add_u64 v[128:129], v[128:129], 0, s[28:29]
	v_lshl_add_u64 v[132:133], v[132:133], 0, v[130:131]
	v_lshl_add_u64 v[128:129], v[128:129], 0, v[130:131]
	global_load_dwordx4 v[110:113], v[132:133], off
	global_load_dwordx4 v[114:117], v[132:133], off offset:16
	global_load_dwordx4 v[118:121], v[128:129], off
	global_load_dwordx4 v[122:125], v[128:129], off offset:16
	v_add_u32_e32 v127, 64, v127
	v_mad_i64_i32 v[128:129], s[12:13], v127, s27, v[18:19]
	v_lshl_add_u64 v[132:133], v[128:129], 0, s[20:21]
	v_lshl_add_u64 v[128:129], v[128:129], 0, s[28:29]
	v_lshl_add_u64 v[132:133], v[132:133], 0, v[130:131]
	v_lshl_add_u64 v[128:129], v[128:129], 0, v[130:131]
	global_load_dwordx4 v[90:93], v[132:133], off
	global_load_dwordx4 v[94:97], v[132:133], off offset:16
	global_load_dwordx4 v[98:101], v[128:129], off
	global_load_dwordx4 v[102:105], v[128:129], off offset:16
	s_add_u32 s10, s10, s30
	s_addc_u32 s11, s11, s31
	v_lshlrev_b32_e32 v208, 2, v108
	s_add_i32 s8, s8, s7
	s_movk_i32 s7, 0x110
	v_or_b32_e32 v209, s8, v107
	v_mov_b32_e32 v108, v1
	v_mov_b32_e32 v109, v1
	s_mov_b32 s5, 0
	v_mov_b32_e32 v185, s9
	v_ashrrev_i32_e32 v187, 31, v186
	s_sub_i32 s34, 16, s6
	v_mov_b32_e32 v216, 0
	v_mov_b32_e32 v192, 0xff800000
	v_mov_b32_e32 v148, 0xff800000
	v_mov_b32_e32 v215, 0
	s_mov_b32 s35, 0
	s_waitcnt vmcnt(0) lgkmcnt(0)
	v_lshlrev_b32_e32 v42, 16, v29
	v_and_b32_e32 v43, 0xffff0000, v29
	v_lshlrev_b32_e32 v20, 16, v33
	v_and_b32_e32 v21, 0xffff0000, v33
	v_lshlrev_b32_e32 v44, 16, v28
	v_and_b32_e32 v45, 0xffff0000, v28
	v_lshlrev_b32_e32 v22, 16, v32
	v_and_b32_e32 v23, 0xffff0000, v32
	v_lshlrev_b32_e32 v28, 16, v27
	v_and_b32_e32 v29, 0xffff0000, v27
	v_lshlrev_b32_e32 v24, 16, v31
	v_and_b32_e32 v25, 0xffff0000, v31
	v_lshlrev_b32_e32 v32, 16, v26
	v_and_b32_e32 v33, 0xffff0000, v26
	v_lshlrev_b32_e32 v26, 16, v30
	v_and_b32_e32 v27, 0xffff0000, v30
	v_lshlrev_b32_e32 v30, 16, v37
	v_and_b32_e32 v31, 0xffff0000, v37
	v_lshlrev_b32_e32 v46, 16, v41
	v_and_b32_e32 v47, 0xffff0000, v41
	v_lshlrev_b32_e32 v48, 16, v36
	v_and_b32_e32 v49, 0xffff0000, v36
	v_lshlrev_b32_e32 v36, 16, v40
	v_and_b32_e32 v37, 0xffff0000, v40
	v_lshlrev_b32_e32 v40, 16, v35
	v_and_b32_e32 v41, 0xffff0000, v35
	v_and_b32_e32 v51, 0xffff0000, v34
	v_and_b32_e32 v35, 0xffff0000, v38
	v_lshlrev_b32_e32 v50, 16, v34
	v_lshlrev_b32_e32 v34, 16, v38
	v_mov_b32_e32 v82, v35
	v_mov_b32_e32 v83, v51
	v_lshlrev_b32_e32 v58, 16, v39
	v_mov_b32_e32 v80, v34
	v_mov_b32_e32 v81, v50
	v_pk_mul_f32 v[82:83], v[82:83], v[82:83]
	v_and_b32_e32 v59, 0xffff0000, v39
	v_mov_b32_e32 v76, v58
	v_mov_b32_e32 v77, v40
	v_pk_fma_f32 v[80:81], v[80:81], v[80:81], v[82:83]
	v_mov_b32_e32 v78, v59
	v_mov_b32_e32 v79, v41
	v_pk_fma_f32 v[76:77], v[76:77], v[76:77], v[80:81]
	v_mov_b32_e32 v72, v36
	v_mov_b32_e32 v73, v48
	v_pk_fma_f32 v[76:77], v[78:79], v[78:79], v[76:77]
	v_mov_b32_e32 v74, v37
	v_mov_b32_e32 v75, v49
	v_pk_fma_f32 v[72:73], v[72:73], v[72:73], v[76:77]
	v_mov_b32_e32 v68, v46
	v_mov_b32_e32 v69, v30
	v_pk_fma_f32 v[72:73], v[74:75], v[74:75], v[72:73]
	v_pk_mul_f32 v[64:65], v[32:33], v[32:33]
	v_pk_mul_f32 v[66:67], v[26:27], v[26:27]
	v_mov_b32_e32 v70, v47
	v_mov_b32_e32 v71, v31
	v_pk_fma_f32 v[68:69], v[68:69], v[68:69], v[72:73]
	v_pk_mul_f32 v[60:61], v[28:29], v[28:29]
	v_pk_fma_f32 v[68:69], v[70:71], v[70:71], v[68:69]
	v_mov_b32_e32 v70, v66
	v_mov_b32_e32 v71, v64
	v_pk_mul_f32 v[62:63], v[24:25], v[24:25]
	v_pk_add_f32 v[68:69], v[70:71], v[68:69]
	v_mov_b32_e32 v64, v67
	v_pk_add_f32 v[64:65], v[64:65], v[68:69]
	v_mov_b32_e32 v66, v62
	v_mov_b32_e32 v67, v60
	v_pk_mul_f32 v[54:55], v[44:45], v[44:45]
	v_pk_mul_f32 v[56:57], v[22:23], v[22:23]
	v_pk_add_f32 v[64:65], v[66:67], v[64:65]
	v_mov_b32_e32 v60, v63
	v_pk_add_f32 v[60:61], v[60:61], v[64:65]
	v_mov_b32_e32 v62, v56
	v_mov_b32_e32 v63, v54
	v_pk_mul_f32 v[38:39], v[42:43], v[42:43]
	v_pk_mul_f32 v[52:53], v[20:21], v[20:21]
	v_pk_add_f32 v[60:61], v[62:63], v[60:61]
	v_mov_b32_e32 v54, v57
	v_pk_add_f32 v[54:55], v[54:55], v[60:61]
	v_mov_b32_e32 v56, v52
	v_mov_b32_e32 v57, v38
	v_pk_add_f32 v[54:55], v[56:57], v[54:55]
	v_mov_b32_e32 v38, v53
	v_pk_add_f32 v[38:39], v[38:39], v[54:55]
	ds_bpermute_b32 v53, v205, v39
	ds_bpermute_b32 v52, v205, v38
	s_waitcnt lgkmcnt(0)
; __device__ __forceinline__ unsigned pk2(float lo, float hi) { f32x2_t v = {lo, hi}; bf16x2_t b = __builtin_convertvector(v, bf16x2_t); return __builtin_bit_cast(unsigned, b); }
; __device__ __forceinline__ void unpack8(u32x4v w, float* f) { f[0] = bflo(w.x); f[1] = bfhi(w.x); f[2] = bflo(w.y); f[3] = bfhi(w.y); f[4] = bflo(w.z); f[5] = bfhi(w.z); f[6] = bflo(w.w); f[7] = bfhi(w.w); }
; __device__ __forceinline__ void attn_unit(const Args& c, int l, int b, int h, int qb, float lam, float lam_init, LAS unsigned char* lds) {
;     ...
;     bf16x8 qf[2][2];
;     {
;         const bf16* qrow = P + (seq0 + 128 * qb + 16 * w + r) * PW + QC;
; #pragma unroll
;         for (int m = 0; m < 2; ++m) {
;             float f[16];
;             unpack8(*(const u32x4v*)(qrow + m * 64 + q4 * 8), f); unpack8(*(const u32x4v*)(qrow + m * 64 + 32 + q4 * 8), f + 8);
;             float ss = 0.f;
; #pragma unroll
;             for (int e = 0; e < 16; ++e) ss += f[e] * f[e];
;             ss += __shfl_xor(ss, 16); ss += __shfl_xor(ss, 32);
;             const float sc = rsqrtf(ss * (1.f / 64.f) + 1e-6f) * (0.125f * 1.4426950408889634f);
; #pragma unroll
;             for (int ks = 0; ks < 2; ++ks) { u32x4v o; const float* g = f + 8 * ks; const float* wn = qnw + ks * 32 + q4 * 8;
;                 o.x = pk2(g[0] * sc * wn[0], g[1] * sc * wn[1]); o.y = pk2(g[2] * sc * wn[2], g[3] * sc * wn[3]); o.z = pk2(g[4] * sc * wn[4], g[5] * sc * wn[5]); o.w = pk2(g[6] * sc * wn[6], g[7] * sc * wn[7]);
;                 qf[m][ks] = __builtin_bit_cast(bf16x8, o); }
;         }
;     }
;     f32x4 O[2][8];
; #pragma unroll
;     for (int m = 0; m < 2; ++m)
; #pragma unroll
;         for (int vb = 0; vb < 8; ++vb) O[m][vb] = (f32x4){0.f, 0.f, 0.f, 0.f};
;     float mrow[2] = {-INFINITY, -INFINITY}, lrow[2] = {0.f, 0.f};
;     const int NT = qb + 1;
;     const int skey = tid >> 3, part = tid & 7;
;     const float* kwp = knw + (part & 3) * 16;
;     u32x4v gk0[2], gk1[2], gv0[2], gv1[2];
;     ...
;     ATT_FETCH(0);
;     typedef short v4i16_t __attribute__((ext_vector_type(4)));
;     const int r4 = (lane & 15) >> 2, c4 = lane & 3;
	v_pk_add_f32 v[38:39], v[38:39], v[52:53]
	ds_bpermute_b32 v53, v206, v39
	ds_bpermute_b32 v52, v206, v38
	s_waitcnt lgkmcnt(0)
	v_pk_add_f32 v[38:39], v[38:39], v[52:53]
	s_nop 0
	v_pk_fma_f32 v[38:39], v[38:39], s[26:27], v[178:179] op_sel_hi:[1,0,0]
	s_nop 0
	v_mul_f32_e32 v52, 0x4b800000, v39
	v_cmp_gt_f32_e32 vcc, s33, v39
	s_nop 1
	v_cndmask_b32_e32 v39, v39, v52, vcc
	v_rsq_f32_e32 v39, v39
	s_nop 0
	v_mul_f32_e32 v52, 0x45800000, v39
	v_cndmask_b32_e32 v39, v39, v52, vcc
	v_mul_f32_e32 v52, 0x3e38aa3b, v39
	v_pk_mul_f32 v[28:29], v[52:53], v[28:29] op_sel_hi:[0,1]
	v_pk_mul_f32 v[32:33], v[52:53], v[32:33] op_sel_hi:[0,1]
	v_pk_mul_f32 v[28:29], v[8:9], v[28:29]
	v_pk_mul_f32 v[60:61], v[52:53], v[50:51] op_sel_hi:[0,1]
	v_pk_mul_f32 v[30:31], v[52:53], v[30:31] op_sel_hi:[0,1]
	v_pk_mul_f32 v[42:43], v[52:53], v[42:43] op_sel_hi:[0,1]
	v_cvt_pk_bf16_f32 v51, v28, v29
	v_pk_mul_f32 v[28:29], v[6:7], v[32:33]
	v_pk_mul_f32 v[48:49], v[52:53], v[48:49] op_sel_hi:[0,1]
	v_pk_mul_f32 v[44:45], v[52:53], v[44:45] op_sel_hi:[0,1]
	v_pk_mul_f32 v[42:43], v[4:5], v[42:43]
	v_cvt_pk_bf16_f32 v50, v28, v29
	v_pk_mul_f32 v[28:29], v[12:13], v[30:31]
	v_lshlrev_b32_e32 v30, 4, v106
	v_add_u32_e32 v39, s18, v186
	v_pk_mul_f32 v[40:41], v[52:53], v[40:41] op_sel_hi:[0,1]
	v_cvt_pk_bf16_f32 v53, v42, v43
	v_pk_mul_f32 v[42:43], v[2:3], v[44:45]
	v_cvt_pk_bf16_f32 v57, v28, v29
	v_pk_mul_f32 v[28:29], v[10:11], v[48:49]
	v_and_b32_e32 v30, 0x70, v30
	v_mad_i64_i32 v[32:33], s[12:13], v39, s27, v[18:19]
	v_cvt_pk_bf16_f32 v52, v42, v43
	v_cvt_pk_bf16_f32 v56, v28, v29
	v_pk_mul_f32 v[28:29], v[16:17], v[40:41]
	v_lshl_add_u64 v[40:41], v[32:33], 0, s[20:21]
	v_lshlrev_b32_e32 v42, 1, v30
	v_mov_b32_e32 v43, v1
	v_lshl_add_u64 v[32:33], v[32:33], 0, s[28:29]
	v_lshl_add_u64 v[40:41], v[40:41], 0, v[42:43]
	v_lshl_add_u64 v[32:33], v[32:33], 0, v[42:43]
	v_mov_b64_e32 v[66:67], v[110:111]
	v_mov_b64_e32 v[68:69], v[112:113]
	v_mov_b64_e32 v[70:71], v[114:115]
	v_mov_b64_e32 v[72:73], v[116:117]
	v_mov_b64_e32 v[78:79], v[118:119]
	v_mov_b64_e32 v[80:81], v[120:121]
	v_mov_b64_e32 v[82:83], v[122:123]
	v_mov_b64_e32 v[84:85], v[124:125]
	v_add_u32_e32 v32, 64, v39
	v_mad_i64_i32 v[18:19], s[12:13], v32, s27, v[18:19]
	v_lshl_add_u64 v[32:33], v[18:19], 0, s[20:21]
	v_lshl_add_u64 v[18:19], v[18:19], 0, s[28:29]
	v_lshl_add_u64 v[32:33], v[32:33], 0, v[42:43]
	v_lshl_add_u64 v[18:19], v[18:19], 0, v[42:43]
	v_mul_f32_e32 v31, 0x4b800000, v38
	v_cmp_gt_f32_e32 vcc, s33, v38
	v_cvt_pk_bf16_f32 v55, v28, v29
	s_nop 0
	v_cndmask_b32_e32 v18, v38, v31, vcc
	v_rsq_f32_e32 v31, v18
	v_pk_mul_f32 v[18:19], v[14:15], v[60:61]
	s_nop 0
	v_cvt_pk_bf16_f32 v54, v18, v19
	v_mul_f32_e32 v18, 0x45800000, v31
	v_cndmask_b32_e32 v18, v31, v18, vcc
	v_mul_f32_e32 v18, 0x3e38aa3b, v18
	v_pk_mul_f32 v[28:29], v[18:19], v[34:35] op_sel_hi:[0,1]
	v_pk_mul_f32 v[14:15], v[14:15], v[28:29]
	s_nop 0
	v_cvt_pk_bf16_f32 v74, v14, v15
	v_pk_mul_f32 v[14:15], v[18:19], v[58:59] op_sel_hi:[0,1]
	v_pk_mul_f32 v[14:15], v[16:17], v[14:15]
	s_nop 0
	v_cvt_pk_bf16_f32 v75, v14, v15
	v_pk_mul_f32 v[14:15], v[18:19], v[36:37] op_sel_hi:[0,1]
	v_pk_mul_f32 v[10:11], v[10:11], v[14:15]
	s_nop 0
	v_cvt_pk_bf16_f32 v76, v10, v11
	v_pk_mul_f32 v[10:11], v[18:19], v[46:47] op_sel_hi:[0,1]
	v_pk_mul_f32 v[10:11], v[12:13], v[10:11]
	s_nop 0
	v_cvt_pk_bf16_f32 v77, v10, v11
	v_pk_mul_f32 v[10:11], v[18:19], v[26:27] op_sel_hi:[0,1]
	v_pk_mul_f32 v[6:7], v[6:7], v[10:11]
	s_nop 0
	v_cvt_pk_bf16_f32 v86, v6, v7
	v_pk_mul_f32 v[6:7], v[18:19], v[24:25] op_sel_hi:[0,1]
	v_pk_mul_f32 v[6:7], v[8:9], v[6:7]
	s_nop 0
	v_cvt_pk_bf16_f32 v87, v6, v7
	v_pk_mul_f32 v[6:7], v[18:19], v[22:23] op_sel_hi:[0,1]
	v_pk_mul_f32 v[2:3], v[2:3], v[6:7]
	s_nop 0
	v_cvt_pk_bf16_f32 v88, v2, v3
	v_pk_mul_f32 v[2:3], v[18:19], v[20:21] op_sel_hi:[0,1]
	v_pk_mul_f32 v[2:3], v[4:5], v[2:3]
	s_nop 0
	v_cvt_pk_bf16_f32 v89, v2, v3
	v_lshlrev_b32_e32 v2, 6, v106
	v_and_b32_e32 v2, 0xc0, v2
	v_mov_b32_e32 v3, v1
	v_lshl_add_u64 v[188:189], s[10:11], 0, v[2:3]
	v_bfe_u32 v2, v106, 2, 2
	v_add_u32_e32 v3, 0, v0
	v_or_b32_e32 v0, v208, v2
	v_lshlrev_b32_e32 v2, 3, v106
	v_mul_u32_u24_e32 v0, 0x110, v0
	v_and_b32_e32 v2, 24, v2
	v_add3_u32 v210, 0, v0, v2
	v_mul_lo_u32 v0, v186, s7
	v_mul_u32_u24_e32 v2, 0x110, v107
	v_mov_b32_e32 v106, v1
	v_mov_b32_e32 v107, v1
	v_add3_u32 v211, 0, v42, v0
	v_lshlrev_b32_e32 v0, 1, v30
	v_add_u32_e32 v212, v3, v2
	v_mov_b64_e32 v[2:3], v[106:107]
	v_mov_b64_e32 v[10:11], v[106:107]
	v_mov_b64_e32 v[18:19], v[106:107]
	v_mov_b64_e32 v[58:59], v[106:107]
	v_mov_b64_e32 v[26:27], v[106:107]
	v_mov_b64_e32 v[34:35], v[106:107]
	v_mov_b64_e32 v[42:43], v[106:107]
	v_mov_b64_e32 v[112:113], v[108:109]
	v_mov_b64_e32 v[6:7], v[106:107]
	v_mov_b64_e32 v[14:15], v[106:107]
	v_mov_b64_e32 v[22:23], v[106:107]
	v_mov_b64_e32 v[62:63], v[106:107]
	v_mov_b64_e32 v[30:31], v[106:107]
	v_mov_b64_e32 v[38:39], v[106:107]
	v_mov_b64_e32 v[46:47], v[106:107]
	v_mov_b64_e32 v[4:5], v[108:109]
	v_mov_b64_e32 v[12:13], v[108:109]
	v_mov_b64_e32 v[20:21], v[108:109]
	v_mov_b64_e32 v[60:61], v[108:109]
	v_mov_b64_e32 v[28:29], v[108:109]
	v_mov_b64_e32 v[36:37], v[108:109]
	v_mov_b64_e32 v[44:45], v[108:109]
	v_mov_b64_e32 v[110:111], v[106:107]
	v_mov_b64_e32 v[8:9], v[108:109]
	v_mov_b64_e32 v[16:17], v[108:109]
	v_mov_b64_e32 v[24:25], v[108:109]
	v_mov_b64_e32 v[64:65], v[108:109]
	v_mov_b64_e32 v[32:33], v[108:109]
	v_mov_b64_e32 v[40:41], v[108:109]
	v_mov_b64_e32 v[48:49], v[108:109]
; #define LAS __attribute__((address_space(3)))
; __device__ __forceinline__ unsigned pk2(float lo, float hi) { f32x2_t v = {lo, hi}; bf16x2_t b = __builtin_convertvector(v, bf16x2_t); return __builtin_bit_cast(unsigned, b); }
; __device__ __forceinline__ void unpack8(u32x4v w, float* f) { f[0] = bflo(w.x); f[1] = bfhi(w.x); f[2] = bflo(w.y); f[3] = bfhi(w.y); f[4] = bflo(w.z); f[5] = bfhi(w.z); f[6] = bflo(w.w); f[7] = bfhi(w.w); }
; __device__ __forceinline__ void attn_unit(const Args& c, int l, int b, int h, int qb, float lam, float lam_init, LAS unsigned char* lds) {
;     ...
;     ATT_FETCH(0);
;     typedef short v4i16_t __attribute__((ext_vector_type(4)));
;     const int r4 = (lane & 15) >> 2, c4 = lane & 3;
;     for (int kt = 0; kt < NT; ++kt) {
;         __syncthreads();
; #pragma unroll
;         for (int hh = 0; hh < 2; ++hh) {
;             const int kr = skey + 64 * hh;
;             float f[16]; unpack8(gk0[hh], f); unpack8(gk1[hh], f + 8);
;             float kw[16];
; #pragma unroll
;             for (int e4 = 0; e4 < 4; ++e4) { const f32x4 t4 = ((const f32x4*)kwp)[e4]; kw[4 * e4] = t4.x; kw[4 * e4 + 1] = t4.y; kw[4 * e4 + 2] = t4.z; kw[4 * e4 + 3] = t4.w; }
;             float ss = 0.f;
; #pragma unroll
;             for (int e = 0; e < 16; ++e) ss += f[e] * f[e];
;             ss += __shfl_xor(ss, 1); ss += __shfl_xor(ss, 2);
;             const float sc = rsqrtf(ss * (1.f / 64.f) + 1e-6f);
;             u32x4v o;
;             o.x = pk2(f[0] * sc * kw[0], f[1] * sc * kw[1]); o.y = pk2(f[2] * sc * kw[2], f[3] * sc * kw[3]); o.z = pk2(f[4] * sc * kw[4], f[5] * sc * kw[5]); o.w = pk2(f[6] * sc * kw[6], f[7] * sc * kw[7]);
;             *(LAS u32x4v*)(Kt + kr * 136 + part * 16) = o;
;             o.x = pk2(f[8] * sc * kw[8], f[9] * sc * kw[9]); o.y = pk2(f[10] * sc * kw[10], f[11] * sc * kw[11]); o.z = pk2(f[12] * sc * kw[12], f[13] * sc * kw[13]); o.w = pk2(f[14] * sc * kw[14], f[15] * sc * kw[15]);
;             *(LAS u32x4v*)(Kt + kr * 136 + part * 16 + 8) = o;
;             *(LAS u32x4v*)(Vs + kr * 136 + part * 16) = gv0[hh]; *(LAS u32x4v*)(Vs + kr * 136 + part * 16 + 8) = gv1[hh];
;         }
;         if (kt + 1 < NT) ATT_FETCH(kt + 1);
.LBB0_245:
	s_waitcnt lgkmcnt(0)
	s_barrier
	s_waitcnt vmcnt(0)
	ds_write_b128 v211, v[66:69]
	ds_write_b128 v211, v[70:73] offset:16
	ds_write_b128 v211, v[90:93] offset:17408
	ds_write_b128 v211, v[94:97] offset:17424
	ds_write_b128 v211, v[78:81] offset:34816
	ds_write_b128 v211, v[82:85] offset:34832
	ds_write_b128 v211, v[98:101] offset:52224
	ds_write_b128 v211, v[102:105] offset:52240
	s_cmp_ge_u32 s35, s22
	s_cbranch_scc1 .LBB0_247
	s_add_i32 s8, s18, s5
	s_add_i32 s14, s8, 0x80
	v_lshl_add_u64 v[66:67], s[14:15], 0, v[186:187]
	s_add_i32 s14, s8, 0xc0
	v_mov_b64_e32 v[90:91], s[2:3]
	v_lshl_add_u64 v[92:93], s[14:15], 0, v[186:187]
	v_mad_u64_u32 v[78:79], s[6:7], v66, s27, v[90:91]
	v_mad_u64_u32 v[98:99], s[6:7], v92, s27, v[90:91]
	v_mad_i32_i24 v79, v67, s27, v79
	s_mov_b32 s21, s15
	s_mov_b32 s29, s15
	v_mad_i32_i24 v99, v93, s27, v99
	v_lshl_add_u64 v[66:67], v[78:79], 0, s[20:21]
	v_lshl_add_u64 v[78:79], v[78:79], 0, s[28:29]
	v_lshl_add_u64 v[90:91], v[98:99], 0, s[20:21]
	v_lshl_add_u64 v[98:99], v[98:99], 0, s[28:29]
	v_lshl_add_u64 v[70:71], v[66:67], 0, v[0:1]
	v_lshl_add_u64 v[82:83], v[78:79], 0, v[0:1]
	v_lshl_add_u64 v[94:95], v[90:91], 0, v[0:1]
	v_lshl_add_u64 v[102:103], v[98:99], 0, v[0:1]
	global_load_dwordx4 v[66:69], v[70:71], off
	global_load_dwordx4 v[70:73], v[70:71], off offset:16
	global_load_dwordx4 v[78:81], v[82:83], off
	global_load_dwordx4 v[82:85], v[82:83], off offset:16
	global_load_dwordx4 v[90:93], v[94:95], off
	global_load_dwordx4 v[94:97], v[94:95], off offset:16
	global_load_dwordx4 v[98:101], v[102:103], off
	global_load_dwordx4 v[102:105], v[102:103], off offset:16

; __device__ __forceinline__ unsigned f2bf(float f) { return pk2(f, f) & 0xffffu; }
; __device__ __forceinline__ float sigmoidf_(float x) { return __builtin_amdgcn_rcpf(1.0f + __expf(-x)); }
; __device__ __forceinline__ float softplusf_(float x) { return fmaxf(x, 0.f) + __logf(1.0f + __expf(-fabsf(x))); }
; __device__ __forceinline__ void rwkv_prep_unit(const Args& c, int u, int l, LAS unsigned char* lds) {
;     ...
;     for (int jb = 0; jb < 4; ++jb) {
;         const int ch = 64 * w + 16 * jb + r;
;         const float mu_r = mu[ch], mu_k = mu[512 + ch], mu_v = mu[1024 + ch];
;         const float w0 = c.in[6 + z_][l * 512 + ch], a0 = c.in[8 + z_][l * 512 + ch], kk_ = c.in[13 + z_][l * 512 + ch], ka_ = c.in[14 + z_][l * 512 + ch];
;         rkv[jb] = c.in[15 + z_][l * 512 + ch];
;         const float v0 = (l > 0) ? c.in[11 + z_][(l - 1) * 512 + ch] : 0.f;
; #pragma unroll
;         for (int e = 0; e < 4; ++e) {
;             const int tok = tok0 + 4 * q4 + e; const bool hp = (tok & (T - 1)) != 0;
;             const bf16* pr = P + (size_t)tok * PW + ch;
;             const float cr = bf2f(pr[0]), ck = bf2f(pr[512]), cv = bf2f(pr[1024]);
;             const bf16* pp = hp ? pr - PW : pr;
;             const float lr_ = bf2f(pp[0]), lk_ = bf2f(pp[512]), lv_ = bf2f(pp[1024]);
;             const float pr_ = hp ? lr_ : 0.f, pk_ = hp ? lk_ : 0.f, pv_ = hp ? lv_ : 0.f;
;             const float r_ = cr + (pr_ - cr) * mu_r, k_ = ck + (pk_ - ck) * mu_k; float v_ = cv + (pv_ - cv) * mu_v;
;             const float wl = -softplusf_(-(w0 + aw[jb][e])) - 0.5f;
;             const float d_ = __expf(-__expf(wl));
;             const float a_ = sigmoidf_(a0 + aa[jb][e]);
;             if (l == 0) ((bf16*)(wsl + WS_VFIRST))[(size_t)tok * 512 + ch] = (bf16)f2bf(v_);
;             else { const float vf = bf2f(((bf16*)(wsl + WS_VFIRST))[(size_t)tok * 512 + ch]); v_ = v_ + (vf - v_) * sigmoidf_(v0 + av[jb][e]); }
.LBB0_355:
	v_bfe_u32 v121, v116, 4, 2
	v_lshlrev_b32_e32 v118, 2, v121
	v_add_u32_e32 v70, s14, v118
	v_add_u32_e32 v2, -3, v70
	s_add_u32 s2, s24, 0x1c800000
	v_lshlrev_b64 v[72:73], 1, v[68:69]
	v_and_b32_e32 v0, 0x7fc, v2
	s_addc_u32 s3, s25, 0
	v_lshl_add_u64 v[98:99], s[30:31], 0, v[72:73]
	v_cmp_eq_u32_e64 s[44:45], 0, v0
	v_mov_b32_e32 v86, 0xffffc800
	v_lshl_add_u64 v[90:91], s[2:3], 0, v[72:73]
	v_mad_i64_i32 v[72:73], s[0:1], v2, s27, v[98:99]
	v_cndmask_b32_e64 v89, -1, 0, s[44:45]
	v_cndmask_b32_e64 v88, v86, 0, s[44:45]
	flat_load_ushort v0, v[72:73]
	flat_load_ushort v123, v[72:73] offset:1024
	flat_load_ushort v71, v[72:73] offset:2048
	v_lshl_add_u64 v[72:73], v[72:73], 0, v[88:89]
	flat_load_ushort v119, v[72:73]
	flat_load_ushort v125, v[72:73] offset:1024
	flat_load_ushort v72, v[72:73] offset:2048
	v_ashrrev_i32_e32 v3, 31, v2
	v_readlane_b32 s0, v250, 32
	v_readlane_b32 s1, v250, 33
	v_lshlrev_b64 v[86:87], 10, v[2:3]
	s_mov_b64 s[4:5], -1
	s_and_b64 vcc, exec, s[0:1]
	s_waitcnt vmcnt(0) lgkmcnt(0)
	v_lshlrev_b32_e32 v71, 16, v71
	v_lshlrev_b32_e32 v72, 16, v72
	v_cndmask_b32_e64 v72, v72, 0, s[44:45]
	v_sub_f32_e32 v72, v72, v71
	v_fmac_f32_e32 v71, v102, v72
	v_lshl_add_u64 v[72:73], v[90:91], 0, v[86:87]
	s_cbranch_vccz .LBB0_357
	flat_load_ushort v92, v[72:73]
	v_add_f32_e32 v64, v64, v103
	v_mul_f32_e32 v64, 0xbfb8aa3b, v64
	v_exp_f32_e32 v64, v64
	s_mov_b64 s[4:5], 0
	v_add_f32_e32 v64, 1.0, v64
	v_rcp_f32_e32 v64, v64
	s_waitcnt vmcnt(0) lgkmcnt(0)
	v_lshlrev_b32_e32 v92, 16, v92
	v_sub_f32_e32 v92, v92, v71
	v_fma_f32 v120, v64, v92, v71

; __device__ __forceinline__ unsigned f2bf(float f) { return pk2(f, f) & 0xffffu; }
; __device__ __forceinline__ float sigmoidf_(float x) { return __builtin_amdgcn_rcpf(1.0f + __expf(-x)); }
; __device__ __forceinline__ float softplusf_(float x) { return fmaxf(x, 0.f) + __logf(1.0f + __expf(-fabsf(x))); }
; __device__ __forceinline__ void rwkv_prep_unit(const Args& c, int u, int l, LAS unsigned char* lds) {
;     ...
; #pragma unroll
;         for (int e = 0; e < 4; ++e) {
;             const int tok = tok0 + 4 * q4 + e; const bool hp = (tok & (T - 1)) != 0;
;             const bf16* pr = P + (size_t)tok * PW + ch;
;             const float cr = bf2f(pr[0]), ck = bf2f(pr[512]), cv = bf2f(pr[1024]);
;             const bf16* pp = hp ? pr - PW : pr;
;             const float lr_ = bf2f(pp[0]), lk_ = bf2f(pp[512]), lv_ = bf2f(pp[1024]);
;             const float pr_ = hp ? lr_ : 0.f, pk_ = hp ? lk_ : 0.f, pv_ = hp ? lv_ : 0.f;
;             const float r_ = cr + (pr_ - cr) * mu_r, k_ = ck + (pk_ - ck) * mu_k; float v_ = cv + (pv_ - cv) * mu_v;
;             const float wl = -softplusf_(-(w0 + aw[jb][e])) - 0.5f;
;             const float d_ = __expf(-__expf(wl));
;             const float a_ = sigmoidf_(a0 + aa[jb][e]);
;             if (l == 0) ((bf16*)(wsl + WS_VFIRST))[(size_t)tok * 512 + ch] = (bf16)f2bf(v_);
;             else { const float vf = bf2f(((bf16*)(wsl + WS_VFIRST))[(size_t)tok * 512 + ch]); v_ = v_ + (vf - v_) * sigmoidf_(v0 + av[jb][e]); }
.LBB0_373:
	v_or_b32_e32 v112, 16, v68
	v_mad_i64_i32 v[64:65], s[0:1], v2, s27, 0
	v_ashrrev_i32_e32 v113, 31, v112
	v_lshl_add_u64 v[64:65], s[30:31], 0, v[64:65]
	v_lshlrev_b64 v[114:115], 1, v[112:113]
	v_lshl_add_u64 v[66:67], v[64:65], 0, v[114:115]
	flat_load_ushort v170, v[66:67]
	flat_load_ushort v99, v[66:67] offset:1024
	flat_load_ushort v66, v[66:67] offset:2048
	s_mov_b64 s[6:7], -1
	s_and_b64 vcc, exec, s[46:47]
	v_lshl_add_u64 v[90:91], s[2:3], 0, v[86:87]
	s_waitcnt vmcnt(0) lgkmcnt(0)
	v_lshlrev_b32_e32 v98, 16, v66
	v_lshl_add_u64 v[66:67], v[64:65], 0, v[88:89]
	v_lshl_add_u64 v[88:89], v[66:67], 0, v[114:115]
	flat_load_ushort v171, v[88:89]
	flat_load_ushort v172, v[88:89] offset:1024
	flat_load_ushort v88, v[88:89] offset:2048
	s_waitcnt vmcnt(0) lgkmcnt(0)
	v_lshlrev_b32_e32 v88, 16, v88
	v_cndmask_b32_e64 v88, v88, 0, s[44:45]
	v_sub_f32_e32 v88, v88, v98
	v_fmac_f32_e32 v98, v161, v88
	s_cbranch_vccnz .LBB0_375
	v_lshl_add_u64 v[86:87], v[112:113], 1, v[90:91]
	flat_load_ushort v86, v[86:87]
	v_add_f32_e32 v56, v56, v160
	v_mul_f32_e32 v56, 0xbfb8aa3b, v56
	v_exp_f32_e32 v56, v56
	s_mov_b64 s[6:7], 0
	v_add_f32_e32 v56, 1.0, v56
	v_rcp_f32_e32 v56, v56
	s_waitcnt vmcnt(0) lgkmcnt(0)
	v_lshlrev_b32_e32 v86, 16, v86
	v_sub_f32_e32 v86, v86, v98
	v_fma_f32 v127, v56, v86, v98

; __device__ __forceinline__ unsigned f2bf(float f) { return pk2(f, f) & 0xffffu; }
; __device__ __forceinline__ float sigmoidf_(float x) { return __builtin_amdgcn_rcpf(1.0f + __expf(-x)); }
; __device__ __forceinline__ float softplusf_(float x) { return fmaxf(x, 0.f) + __logf(1.0f + __expf(-fabsf(x))); }
; __device__ __forceinline__ void rwkv_prep_unit(const Args& c, int u, int l, LAS unsigned char* lds) {
;     ...
;         for (int e = 0; e < 4; ++e) {
;             const int tok = tok0 + 4 * q4 + e; const bool hp = (tok & (T - 1)) != 0;
;             const bf16* pr = P + (size_t)tok * PW + ch;
;             const float cr = bf2f(pr[0]), ck = bf2f(pr[512]), cv = bf2f(pr[1024]);
;             const bf16* pp = hp ? pr - PW : pr;
;             const float lr_ = bf2f(pp[0]), lk_ = bf2f(pp[512]), lv_ = bf2f(pp[1024]);
;             const float pr_ = hp ? lr_ : 0.f, pk_ = hp ? lk_ : 0.f, pv_ = hp ? lv_ : 0.f;
;             const float r_ = cr + (pr_ - cr) * mu_r, k_ = ck + (pk_ - ck) * mu_k; float v_ = cv + (pv_ - cv) * mu_v;
;             const float wl = -softplusf_(-(w0 + aw[jb][e])) - 0.5f;
;             const float d_ = __expf(-__expf(wl));
;             const float a_ = sigmoidf_(a0 + aa[jb][e]);
;             if (l == 0) ((bf16*)(wsl + WS_VFIRST))[(size_t)tok * 512 + ch] = (bf16)f2bf(v_);
;             else { const float vf = bf2f(((bf16*)(wsl + WS_VFIRST))[(size_t)tok * 512 + ch]); v_ = v_ + (vf - v_) * sigmoidf_(v0 + av[jb][e]); }
;             rr[jb][e] = r_; vv[jb][e] = v_; dec[jb][e] = d_; asg[jb][e] = a_;
;             kkr[jb][e] = k_ * kk_; k2[jb][e] = k_ * (1.0f + (a_ - 1.0f) * ka_);
;             ((bf16*)(wsl + WS_MIXED))[(size_t)tok * 2048 + ch] = (bf16)f2bf(ag[jb][e]);
.LBB0_381:
	v_lshl_add_u64 v[98:99], s[4:5], 0, v[94:95]
	v_cvt_pk_bf16_f32 v86, v53, s0
	v_lshl_add_u64 v[52:53], v[98:99], 0, v[114:115]
	flat_store_short v[52:53], v86
	flat_load_ushort v157, v[56:57]
	flat_load_ushort v52, v[56:57] offset:1024
	flat_load_ushort v53, v[56:57] offset:2048
	v_add_co_u32_e32 v92, vcc, 0xffffc800, v56
	s_mov_b64 s[6:7], -1
	s_nop 0
	v_addc_co_u32_e32 v93, vcc, -1, v57, vcc
	v_add_co_u32_e32 v56, vcc, 0xffffd000, v56
	flat_load_ushort v158, v[92:93]
	s_nop 0
	v_addc_co_u32_e32 v57, vcc, -1, v57, vcc
	s_and_b64 vcc, exec, s[46:47]
	s_waitcnt vmcnt(0) lgkmcnt(0)
	v_lshlrev_b32_e32 v86, 16, v53
	flat_load_ushort v53, v[56:57]
	v_lshl_add_u64 v[56:57], s[2:3], 0, v[108:109]
	s_waitcnt vmcnt(0) lgkmcnt(0)
	v_lshlrev_b32_e32 v53, 16, v53
	v_sub_f32_e32 v53, v53, v86
	v_fmac_f32_e32 v86, v161, v53
	s_cbranch_vccnz .LBB0_383
	v_lshl_add_u64 v[92:93], v[112:113], 1, v[56:57]
	flat_load_ushort v53, v[92:93]
	v_add_f32_e32 v58, v58, v160
	v_mul_f32_e32 v58, 0xbfb8aa3b, v58
	v_exp_f32_e32 v58, v58
	s_mov_b64 s[6:7], 0
	v_add_f32_e32 v58, 1.0, v58
	v_rcp_f32_e32 v58, v58
	s_waitcnt vmcnt(0) lgkmcnt(0)
	v_lshlrev_b32_e32 v53, 16, v53
	v_sub_f32_e32 v53, v53, v86
	v_fma_f32 v108, v58, v53, v86

; __device__ __forceinline__ unsigned f2bf(float f) { return pk2(f, f) & 0xffffu; }
; __device__ __forceinline__ float sigmoidf_(float x) { return __builtin_amdgcn_rcpf(1.0f + __expf(-x)); }
; __device__ __forceinline__ float softplusf_(float x) { return fmaxf(x, 0.f) + __logf(1.0f + __expf(-fabsf(x))); }
; __device__ __forceinline__ void rwkv_prep_unit(const Args& c, int u, int l, LAS unsigned char* lds) {
;     ...
;         for (int e = 0; e < 4; ++e) {
;             const int tok = tok0 + 4 * q4 + e; const bool hp = (tok & (T - 1)) != 0;
;             const bf16* pr = P + (size_t)tok * PW + ch;
;             const float cr = bf2f(pr[0]), ck = bf2f(pr[512]), cv = bf2f(pr[1024]);
;             const bf16* pp = hp ? pr - PW : pr;
;             const float lr_ = bf2f(pp[0]), lk_ = bf2f(pp[512]), lv_ = bf2f(pp[1024]);
;             const float pr_ = hp ? lr_ : 0.f, pk_ = hp ? lk_ : 0.f, pv_ = hp ? lv_ : 0.f;
;             const float r_ = cr + (pr_ - cr) * mu_r, k_ = ck + (pk_ - ck) * mu_k; float v_ = cv + (pv_ - cv) * mu_v;
;             const float wl = -softplusf_(-(w0 + aw[jb][e])) - 0.5f;
;             const float d_ = __expf(-__expf(wl));
;             const float a_ = sigmoidf_(a0 + aa[jb][e]);
;             if (l == 0) ((bf16*)(wsl + WS_VFIRST))[(size_t)tok * 512 + ch] = (bf16)f2bf(v_);
;             else { const float vf = bf2f(((bf16*)(wsl + WS_VFIRST))[(size_t)tok * 512 + ch]); v_ = v_ + (vf - v_) * sigmoidf_(v0 + av[jb][e]); }
;             rr[jb][e] = r_; vv[jb][e] = v_; dec[jb][e] = d_; asg[jb][e] = a_;
;             kkr[jb][e] = k_ * kk_; k2[jb][e] = k_ * (1.0f + (a_ - 1.0f) * ka_);
;             ((bf16*)(wsl + WS_MIXED))[(size_t)tok * 2048 + ch] = (bf16)f2bf(ag[jb][e]);
.LBB0_399:
	v_cvt_pk_bf16_f32 v105, v45, s0
	v_lshl_add_u64 v[44:45], v[98:99], 0, v[58:59]
	flat_store_short v[44:45], v105
	flat_load_ushort v173, v[48:49]
	flat_load_ushort v44, v[48:49] offset:1024
	flat_load_ushort v45, v[48:49] offset:2048
	v_add_co_u32_e32 v168, vcc, 0xffffc800, v48
	s_mov_b64 s[2:3], -1
	s_nop 0
	v_addc_co_u32_e32 v169, vcc, -1, v49, vcc
	v_add_co_u32_e32 v48, vcc, 0xffffd000, v48
	flat_load_ushort v176, v[168:169]
	s_nop 0
	v_addc_co_u32_e32 v49, vcc, -1, v49, vcc
	s_and_b64 vcc, exec, s[46:47]
	s_waitcnt vmcnt(0) lgkmcnt(0)
	v_lshlrev_b32_e32 v167, 16, v45
	flat_load_ushort v45, v[48:49]
	s_waitcnt vmcnt(0) lgkmcnt(0)
	v_lshlrev_b32_e32 v45, 16, v45
	v_sub_f32_e32 v45, v45, v167
	v_fmac_f32_e32 v167, v203, v45
	s_cbranch_vccnz .LBB0_401
	v_lshl_add_u64 v[48:49], v[54:55], 1, v[56:57]
	flat_load_ushort v45, v[48:49]
	v_add_f32_e32 v48, v50, v174
	v_mul_f32_e32 v48, 0xbfb8aa3b, v48
	v_exp_f32_e32 v48, v48
	s_mov_b64 s[2:3], 0
	v_add_f32_e32 v48, 1.0, v48
	v_rcp_f32_e32 v48, v48
	s_waitcnt vmcnt(0) lgkmcnt(0)
	v_lshlrev_b32_e32 v45, 16, v45
	v_sub_f32_e32 v45, v45, v167
	v_fma_f32 v105, v48, v45, v167

; __device__ __forceinline__ unsigned f2bf(float f) { return pk2(f, f) & 0xffffu; }
; __device__ __forceinline__ float sigmoidf_(float x) { return __builtin_amdgcn_rcpf(1.0f + __expf(-x)); }
; __device__ __forceinline__ float softplusf_(float x) { return fmaxf(x, 0.f) + __logf(1.0f + __expf(-fabsf(x))); }
; __device__ __forceinline__ void rwkv_prep_unit(const Args& c, int u, int l, LAS unsigned char* lds) {
;     ...
;     for (int jb = 0; jb < 4; ++jb) {
;         const int ch = 64 * w + 16 * jb + r;
;         const float mu_r = mu[ch], mu_k = mu[512 + ch], mu_v = mu[1024 + ch];
;         const float w0 = c.in[6 + z_][l * 512 + ch], a0 = c.in[8 + z_][l * 512 + ch], kk_ = c.in[13 + z_][l * 512 + ch], ka_ = c.in[14 + z_][l * 512 + ch];
;         rkv[jb] = c.in[15 + z_][l * 512 + ch];
;         const float v0 = (l > 0) ? c.in[11 + z_][(l - 1) * 512 + ch] : 0.f;
; #pragma unroll
;         for (int e = 0; e < 4; ++e) {
;             const int tok = tok0 + 4 * q4 + e; const bool hp = (tok & (T - 1)) != 0;
;             const bf16* pr = P + (size_t)tok * PW + ch;
;             const float cr = bf2f(pr[0]), ck = bf2f(pr[512]), cv = bf2f(pr[1024]);
;             const bf16* pp = hp ? pr - PW : pr;
;             const float lr_ = bf2f(pp[0]), lk_ = bf2f(pp[512]), lv_ = bf2f(pp[1024]);
;             const float pr_ = hp ? lr_ : 0.f, pk_ = hp ? lk_ : 0.f, pv_ = hp ? lv_ : 0.f;
;             const float r_ = cr + (pr_ - cr) * mu_r, k_ = ck + (pk_ - ck) * mu_k; float v_ = cv + (pv_ - cv) * mu_v;
;             const float wl = -softplusf_(-(w0 + aw[jb][e])) - 0.5f;
;             const float d_ = __expf(-__expf(wl));
;             const float a_ = sigmoidf_(a0 + aa[jb][e]);
;             if (l == 0) ((bf16*)(wsl + WS_VFIRST))[(size_t)tok * 512 + ch] = (bf16)f2bf(v_);
;             else { const float vf = bf2f(((bf16*)(wsl + WS_VFIRST))[(size_t)tok * 512 + ch]); v_ = v_ + (vf - v_) * sigmoidf_(v0 + av[jb][e]); }
.LBB0_407:
	v_cvt_pk_bf16_f32 v46, v47, s0
	v_lshl_add_u64 v[44:45], v[54:55], 1, v[52:53]
	flat_store_short v[44:45], v46
	v_add_co_u32_e32 v44, vcc, 0x1000, v74
	global_load_dword v51, v[74:75], off offset:192
	global_load_dword v174, v[74:75], off offset:2240
	v_addc_co_u32_e32 v45, vcc, 0, v75, vcc
	global_load_dword v203, v[44:45], off offset:192
	global_load_dword v74, v[76:77], off offset:192
	global_load_dword v79, v[78:79], off offset:192
	global_load_dword v78, v[80:81], off offset:192
	global_load_dword v77, v[82:83], off offset:192
	global_load_dword v75, v[84:85], off offset:192
	v_mov_b32_e32 v81, 0
	s_and_b64 vcc, exec, s[42:43]
	s_cbranch_vccnz .LBB0_409
	s_load_dwordx2 s[0:1], s[12:13], 0x58
	s_waitcnt lgkmcnt(0)
	v_lshl_add_u64 v[44:45], v[62:63], 2, s[0:1]
	global_load_dword v81, v[44:45], off offset:192
.LBB0_409:
	v_or_b32_e32 v46, 48, v68
	v_ashrrev_i32_e32 v47, 31, v46
	v_lshlrev_b64 v[44:45], 1, v[46:47]
	v_lshl_add_u64 v[48:49], v[64:65], 0, v[44:45]
	v_lshl_add_u64 v[54:55], v[66:67], 0, v[44:45]
	flat_load_ushort v59, v[48:49] offset:2048
	flat_load_ushort v65, v[54:55] offset:2048
	flat_load_ushort v62, v[48:49]
	flat_load_ushort v48, v[48:49] offset:1024
	flat_load_ushort v63, v[54:55]
	flat_load_ushort v64, v[54:55] offset:1024
	s_and_b64 vcc, exec, s[46:47]
	s_mov_b64 s[2:3], -1
	s_waitcnt vmcnt(0) lgkmcnt(0)
	v_lshlrev_b32_e32 v55, 16, v59
	v_lshlrev_b32_e32 v49, 16, v65
	v_cndmask_b32_e64 v49, v49, 0, s[44:45]
	v_sub_f32_e32 v49, v49, v55
	v_fmac_f32_e32 v55, v203, v49
	s_cbranch_vccnz .LBB0_411
	v_lshl_add_u64 v[66:67], v[46:47], 1, v[90:91]
	flat_load_ushort v49, v[66:67]
	v_add_f32_e32 v40, v40, v81
	v_mul_f32_e32 v40, 0xbfb8aa3b, v40
	v_exp_f32_e32 v40, v40
	s_mov_b64 s[2:3], 0
	v_add_f32_e32 v40, 1.0, v40
	v_rcp_f32_e32 v40, v40
	s_waitcnt vmcnt(0) lgkmcnt(0)
	v_lshlrev_b32_e32 v49, 16, v49
	v_sub_f32_e32 v49, v49, v55
	v_fma_f32 v54, v40, v49, v55

; __device__ __forceinline__ unsigned f2bf(float f) { return pk2(f, f) & 0xffffu; }
; __device__ __forceinline__ float sigmoidf_(float x) { return __builtin_amdgcn_rcpf(1.0f + __expf(-x)); }
; __device__ __forceinline__ float softplusf_(float x) { return fmaxf(x, 0.f) + __logf(1.0f + __expf(-fabsf(x))); }
; __device__ __forceinline__ void rwkv_prep_unit(const Args& c, int u, int l, LAS unsigned char* lds) {
;     ...
;         for (int e = 0; e < 4; ++e) {
;             const int tok = tok0 + 4 * q4 + e; const bool hp = (tok & (T - 1)) != 0;
;             const bf16* pr = P + (size_t)tok * PW + ch;
;             const float cr = bf2f(pr[0]), ck = bf2f(pr[512]), cv = bf2f(pr[1024]);
;             const bf16* pp = hp ? pr - PW : pr;
;             const float lr_ = bf2f(pp[0]), lk_ = bf2f(pp[512]), lv_ = bf2f(pp[1024]);
;             const float pr_ = hp ? lr_ : 0.f, pk_ = hp ? lk_ : 0.f, pv_ = hp ? lv_ : 0.f;
;             const float r_ = cr + (pr_ - cr) * mu_r, k_ = ck + (pk_ - ck) * mu_k; float v_ = cv + (pv_ - cv) * mu_v;
;             const float wl = -softplusf_(-(w0 + aw[jb][e])) - 0.5f;
;             const float d_ = __expf(-__expf(wl));
;             const float a_ = sigmoidf_(a0 + aa[jb][e]);
;             if (l == 0) ((bf16*)(wsl + WS_VFIRST))[(size_t)tok * 512 + ch] = (bf16)f2bf(v_);
;             else { const float vf = bf2f(((bf16*)(wsl + WS_VFIRST))[(size_t)tok * 512 + ch]); v_ = v_ + (vf - v_) * sigmoidf_(v0 + av[jb][e]); }
;             rr[jb][e] = r_; vv[jb][e] = v_; dec[jb][e] = d_; asg[jb][e] = a_;
;             kkr[jb][e] = k_ * kk_; k2[jb][e] = k_ * (1.0f + (a_ - 1.0f) * ka_);
;             ((bf16*)(wsl + WS_MIXED))[(size_t)tok * 2048 + ch] = (bf16)f2bf(ag[jb][e]);
.LBB0_417:
	v_cvt_pk_bf16_f32 v48, v37, s0
	v_lshl_add_u64 v[36:37], v[98:99], 0, v[44:45]
	flat_store_short v[36:37], v48
	flat_load_ushort v48, v[40:41]
	flat_load_ushort v36, v[40:41] offset:1024
	flat_load_ushort v37, v[40:41] offset:2048
	v_add_co_u32_e32 v88, vcc, 0xffffc800, v40
	s_mov_b64 s[2:3], -1
	s_nop 0
	v_addc_co_u32_e32 v89, vcc, -1, v41, vcc
	v_add_co_u32_e32 v40, vcc, 0xffffd000, v40
	flat_load_ushort v49, v[88:89]
	s_nop 0
	v_addc_co_u32_e32 v41, vcc, -1, v41, vcc
	s_and_b64 vcc, exec, s[46:47]
	s_waitcnt vmcnt(0) lgkmcnt(0)
	v_lshlrev_b32_e32 v67, 16, v37
	flat_load_ushort v37, v[40:41]
	s_waitcnt vmcnt(0) lgkmcnt(0)
	v_lshlrev_b32_e32 v37, 16, v37
	v_sub_f32_e32 v37, v37, v67
	v_fmac_f32_e32 v67, v203, v37
	s_cbranch_vccnz .LBB0_419
	v_lshl_add_u64 v[40:41], v[46:47], 1, v[56:57]
	flat_load_ushort v37, v[40:41]
	v_add_f32_e32 v40, v42, v81
	v_mul_f32_e32 v40, 0xbfb8aa3b, v40
	v_exp_f32_e32 v40, v40
	s_mov_b64 s[2:3], 0
	v_add_f32_e32 v40, 1.0, v40
	v_rcp_f32_e32 v40, v40
	s_waitcnt vmcnt(0) lgkmcnt(0)
	v_lshlrev_b32_e32 v37, 16, v37
	v_sub_f32_e32 v37, v37, v67
	v_fma_f32 v59, v40, v37, v67

; #define LAS __attribute__((address_space(3)))
; __device__ __forceinline__ void transpose_item(const float* W, int K, int N, bf16* WT, LAS float* scr, int item, int nblk, int lane, int mode, const float* W2) {
;     const int kb = item / nblk, nb = item % nblk, k0 = 64 * kb, n0 = 128 * nb;
;     const int c32 = lane & 31, nn = n0 + 4 * c32;
;     const int sc = src_col(mode, nn);
;     f32x4 vals[32];
;     {
;         const bool useW = sc >= 0, use2 = (sc == -2) && (W2 != nullptr);
;         const float* pl = useW ? W + (size_t)(k0 + (lane >> 5)) * N + sc : (use2 ? W2 + (size_t)(k0 + (lane >> 5)) * 32 + (nn - 1792) : W);
;         const size_t step = useW ? (size_t)2 * N : (use2 ? 64 : 0);
; #pragma unroll
;         for (int i = 0; i < 32; ++i) { f32x4 v = *(const f32x4*)pl; pl += step; if (!(useW || use2)) v = (f32x4){0.f, 0.f, 0.f, 0.f}; vals[i] = v; }
;     }
; __device__ __forceinline__ void prep_phase(const Args& c, int l, LAS unsigned char* lds, int vcu, int G) {
;     ...
;     for (int it = gw; it < I_IN + I_OUT + I_FI + I_FO; it += NGW) {
;         int r = it;
;         if (r < I_IN) { transpose_item(w_in, D, NINW, ((bf16*)(wsl + WS_WIN)), scr, r, PW / 128, lane, 1, w_vres); continue; } r -= I_IN;
;         if (r < I_OUT) { transpose_item(w_out, D, D, ((bf16*)(wsl + WS_WOUT)), scr, r, D / 128, lane, 0, nullptr); continue; } r -= I_OUT;
;         if (r < I_FI) { transpose_item(w_fi, D, 2 * FF, ((bf16*)(wsl + WS_WFI)), scr, r, 2 * FF / 128, lane, 2, nullptr); continue; } r -= I_FI;
;         transpose_item(w_fo, FF, D, ((bf16*)(wsl + WS_WFO)), scr, r, D / 128, lane, 0, nullptr);
.LBB0_511:
	s_cmpk_gt_i32 s28, 0x6ff
	s_mov_b64 s[2:3], -1
	s_cbranch_scc0 .LBB0_532
	s_cmpk_gt_u32 s28, 0x8ff
	s_cbranch_scc0 .LBB0_525
	s_cmpk_gt_u32 s28, 0x13ff
	s_cbranch_scc0 .LBB0_519
	s_and_b32 s1, s20, 0x3ffc0
	s_add_i32 s0, s18, 0xf80
	s_and_b32 s0, s0, 0x780
	v_or_b32_e32 v0, s1, v144
	v_or_b32_e32 v4, s0, v135
	v_lshlrev_b32_e32 v0, 13, v0
	v_lshl_add_u64 v[2:3], s[52:53], 0, v[0:1]
	v_lshlrev_b32_e32 v0, 2, v4
	v_lshl_add_u64 v[122:123], v[2:3], 0, v[0:1]
	v_add_co_u32_e32 v6, vcc, 0x4000, v122
	s_mov_b32 s2, 0x10000
	s_nop 0
	v_addc_co_u32_e32 v7, vcc, 0, v123, vcc
	v_add_co_u32_e32 v10, vcc, 0x8000, v122
	global_load_dwordx4 v[2:5], v[122:123], off
	global_load_dwordx4 v[6:9], v[6:7], off
	v_addc_co_u32_e32 v11, vcc, 0, v123, vcc
	v_add_co_u32_e32 v12, vcc, 0xc000, v122
	s_nop 1
	v_addc_co_u32_e32 v13, vcc, 0, v123, vcc
	v_add_co_u32_e32 v18, vcc, s2, v122
	s_mov_b32 s2, 0x14000
	s_nop 0
	v_addc_co_u32_e32 v19, vcc, 0, v123, vcc
	v_add_co_u32_e32 v20, vcc, s2, v122
	s_mov_b32 s2, 0x18000
	s_nop 0
	v_addc_co_u32_e32 v21, vcc, 0, v123, vcc
	v_add_co_u32_e32 v26, vcc, s2, v122
	s_mov_b32 s2, 0x1c000
	s_nop 0
	v_addc_co_u32_e32 v27, vcc, 0, v123, vcc
	v_add_co_u32_e32 v28, vcc, s2, v122
	s_mov_b32 s2, 0x20000
	s_nop 0
	v_addc_co_u32_e32 v29, vcc, 0, v123, vcc
	v_add_co_u32_e32 v34, vcc, s2, v122
	s_mov_b32 s2, 0x24000
	s_nop 0
	v_addc_co_u32_e32 v35, vcc, 0, v123, vcc
	v_add_co_u32_e32 v36, vcc, s2, v122
	s_mov_b32 s2, 0x28000
	s_nop 0
	v_addc_co_u32_e32 v37, vcc, 0, v123, vcc
	v_add_co_u32_e32 v42, vcc, s2, v122
	s_mov_b32 s2, 0x2c000
	s_nop 0
	v_addc_co_u32_e32 v43, vcc, 0, v123, vcc
	v_add_co_u32_e32 v44, vcc, s2, v122
	s_mov_b32 s2, 0x30000
	s_nop 0
	v_addc_co_u32_e32 v45, vcc, 0, v123, vcc
	v_add_co_u32_e32 v50, vcc, s2, v122
	s_mov_b32 s2, 0x34000
	s_nop 0
	v_addc_co_u32_e32 v51, vcc, 0, v123, vcc
	v_add_co_u32_e32 v52, vcc, s2, v122
	s_mov_b32 s2, 0x38000
	s_nop 0
	v_addc_co_u32_e32 v53, vcc, 0, v123, vcc
	v_add_co_u32_e32 v58, vcc, s2, v122
	s_mov_b32 s2, 0x3c000
	s_nop 0
	v_addc_co_u32_e32 v59, vcc, 0, v123, vcc
	v_add_co_u32_e32 v60, vcc, s2, v122
	s_mov_b32 s2, 0x40000
	s_nop 0
	v_addc_co_u32_e32 v61, vcc, 0, v123, vcc
	v_add_co_u32_e32 v66, vcc, s2, v122
	s_mov_b32 s2, 0x44000
	s_nop 0
	v_addc_co_u32_e32 v67, vcc, 0, v123, vcc
	v_add_co_u32_e32 v68, vcc, s2, v122
	s_mov_b32 s2, 0x48000
	s_nop 0
	v_addc_co_u32_e32 v69, vcc, 0, v123, vcc
	v_add_co_u32_e32 v74, vcc, s2, v122
	s_mov_b32 s2, 0x4c000
	s_nop 0
	v_addc_co_u32_e32 v75, vcc, 0, v123, vcc
	v_add_co_u32_e32 v76, vcc, s2, v122
	s_mov_b32 s2, 0x50000
	s_nop 0
	v_addc_co_u32_e32 v77, vcc, 0, v123, vcc
	v_add_co_u32_e32 v82, vcc, s2, v122
	s_mov_b32 s2, 0x54000
	s_nop 0
	v_addc_co_u32_e32 v83, vcc, 0, v123, vcc
	v_add_co_u32_e32 v84, vcc, s2, v122
	s_mov_b32 s2, 0x58000
	s_nop 0
	v_addc_co_u32_e32 v85, vcc, 0, v123, vcc
	v_add_co_u32_e32 v90, vcc, s2, v122
	s_mov_b32 s2, 0x5c000
	s_nop 0
	v_addc_co_u32_e32 v91, vcc, 0, v123, vcc
	v_add_co_u32_e32 v92, vcc, s2, v122
	s_mov_b32 s2, 0x60000
	s_nop 0
	v_addc_co_u32_e32 v93, vcc, 0, v123, vcc
	v_add_co_u32_e32 v98, vcc, s2, v122
	s_mov_b32 s2, 0x64000
	s_nop 0
	v_addc_co_u32_e32 v99, vcc, 0, v123, vcc
	v_add_co_u32_e32 v100, vcc, s2, v122
	s_mov_b32 s2, 0x68000
	s_nop 0
	v_addc_co_u32_e32 v101, vcc, 0, v123, vcc
	v_add_co_u32_e32 v106, vcc, s2, v122
	s_mov_b32 s2, 0x6c000
	s_nop 0
	v_addc_co_u32_e32 v107, vcc, 0, v123, vcc
	v_add_co_u32_e32 v108, vcc, s2, v122
	s_mov_b32 s2, 0x70000
	s_nop 0
	v_addc_co_u32_e32 v109, vcc, 0, v123, vcc
	v_add_co_u32_e32 v114, vcc, s2, v122
	global_load_dwordx4 v[14:17], v[10:11], off
	global_load_dwordx4 v[10:13], v[12:13], off
	v_addc_co_u32_e32 v115, vcc, 0, v123, vcc
	v_add_co_u32_e32 v116, vcc, 0x74000, v122
	global_load_dwordx4 v[22:25], v[18:19], off
	global_load_dwordx4 v[18:21], v[20:21], off
	v_addc_co_u32_e32 v117, vcc, 0, v123, vcc
	v_add_co_u32_e32 v124, vcc, 0x78000, v122
	global_load_dwordx4 v[30:33], v[26:27], off
	global_load_dwordx4 v[26:29], v[28:29], off
	v_addc_co_u32_e32 v125, vcc, 0, v123, vcc
	v_add_co_u32_e32 v122, vcc, 0x7c000, v122
	global_load_dwordx4 v[38:41], v[34:35], off
	global_load_dwordx4 v[34:37], v[36:37], off
	v_addc_co_u32_e32 v123, vcc, 0, v123, vcc
	global_load_dwordx4 v[46:49], v[42:43], off
	global_load_dwordx4 v[42:45], v[44:45], off
	global_load_dwordx4 v[54:57], v[50:51], off
	global_load_dwordx4 v[50:53], v[52:53], off
	global_load_dwordx4 v[62:65], v[58:59], off
	global_load_dwordx4 v[58:61], v[60:61], off
	global_load_dwordx4 v[70:73], v[66:67], off
	global_load_dwordx4 v[66:69], v[68:69], off
	global_load_dwordx4 v[78:81], v[74:75], off
	global_load_dwordx4 v[74:77], v[76:77], off
	global_load_dwordx4 v[86:89], v[82:83], off
	global_load_dwordx4 v[82:85], v[84:85], off
	global_load_dwordx4 v[94:97], v[90:91], off
	global_load_dwordx4 v[90:93], v[92:93], off
	global_load_dwordx4 v[102:105], v[98:99], off
	global_load_dwordx4 v[98:101], v[100:101], off
	global_load_dwordx4 v[110:113], v[106:107], off
	global_load_dwordx4 v[106:109], v[108:109], off
	global_load_dwordx4 v[118:121], v[114:115], off
	global_load_dwordx4 v[114:117], v[116:117], off
	global_load_dwordx4 v[126:129], v[124:125], off
	global_load_dwordx4 v[122:125], v[122:123], off
	s_and_saveexec_b64 s[2:3], s[44:45]
	s_cbranch_execz .LBB0_516
; #define LAS __attribute__((address_space(3)))
; __device__ __forceinline__ void transpose_item(const float* W, int K, int N, bf16* WT, LAS float* scr, int item, int nblk, int lane, int mode, const float* W2) {
;     ...
; #pragma unroll
;     for (int pass = 0; pass < 2; ++pass) {
;         if ((c32 >> 4) == pass) {
;             const int cc = 4 * (c32 & 15);
; #pragma unroll
;             for (int i = 0; i < 32; ++i) { LAS float* d = scr + (2 * i + (lane >> 5)) * 65 + cc; d[0] = vals[i].x; d[1] = vals[i].y; d[2] = vals[i].z; d[3] = vals[i].w; }
;         }
	v_add_u32_e32 v0, 0x410, v147
	s_waitcnt vmcnt(0)
	ds_write2_b32 v147, v2, v3 offset1:1
	ds_write2_b32 v147, v4, v5 offset0:2 offset1:3
	ds_write2_b32 v147, v6, v7 offset0:130 offset1:131
	ds_write2_b32 v147, v8, v9 offset0:132 offset1:133
	ds_write2_b32 v0, v14, v15 offset1:1
	v_add_u32_e32 v0, 0x418, v147
	ds_write2_b32 v0, v16, v17 offset1:1
	v_add_u32_e32 v0, 0x618, v147
	ds_write2_b32 v0, v10, v11 offset1:1
	v_add_u32_e32 v0, 0x620, v147
	ds_write2_b32 v0, v12, v13 offset1:1
	v_add_u32_e32 v0, 0x820, v147
	ds_write2_b32 v0, v22, v23 offset1:1
	v_add_u32_e32 v0, 0x828, v147
	ds_write2_b32 v0, v24, v25 offset1:1
	v_add_u32_e32 v0, 0xa28, v147
	ds_write2_b32 v0, v18, v19 offset1:1
	v_add_u32_e32 v0, 0xa30, v147
	ds_write2_b32 v0, v20, v21 offset1:1
	v_add_u32_e32 v0, 0xc30, v147
	ds_write2_b32 v0, v30, v31 offset1:1
	v_add_u32_e32 v0, 0xc38, v147
	ds_write2_b32 v0, v32, v33 offset1:1
	v_add_u32_e32 v0, 0xe38, v147
	ds_write2_b32 v0, v26, v27 offset1:1
	v_add_u32_e32 v0, 0xe40, v147
	ds_write2_b32 v0, v28, v29 offset1:1
	v_add_u32_e32 v0, 0x1040, v147
	ds_write2_b32 v0, v38, v39 offset1:1
	v_add_u32_e32 v0, 0x1048, v147
	ds_write2_b32 v0, v40, v41 offset1:1
	v_add_u32_e32 v0, 0x1248, v147
	ds_write2_b32 v0, v34, v35 offset1:1
	v_add_u32_e32 v0, 0x1250, v147
	ds_write2_b32 v0, v36, v37 offset1:1
	v_add_u32_e32 v0, 0x1450, v147
	ds_write2_b32 v0, v46, v47 offset1:1
	v_add_u32_e32 v0, 0x1458, v147
	ds_write2_b32 v0, v48, v49 offset1:1
	v_add_u32_e32 v0, 0x1658, v147
	ds_write2_b32 v0, v42, v43 offset1:1
	v_add_u32_e32 v0, 0x1660, v147
	ds_write2_b32 v0, v44, v45 offset1:1
	v_add_u32_e32 v0, 0x1860, v147
	ds_write2_b32 v0, v54, v55 offset1:1
	v_add_u32_e32 v0, 0x1868, v147
	ds_write2_b32 v0, v56, v57 offset1:1
	v_add_u32_e32 v0, 0x1a68, v147
	ds_write2_b32 v0, v50, v51 offset1:1
	v_add_u32_e32 v0, 0x1a70, v147
	ds_write2_b32 v0, v52, v53 offset1:1
	v_add_u32_e32 v0, 0x1c70, v147
	ds_write2_b32 v0, v62, v63 offset1:1
	v_add_u32_e32 v0, 0x1c78, v147
	ds_write2_b32 v0, v64, v65 offset1:1
	v_add_u32_e32 v0, 0x1e78, v147
	ds_write2_b32 v0, v58, v59 offset1:1
	v_add_u32_e32 v0, 0x1e80, v147
	ds_write2_b32 v0, v60, v61 offset1:1
	v_add_u32_e32 v0, 0x2080, v147
	ds_write2_b32 v0, v70, v71 offset1:1
	v_add_u32_e32 v0, 0x2088, v147
	ds_write2_b32 v0, v72, v73 offset1:1
	v_add_u32_e32 v0, 0x2288, v147
	ds_write2_b32 v0, v66, v67 offset1:1
	v_add_u32_e32 v0, 0x2290, v147
	ds_write2_b32 v0, v68, v69 offset1:1
	v_add_u32_e32 v0, 0x2490, v147
	ds_write2_b32 v0, v78, v79 offset1:1
	v_add_u32_e32 v0, 0x2498, v147
	ds_write2_b32 v0, v80, v81 offset1:1
	v_add_u32_e32 v0, 0x2698, v147
	ds_write2_b32 v0, v74, v75 offset1:1
	v_add_u32_e32 v0, 0x26a0, v147
	ds_write2_b32 v0, v76, v77 offset1:1
	v_add_u32_e32 v0, 0x28a0, v147
	ds_write2_b32 v0, v86, v87 offset1:1
	v_add_u32_e32 v0, 0x28a8, v147
	ds_write2_b32 v0, v88, v89 offset1:1
	v_add_u32_e32 v0, 0x2aa8, v147
	ds_write2_b32 v0, v82, v83 offset1:1
	v_add_u32_e32 v0, 0x2ab0, v147
	ds_write2_b32 v0, v84, v85 offset1:1
	v_add_u32_e32 v0, 0x2cb0, v147
	ds_write2_b32 v0, v94, v95 offset1:1
	v_add_u32_e32 v0, 0x2cb8, v147
	ds_write2_b32 v0, v96, v97 offset1:1
	v_add_u32_e32 v0, 0x2eb8, v147
	ds_write2_b32 v0, v90, v91 offset1:1
	v_add_u32_e32 v0, 0x2ec0, v147
	ds_write2_b32 v0, v92, v93 offset1:1
	v_add_u32_e32 v0, 0x30c0, v147
	ds_write2_b32 v0, v102, v103 offset1:1
	v_add_u32_e32 v0, 0x30c8, v147
	ds_write2_b32 v0, v104, v105 offset1:1
	v_add_u32_e32 v0, 0x32c8, v147
	ds_write2_b32 v0, v98, v99 offset1:1
	v_add_u32_e32 v0, 0x32d0, v147
	ds_write2_b32 v0, v100, v101 offset1:1
	v_add_u32_e32 v0, 0x34d0, v147
	ds_write2_b32 v0, v110, v111 offset1:1
	v_add_u32_e32 v0, 0x34d8, v147
	ds_write2_b32 v0, v112, v113 offset1:1
	v_add_u32_e32 v0, 0x36d8, v147
	ds_write2_b32 v0, v106, v107 offset1:1
	v_add_u32_e32 v0, 0x36e0, v147
	ds_write2_b32 v0, v108, v109 offset1:1
	v_add_u32_e32 v0, 0x38e0, v147
	ds_write2_b32 v0, v118, v119 offset1:1
	v_add_u32_e32 v0, 0x38e8, v147
	ds_write2_b32 v0, v120, v121 offset1:1
	v_add_u32_e32 v0, 0x3ae8, v147
	ds_write2_b32 v0, v114, v115 offset1:1
	v_add_u32_e32 v0, 0x3af0, v147
	ds_write2_b32 v0, v116, v117 offset1:1
	v_add_u32_e32 v0, 0x3cf0, v147
	ds_write2_b32 v0, v126, v127 offset1:1
	v_add_u32_e32 v0, 0x3cf8, v147
	ds_write2_b32 v0, v128, v129 offset1:1
	v_add_u32_e32 v0, 0x3ef8, v147
	ds_write2_b32 v0, v122, v123 offset1:1
	v_add_u32_e32 v0, 0x3f00, v147
	ds_write2_b32 v0, v124, v125 offset1:1

; #define LAS __attribute__((address_space(3)))
; __device__ __forceinline__ int src_col(int mode, int n) {
;     if (mode == 0) return n;
;     if (mode == 2) { const int g = n >> 3, e = n & 7; return (e < 4) ? 4 * g + e : FF + 4 * g + (e - 4); }
; __device__ __forceinline__ void transpose_item(const float* W, int K, int N, bf16* WT, LAS float* scr, int item, int nblk, int lane, int mode, const float* W2) {
;     const int kb = item / nblk, nb = item % nblk, k0 = 64 * kb, n0 = 128 * nb;
;     const int c32 = lane & 31, nn = n0 + 4 * c32;
;     const int sc = src_col(mode, nn);
;     f32x4 vals[32];
;     {
;         const bool useW = sc >= 0, use2 = (sc == -2) && (W2 != nullptr);
;         const float* pl = useW ? W + (size_t)(k0 + (lane >> 5)) * N + sc : (use2 ? W2 + (size_t)(k0 + (lane >> 5)) * 32 + (nn - 1792) : W);
;         const size_t step = useW ? (size_t)2 * N : (use2 ? 64 : 0);
; #pragma unroll
;         for (int i = 0; i < 32; ++i) { f32x4 v = *(const f32x4*)pl; pl += step; if (!(useW || use2)) v = (f32x4){0.f, 0.f, 0.f, 0.f}; vals[i] = v; }
;     }
.LBB0_519:
	s_and_b64 vcc, exec, s[2:3]
	s_cbranch_vccz .LBB0_551
	s_add_i32 s0, s28, 0xf700
	s_and_b32 s1, s0, 0xffff
	s_mul_i32 s1, s1, 0xba2f
	s_lshr_b32 s2, s1, 16
	s_lshr_b32 s1, s1, 22
	s_mulk_i32 s1, 0x58
	s_sub_i32 s0, s0, s1
	s_lshl_b32 s0, s0, 7
	s_and_b32 s0, s0, 0xff80
	v_or_b32_e32 v0, s0, v135
	s_and_b32 s1, s2, 0xffc0
	v_lshrrev_b32_e32 v0, 1, v0
	v_and_b32_e32 v4, 0x1ffc, v0
	v_or_b32_e32 v0, s1, v144
	v_mul_u32_u24_e32 v0, 0x2c00, v0
	v_lshlrev_b32_e32 v0, 2, v0
	v_lshl_add_u64 v[2:3], s[50:51], 0, v[0:1]
	v_add_lshl_u32 v0, v4, v155, 2
	v_lshl_add_u64 v[122:123], v[2:3], 0, v[0:1]
	s_mov_b32 s2, 0x16000
	v_add_co_u32_e32 v6, vcc, s2, v122
	s_mov_b32 s2, 0x2c000
	s_nop 0
	v_addc_co_u32_e32 v7, vcc, 0, v123, vcc
	v_add_co_u32_e32 v10, vcc, s2, v122
	s_mov_b32 s2, 0x42000
	s_nop 0
	v_addc_co_u32_e32 v11, vcc, 0, v123, vcc
	v_add_co_u32_e32 v12, vcc, s2, v122
	s_mov_b32 s2, 0x58000
	s_nop 0
	v_addc_co_u32_e32 v13, vcc, 0, v123, vcc
	v_add_co_u32_e32 v18, vcc, s2, v122
	s_mov_b32 s2, 0x6e000
	s_nop 0
	v_addc_co_u32_e32 v19, vcc, 0, v123, vcc
	v_add_co_u32_e32 v20, vcc, s2, v122
	s_mov_b32 s2, 0x84000
	s_nop 0
	v_addc_co_u32_e32 v21, vcc, 0, v123, vcc
	v_add_co_u32_e32 v26, vcc, s2, v122
	s_mov_b32 s2, 0x9a000
	s_nop 0
	v_addc_co_u32_e32 v27, vcc, 0, v123, vcc
	v_add_co_u32_e32 v28, vcc, s2, v122
	s_mov_b32 s2, 0xb0000
	s_nop 0
	v_addc_co_u32_e32 v29, vcc, 0, v123, vcc
	v_add_co_u32_e32 v34, vcc, s2, v122
	s_mov_b32 s2, 0xc6000
	s_nop 0
	v_addc_co_u32_e32 v35, vcc, 0, v123, vcc
	v_add_co_u32_e32 v36, vcc, s2, v122
	s_mov_b32 s2, 0xdc000
	s_nop 0
	v_addc_co_u32_e32 v37, vcc, 0, v123, vcc
	v_add_co_u32_e32 v42, vcc, s2, v122
	s_mov_b32 s2, 0xf2000
	s_nop 0
	v_addc_co_u32_e32 v43, vcc, 0, v123, vcc
	v_add_co_u32_e32 v44, vcc, s2, v122
	s_mov_b32 s2, 0x108000
	s_nop 0
	v_addc_co_u32_e32 v45, vcc, 0, v123, vcc
	v_add_co_u32_e32 v50, vcc, s2, v122
	s_mov_b32 s2, 0x11e000
	s_nop 0
	v_addc_co_u32_e32 v51, vcc, 0, v123, vcc
	v_add_co_u32_e32 v52, vcc, s2, v122
	s_mov_b32 s2, 0x134000
	s_nop 0
	v_addc_co_u32_e32 v53, vcc, 0, v123, vcc
	v_add_co_u32_e32 v58, vcc, s2, v122
	s_mov_b32 s2, 0x14a000
	s_nop 0
	v_addc_co_u32_e32 v59, vcc, 0, v123, vcc
	v_add_co_u32_e32 v60, vcc, s2, v122
	s_mov_b32 s2, 0x160000
	s_nop 0
	v_addc_co_u32_e32 v61, vcc, 0, v123, vcc
	v_add_co_u32_e32 v66, vcc, s2, v122
	s_mov_b32 s2, 0x176000
	s_nop 0
	v_addc_co_u32_e32 v67, vcc, 0, v123, vcc
	v_add_co_u32_e32 v68, vcc, s2, v122
	s_mov_b32 s2, 0x18c000
	s_nop 0
	v_addc_co_u32_e32 v69, vcc, 0, v123, vcc
	v_add_co_u32_e32 v74, vcc, s2, v122
	s_mov_b32 s2, 0x1a2000
	s_nop 0
	v_addc_co_u32_e32 v75, vcc, 0, v123, vcc
	v_add_co_u32_e32 v76, vcc, s2, v122
	s_mov_b32 s2, 0x1b8000
	s_nop 0
	v_addc_co_u32_e32 v77, vcc, 0, v123, vcc
	v_add_co_u32_e32 v82, vcc, s2, v122
	s_mov_b32 s2, 0x1ce000
	s_nop 0
	v_addc_co_u32_e32 v83, vcc, 0, v123, vcc
	v_add_co_u32_e32 v84, vcc, s2, v122
	s_mov_b32 s2, 0x1e4000
	s_nop 0
	v_addc_co_u32_e32 v85, vcc, 0, v123, vcc
	v_add_co_u32_e32 v90, vcc, s2, v122
	s_mov_b32 s2, 0x1fa000
	s_nop 0
	v_addc_co_u32_e32 v91, vcc, 0, v123, vcc
	v_add_co_u32_e32 v92, vcc, s2, v122
	s_mov_b32 s2, 0x210000
	s_nop 0
	v_addc_co_u32_e32 v93, vcc, 0, v123, vcc
	v_add_co_u32_e32 v98, vcc, s2, v122
	s_mov_b32 s2, 0x226000
	s_nop 0
	v_addc_co_u32_e32 v99, vcc, 0, v123, vcc
	v_add_co_u32_e32 v100, vcc, s2, v122
	s_mov_b32 s2, 0x23c000
	s_nop 0
	v_addc_co_u32_e32 v101, vcc, 0, v123, vcc
	v_add_co_u32_e32 v106, vcc, s2, v122
	s_mov_b32 s2, 0x252000
	s_nop 0
	v_addc_co_u32_e32 v107, vcc, 0, v123, vcc
	v_add_co_u32_e32 v108, vcc, s2, v122
	s_mov_b32 s2, 0x268000
	s_nop 0
	v_addc_co_u32_e32 v109, vcc, 0, v123, vcc
	v_add_co_u32_e32 v114, vcc, s2, v122
	global_load_dwordx4 v[2:5], v[122:123], off
	global_load_dwordx4 v[6:9], v[6:7], off
	v_addc_co_u32_e32 v115, vcc, 0, v123, vcc
	v_add_co_u32_e32 v116, vcc, 0x27e000, v122
	global_load_dwordx4 v[14:17], v[10:11], off
	global_load_dwordx4 v[10:13], v[12:13], off
	v_addc_co_u32_e32 v117, vcc, 0, v123, vcc
	v_add_co_u32_e32 v124, vcc, 0x294000, v122
	global_load_dwordx4 v[22:25], v[18:19], off
	global_load_dwordx4 v[18:21], v[20:21], off
	v_addc_co_u32_e32 v125, vcc, 0, v123, vcc
	v_add_co_u32_e32 v122, vcc, 0x2aa000, v122
	global_load_dwordx4 v[30:33], v[26:27], off
	global_load_dwordx4 v[26:29], v[28:29], off
	v_addc_co_u32_e32 v123, vcc, 0, v123, vcc
	global_load_dwordx4 v[38:41], v[34:35], off
	global_load_dwordx4 v[34:37], v[36:37], off
	global_load_dwordx4 v[46:49], v[42:43], off
	global_load_dwordx4 v[42:45], v[44:45], off
	global_load_dwordx4 v[54:57], v[50:51], off
	global_load_dwordx4 v[50:53], v[52:53], off
	global_load_dwordx4 v[62:65], v[58:59], off
	global_load_dwordx4 v[58:61], v[60:61], off
	global_load_dwordx4 v[70:73], v[66:67], off
	global_load_dwordx4 v[66:69], v[68:69], off
	global_load_dwordx4 v[78:81], v[74:75], off
	global_load_dwordx4 v[74:77], v[76:77], off
	global_load_dwordx4 v[86:89], v[82:83], off
	global_load_dwordx4 v[82:85], v[84:85], off
	global_load_dwordx4 v[94:97], v[90:91], off
	global_load_dwordx4 v[90:93], v[92:93], off
	global_load_dwordx4 v[102:105], v[98:99], off
	global_load_dwordx4 v[98:101], v[100:101], off
	global_load_dwordx4 v[110:113], v[106:107], off
	global_load_dwordx4 v[106:109], v[108:109], off
	global_load_dwordx4 v[118:121], v[114:115], off
	global_load_dwordx4 v[114:117], v[116:117], off
	global_load_dwordx4 v[126:129], v[124:125], off
	global_load_dwordx4 v[122:125], v[122:123], off
	s_and_saveexec_b64 s[2:3], s[44:45]
	s_cbranch_execz .LBB0_522
; #define LAS __attribute__((address_space(3)))
; __device__ __forceinline__ void transpose_item(const float* W, int K, int N, bf16* WT, LAS float* scr, int item, int nblk, int lane, int mode, const float* W2) {
;     ...
; #pragma unroll
;     for (int pass = 0; pass < 2; ++pass) {
;         if ((c32 >> 4) == pass) {
;             const int cc = 4 * (c32 & 15);
; #pragma unroll
;             for (int i = 0; i < 32; ++i) { LAS float* d = scr + (2 * i + (lane >> 5)) * 65 + cc; d[0] = vals[i].x; d[1] = vals[i].y; d[2] = vals[i].z; d[3] = vals[i].w; }
;         }
	v_add_u32_e32 v0, 0x410, v147
	s_waitcnt vmcnt(0)
	ds_write2_b32 v147, v2, v3 offset1:1
	ds_write2_b32 v147, v4, v5 offset0:2 offset1:3
	ds_write2_b32 v147, v6, v7 offset0:130 offset1:131
	ds_write2_b32 v147, v8, v9 offset0:132 offset1:133
	ds_write2_b32 v0, v14, v15 offset1:1
	v_add_u32_e32 v0, 0x418, v147
	ds_write2_b32 v0, v16, v17 offset1:1
	v_add_u32_e32 v0, 0x618, v147
	ds_write2_b32 v0, v10, v11 offset1:1
	v_add_u32_e32 v0, 0x620, v147
	ds_write2_b32 v0, v12, v13 offset1:1
	v_add_u32_e32 v0, 0x820, v147
	ds_write2_b32 v0, v22, v23 offset1:1
	v_add_u32_e32 v0, 0x828, v147
	ds_write2_b32 v0, v24, v25 offset1:1
	v_add_u32_e32 v0, 0xa28, v147
	ds_write2_b32 v0, v18, v19 offset1:1
	v_add_u32_e32 v0, 0xa30, v147
	ds_write2_b32 v0, v20, v21 offset1:1
	v_add_u32_e32 v0, 0xc30, v147
	ds_write2_b32 v0, v30, v31 offset1:1
	v_add_u32_e32 v0, 0xc38, v147
	ds_write2_b32 v0, v32, v33 offset1:1
	v_add_u32_e32 v0, 0xe38, v147
	ds_write2_b32 v0, v26, v27 offset1:1
	v_add_u32_e32 v0, 0xe40, v147
	ds_write2_b32 v0, v28, v29 offset1:1
	v_add_u32_e32 v0, 0x1040, v147
	ds_write2_b32 v0, v38, v39 offset1:1
	v_add_u32_e32 v0, 0x1048, v147
	ds_write2_b32 v0, v40, v41 offset1:1
	v_add_u32_e32 v0, 0x1248, v147
	ds_write2_b32 v0, v34, v35 offset1:1
	v_add_u32_e32 v0, 0x1250, v147
	ds_write2_b32 v0, v36, v37 offset1:1
	v_add_u32_e32 v0, 0x1450, v147
	ds_write2_b32 v0, v46, v47 offset1:1
	v_add_u32_e32 v0, 0x1458, v147
	ds_write2_b32 v0, v48, v49 offset1:1
	v_add_u32_e32 v0, 0x1658, v147
	ds_write2_b32 v0, v42, v43 offset1:1
	v_add_u32_e32 v0, 0x1660, v147
	ds_write2_b32 v0, v44, v45 offset1:1
	v_add_u32_e32 v0, 0x1860, v147
	ds_write2_b32 v0, v54, v55 offset1:1
	v_add_u32_e32 v0, 0x1868, v147
	ds_write2_b32 v0, v56, v57 offset1:1
	v_add_u32_e32 v0, 0x1a68, v147
	ds_write2_b32 v0, v50, v51 offset1:1
	v_add_u32_e32 v0, 0x1a70, v147
	ds_write2_b32 v0, v52, v53 offset1:1
	v_add_u32_e32 v0, 0x1c70, v147
	ds_write2_b32 v0, v62, v63 offset1:1
	v_add_u32_e32 v0, 0x1c78, v147
	ds_write2_b32 v0, v64, v65 offset1:1
	v_add_u32_e32 v0, 0x1e78, v147
	ds_write2_b32 v0, v58, v59 offset1:1
	v_add_u32_e32 v0, 0x1e80, v147
	ds_write2_b32 v0, v60, v61 offset1:1
	v_add_u32_e32 v0, 0x2080, v147
	ds_write2_b32 v0, v70, v71 offset1:1
	v_add_u32_e32 v0, 0x2088, v147
	ds_write2_b32 v0, v72, v73 offset1:1
	v_add_u32_e32 v0, 0x2288, v147
	ds_write2_b32 v0, v66, v67 offset1:1
	v_add_u32_e32 v0, 0x2290, v147
	ds_write2_b32 v0, v68, v69 offset1:1
	v_add_u32_e32 v0, 0x2490, v147
	ds_write2_b32 v0, v78, v79 offset1:1
	v_add_u32_e32 v0, 0x2498, v147
	ds_write2_b32 v0, v80, v81 offset1:1
	v_add_u32_e32 v0, 0x2698, v147
	ds_write2_b32 v0, v74, v75 offset1:1
	v_add_u32_e32 v0, 0x26a0, v147
	ds_write2_b32 v0, v76, v77 offset1:1
	v_add_u32_e32 v0, 0x28a0, v147
	ds_write2_b32 v0, v86, v87 offset1:1
	v_add_u32_e32 v0, 0x28a8, v147
	ds_write2_b32 v0, v88, v89 offset1:1
	v_add_u32_e32 v0, 0x2aa8, v147
	ds_write2_b32 v0, v82, v83 offset1:1
	v_add_u32_e32 v0, 0x2ab0, v147
	ds_write2_b32 v0, v84, v85 offset1:1
	v_add_u32_e32 v0, 0x2cb0, v147
	ds_write2_b32 v0, v94, v95 offset1:1
	v_add_u32_e32 v0, 0x2cb8, v147
	ds_write2_b32 v0, v96, v97 offset1:1
	v_add_u32_e32 v0, 0x2eb8, v147
	ds_write2_b32 v0, v90, v91 offset1:1
	v_add_u32_e32 v0, 0x2ec0, v147
	ds_write2_b32 v0, v92, v93 offset1:1
	v_add_u32_e32 v0, 0x30c0, v147
	ds_write2_b32 v0, v102, v103 offset1:1
	v_add_u32_e32 v0, 0x30c8, v147
	ds_write2_b32 v0, v104, v105 offset1:1
	v_add_u32_e32 v0, 0x32c8, v147
	ds_write2_b32 v0, v98, v99 offset1:1
	v_add_u32_e32 v0, 0x32d0, v147
	ds_write2_b32 v0, v100, v101 offset1:1
	v_add_u32_e32 v0, 0x34d0, v147
	ds_write2_b32 v0, v110, v111 offset1:1
	v_add_u32_e32 v0, 0x34d8, v147
	ds_write2_b32 v0, v112, v113 offset1:1
	v_add_u32_e32 v0, 0x36d8, v147
	ds_write2_b32 v0, v106, v107 offset1:1
	v_add_u32_e32 v0, 0x36e0, v147
	ds_write2_b32 v0, v108, v109 offset1:1
	v_add_u32_e32 v0, 0x38e0, v147
	ds_write2_b32 v0, v118, v119 offset1:1
	v_add_u32_e32 v0, 0x38e8, v147
	ds_write2_b32 v0, v120, v121 offset1:1
	v_add_u32_e32 v0, 0x3ae8, v147
	ds_write2_b32 v0, v114, v115 offset1:1
	v_add_u32_e32 v0, 0x3af0, v147
	ds_write2_b32 v0, v116, v117 offset1:1
	v_add_u32_e32 v0, 0x3cf0, v147
	ds_write2_b32 v0, v126, v127 offset1:1
	v_add_u32_e32 v0, 0x3cf8, v147
	ds_write2_b32 v0, v128, v129 offset1:1
	v_add_u32_e32 v0, 0x3ef8, v147
	ds_write2_b32 v0, v122, v123 offset1:1
	v_add_u32_e32 v0, 0x3f00, v147
	ds_write2_b32 v0, v124, v125 offset1:1

; #define LAS __attribute__((address_space(3)))
; __device__ __forceinline__ void transpose_item(const float* W, int K, int N, bf16* WT, LAS float* scr, int item, int nblk, int lane, int mode, const float* W2) {
;     const int kb = item / nblk, nb = item % nblk, k0 = 64 * kb, n0 = 128 * nb;
;     const int c32 = lane & 31, nn = n0 + 4 * c32;
;     const int sc = src_col(mode, nn);
;     f32x4 vals[32];
;     {
;         const bool useW = sc >= 0, use2 = (sc == -2) && (W2 != nullptr);
;         const float* pl = useW ? W + (size_t)(k0 + (lane >> 5)) * N + sc : (use2 ? W2 + (size_t)(k0 + (lane >> 5)) * 32 + (nn - 1792) : W);
;         const size_t step = useW ? (size_t)2 * N : (use2 ? 64 : 0);
; #pragma unroll
;         for (int i = 0; i < 32; ++i) { f32x4 v = *(const f32x4*)pl; pl += step; if (!(useW || use2)) v = (f32x4){0.f, 0.f, 0.f, 0.f}; vals[i] = v; }
;     }
; __device__ __forceinline__ void prep_phase(const Args& c, int l, LAS unsigned char* lds, int vcu, int G) {
;     ...
;     for (int it = gw; it < I_IN + I_OUT + I_FI + I_FO; it += NGW) {
;         int r = it;
;         if (r < I_IN) { transpose_item(w_in, D, NINW, ((bf16*)(wsl + WS_WIN)), scr, r, PW / 128, lane, 1, w_vres); continue; } r -= I_IN;
;         if (r < I_OUT) { transpose_item(w_out, D, D, ((bf16*)(wsl + WS_WOUT)), scr, r, D / 128, lane, 0, nullptr); continue; } r -= I_OUT;
;         if (r < I_FI) { transpose_item(w_fi, D, 2 * FF, ((bf16*)(wsl + WS_WFI)), scr, r, 2 * FF / 128, lane, 2, nullptr); continue; } r -= I_FI;
;         transpose_item(w_fo, FF, D, ((bf16*)(wsl + WS_WFO)), scr, r, D / 128, lane, 0, nullptr);
.LBB0_526:
	s_add_i32 s0, s20, 0x3400
	s_and_b32 s1, s0, 0x3ffc0
	s_add_i32 s0, s18, 0xf80
	s_and_b32 s0, s0, 0x780
	v_or_b32_e32 v0, s1, v144
	v_or_b32_e32 v4, s0, v135
	v_lshlrev_b32_e32 v0, 13, v0
	v_lshl_add_u64 v[2:3], s[30:31], 0, v[0:1]
	v_lshlrev_b32_e32 v0, 2, v4
	v_lshl_add_u64 v[122:123], v[2:3], 0, v[0:1]
	v_add_co_u32_e32 v6, vcc, 0x4000, v122
	s_mov_b32 s2, 0x10000
	s_nop 0
	v_addc_co_u32_e32 v7, vcc, 0, v123, vcc
	v_add_co_u32_e32 v10, vcc, 0x8000, v122
	global_load_dwordx4 v[2:5], v[122:123], off
	global_load_dwordx4 v[6:9], v[6:7], off
	v_addc_co_u32_e32 v11, vcc, 0, v123, vcc
	v_add_co_u32_e32 v12, vcc, 0xc000, v122
	s_nop 1
	v_addc_co_u32_e32 v13, vcc, 0, v123, vcc
	v_add_co_u32_e32 v18, vcc, s2, v122
	s_mov_b32 s2, 0x14000
	s_nop 0
	v_addc_co_u32_e32 v19, vcc, 0, v123, vcc
	v_add_co_u32_e32 v20, vcc, s2, v122
	s_mov_b32 s2, 0x18000
	s_nop 0
	v_addc_co_u32_e32 v21, vcc, 0, v123, vcc
	v_add_co_u32_e32 v26, vcc, s2, v122
	s_mov_b32 s2, 0x1c000
	s_nop 0
	v_addc_co_u32_e32 v27, vcc, 0, v123, vcc
	v_add_co_u32_e32 v28, vcc, s2, v122
	s_mov_b32 s2, 0x20000
	s_nop 0
	v_addc_co_u32_e32 v29, vcc, 0, v123, vcc
	v_add_co_u32_e32 v34, vcc, s2, v122
	s_mov_b32 s2, 0x24000
	s_nop 0
	v_addc_co_u32_e32 v35, vcc, 0, v123, vcc
	v_add_co_u32_e32 v36, vcc, s2, v122
	s_mov_b32 s2, 0x28000
	s_nop 0
	v_addc_co_u32_e32 v37, vcc, 0, v123, vcc
	v_add_co_u32_e32 v42, vcc, s2, v122
	s_mov_b32 s2, 0x2c000
	s_nop 0
	v_addc_co_u32_e32 v43, vcc, 0, v123, vcc
	v_add_co_u32_e32 v44, vcc, s2, v122
	s_mov_b32 s2, 0x30000
	s_nop 0
	v_addc_co_u32_e32 v45, vcc, 0, v123, vcc
	v_add_co_u32_e32 v50, vcc, s2, v122
	s_mov_b32 s2, 0x34000
	s_nop 0
	v_addc_co_u32_e32 v51, vcc, 0, v123, vcc
	v_add_co_u32_e32 v52, vcc, s2, v122
	s_mov_b32 s2, 0x38000
	s_nop 0
	v_addc_co_u32_e32 v53, vcc, 0, v123, vcc
	v_add_co_u32_e32 v58, vcc, s2, v122
	s_mov_b32 s2, 0x3c000
	s_nop 0
	v_addc_co_u32_e32 v59, vcc, 0, v123, vcc
	v_add_co_u32_e32 v60, vcc, s2, v122
	s_mov_b32 s2, 0x40000
	s_nop 0
	v_addc_co_u32_e32 v61, vcc, 0, v123, vcc
	v_add_co_u32_e32 v66, vcc, s2, v122
	s_mov_b32 s2, 0x44000
	s_nop 0
	v_addc_co_u32_e32 v67, vcc, 0, v123, vcc
	v_add_co_u32_e32 v68, vcc, s2, v122
	s_mov_b32 s2, 0x48000
	s_nop 0
	v_addc_co_u32_e32 v69, vcc, 0, v123, vcc
	v_add_co_u32_e32 v74, vcc, s2, v122
	s_mov_b32 s2, 0x4c000
	s_nop 0
	v_addc_co_u32_e32 v75, vcc, 0, v123, vcc
	v_add_co_u32_e32 v76, vcc, s2, v122
	s_mov_b32 s2, 0x50000
	s_nop 0
	v_addc_co_u32_e32 v77, vcc, 0, v123, vcc
	v_add_co_u32_e32 v82, vcc, s2, v122
	s_mov_b32 s2, 0x54000
	s_nop 0
	v_addc_co_u32_e32 v83, vcc, 0, v123, vcc
	v_add_co_u32_e32 v84, vcc, s2, v122
	s_mov_b32 s2, 0x58000
	s_nop 0
	v_addc_co_u32_e32 v85, vcc, 0, v123, vcc
	v_add_co_u32_e32 v90, vcc, s2, v122
	s_mov_b32 s2, 0x5c000
	s_nop 0
	v_addc_co_u32_e32 v91, vcc, 0, v123, vcc
	v_add_co_u32_e32 v92, vcc, s2, v122
	s_mov_b32 s2, 0x60000
	s_nop 0
	v_addc_co_u32_e32 v93, vcc, 0, v123, vcc
	v_add_co_u32_e32 v98, vcc, s2, v122
	s_mov_b32 s2, 0x64000
	s_nop 0
	v_addc_co_u32_e32 v99, vcc, 0, v123, vcc
	v_add_co_u32_e32 v100, vcc, s2, v122
	s_mov_b32 s2, 0x68000
	s_nop 0
	v_addc_co_u32_e32 v101, vcc, 0, v123, vcc
	v_add_co_u32_e32 v106, vcc, s2, v122
	s_mov_b32 s2, 0x6c000
	s_nop 0
	v_addc_co_u32_e32 v107, vcc, 0, v123, vcc
	v_add_co_u32_e32 v108, vcc, s2, v122
	s_mov_b32 s2, 0x70000
	s_nop 0
	v_addc_co_u32_e32 v109, vcc, 0, v123, vcc
	v_add_co_u32_e32 v114, vcc, s2, v122
	global_load_dwordx4 v[14:17], v[10:11], off
	global_load_dwordx4 v[10:13], v[12:13], off
	v_addc_co_u32_e32 v115, vcc, 0, v123, vcc
	v_add_co_u32_e32 v116, vcc, 0x74000, v122
	global_load_dwordx4 v[22:25], v[18:19], off
	global_load_dwordx4 v[18:21], v[20:21], off
	v_addc_co_u32_e32 v117, vcc, 0, v123, vcc
	v_add_co_u32_e32 v124, vcc, 0x78000, v122
	global_load_dwordx4 v[30:33], v[26:27], off
	global_load_dwordx4 v[26:29], v[28:29], off
	v_addc_co_u32_e32 v125, vcc, 0, v123, vcc
	v_add_co_u32_e32 v122, vcc, 0x7c000, v122
	global_load_dwordx4 v[38:41], v[34:35], off
	global_load_dwordx4 v[34:37], v[36:37], off
	v_addc_co_u32_e32 v123, vcc, 0, v123, vcc
	global_load_dwordx4 v[46:49], v[42:43], off
	global_load_dwordx4 v[42:45], v[44:45], off
	global_load_dwordx4 v[54:57], v[50:51], off
	global_load_dwordx4 v[50:53], v[52:53], off
	global_load_dwordx4 v[62:65], v[58:59], off
	global_load_dwordx4 v[58:61], v[60:61], off
	global_load_dwordx4 v[70:73], v[66:67], off
	global_load_dwordx4 v[66:69], v[68:69], off
	global_load_dwordx4 v[78:81], v[74:75], off
	global_load_dwordx4 v[74:77], v[76:77], off
	global_load_dwordx4 v[86:89], v[82:83], off
	global_load_dwordx4 v[82:85], v[84:85], off
	global_load_dwordx4 v[94:97], v[90:91], off
	global_load_dwordx4 v[90:93], v[92:93], off
	global_load_dwordx4 v[102:105], v[98:99], off
	global_load_dwordx4 v[98:101], v[100:101], off
	global_load_dwordx4 v[110:113], v[106:107], off
	global_load_dwordx4 v[106:109], v[108:109], off
	global_load_dwordx4 v[118:121], v[114:115], off
	global_load_dwordx4 v[114:117], v[116:117], off
	global_load_dwordx4 v[126:129], v[124:125], off
	global_load_dwordx4 v[122:125], v[122:123], off
	s_and_saveexec_b64 s[2:3], s[44:45]
	s_cbranch_execz .LBB0_528
; #define LAS __attribute__((address_space(3)))
; __device__ __forceinline__ void transpose_item(const float* W, int K, int N, bf16* WT, LAS float* scr, int item, int nblk, int lane, int mode, const float* W2) {
;     ...
; #pragma unroll
;     for (int pass = 0; pass < 2; ++pass) {
;         if ((c32 >> 4) == pass) {
;             const int cc = 4 * (c32 & 15);
; #pragma unroll
;             for (int i = 0; i < 32; ++i) { LAS float* d = scr + (2 * i + (lane >> 5)) * 65 + cc; d[0] = vals[i].x; d[1] = vals[i].y; d[2] = vals[i].z; d[3] = vals[i].w; }
;         }
	v_add_u32_e32 v0, 0x410, v147
	s_waitcnt vmcnt(0)
	ds_write2_b32 v147, v2, v3 offset1:1
	ds_write2_b32 v147, v4, v5 offset0:2 offset1:3
	ds_write2_b32 v147, v6, v7 offset0:130 offset1:131
	ds_write2_b32 v147, v8, v9 offset0:132 offset1:133
	ds_write2_b32 v0, v14, v15 offset1:1
	v_add_u32_e32 v0, 0x418, v147
	ds_write2_b32 v0, v16, v17 offset1:1
	v_add_u32_e32 v0, 0x618, v147
	ds_write2_b32 v0, v10, v11 offset1:1
	v_add_u32_e32 v0, 0x620, v147
	ds_write2_b32 v0, v12, v13 offset1:1
	v_add_u32_e32 v0, 0x820, v147
	ds_write2_b32 v0, v22, v23 offset1:1
	v_add_u32_e32 v0, 0x828, v147
	ds_write2_b32 v0, v24, v25 offset1:1
	v_add_u32_e32 v0, 0xa28, v147
	ds_write2_b32 v0, v18, v19 offset1:1
	v_add_u32_e32 v0, 0xa30, v147
	ds_write2_b32 v0, v20, v21 offset1:1
	v_add_u32_e32 v0, 0xc30, v147
	ds_write2_b32 v0, v30, v31 offset1:1
	v_add_u32_e32 v0, 0xc38, v147
	ds_write2_b32 v0, v32, v33 offset1:1
	v_add_u32_e32 v0, 0xe38, v147
	ds_write2_b32 v0, v26, v27 offset1:1
	v_add_u32_e32 v0, 0xe40, v147
	ds_write2_b32 v0, v28, v29 offset1:1
	v_add_u32_e32 v0, 0x1040, v147
	ds_write2_b32 v0, v38, v39 offset1:1
	v_add_u32_e32 v0, 0x1048, v147
	ds_write2_b32 v0, v40, v41 offset1:1
	v_add_u32_e32 v0, 0x1248, v147
	ds_write2_b32 v0, v34, v35 offset1:1
	v_add_u32_e32 v0, 0x1250, v147
	ds_write2_b32 v0, v36, v37 offset1:1
	v_add_u32_e32 v0, 0x1450, v147
	ds_write2_b32 v0, v46, v47 offset1:1
	v_add_u32_e32 v0, 0x1458, v147
	ds_write2_b32 v0, v48, v49 offset1:1
	v_add_u32_e32 v0, 0x1658, v147
	ds_write2_b32 v0, v42, v43 offset1:1
	v_add_u32_e32 v0, 0x1660, v147
	ds_write2_b32 v0, v44, v45 offset1:1
	v_add_u32_e32 v0, 0x1860, v147
	ds_write2_b32 v0, v54, v55 offset1:1
	v_add_u32_e32 v0, 0x1868, v147
	ds_write2_b32 v0, v56, v57 offset1:1
	v_add_u32_e32 v0, 0x1a68, v147
	ds_write2_b32 v0, v50, v51 offset1:1
	v_add_u32_e32 v0, 0x1a70, v147
	ds_write2_b32 v0, v52, v53 offset1:1
	v_add_u32_e32 v0, 0x1c70, v147
	ds_write2_b32 v0, v62, v63 offset1:1
	v_add_u32_e32 v0, 0x1c78, v147
	ds_write2_b32 v0, v64, v65 offset1:1
	v_add_u32_e32 v0, 0x1e78, v147
	ds_write2_b32 v0, v58, v59 offset1:1
	v_add_u32_e32 v0, 0x1e80, v147
	ds_write2_b32 v0, v60, v61 offset1:1
	v_add_u32_e32 v0, 0x2080, v147
	ds_write2_b32 v0, v70, v71 offset1:1
	v_add_u32_e32 v0, 0x2088, v147
	ds_write2_b32 v0, v72, v73 offset1:1
	v_add_u32_e32 v0, 0x2288, v147
	ds_write2_b32 v0, v66, v67 offset1:1
	v_add_u32_e32 v0, 0x2290, v147
	ds_write2_b32 v0, v68, v69 offset1:1
	v_add_u32_e32 v0, 0x2490, v147
	ds_write2_b32 v0, v78, v79 offset1:1
	v_add_u32_e32 v0, 0x2498, v147
	ds_write2_b32 v0, v80, v81 offset1:1
	v_add_u32_e32 v0, 0x2698, v147
	ds_write2_b32 v0, v74, v75 offset1:1
	v_add_u32_e32 v0, 0x26a0, v147
	ds_write2_b32 v0, v76, v77 offset1:1
	v_add_u32_e32 v0, 0x28a0, v147
	ds_write2_b32 v0, v86, v87 offset1:1
	v_add_u32_e32 v0, 0x28a8, v147
	ds_write2_b32 v0, v88, v89 offset1:1
	v_add_u32_e32 v0, 0x2aa8, v147
	ds_write2_b32 v0, v82, v83 offset1:1
	v_add_u32_e32 v0, 0x2ab0, v147
	ds_write2_b32 v0, v84, v85 offset1:1
	v_add_u32_e32 v0, 0x2cb0, v147
	ds_write2_b32 v0, v94, v95 offset1:1
	v_add_u32_e32 v0, 0x2cb8, v147
	ds_write2_b32 v0, v96, v97 offset1:1
	v_add_u32_e32 v0, 0x2eb8, v147
	ds_write2_b32 v0, v90, v91 offset1:1
	v_add_u32_e32 v0, 0x2ec0, v147
	ds_write2_b32 v0, v92, v93 offset1:1
	v_add_u32_e32 v0, 0x30c0, v147
	ds_write2_b32 v0, v102, v103 offset1:1
	v_add_u32_e32 v0, 0x30c8, v147
	ds_write2_b32 v0, v104, v105 offset1:1
	v_add_u32_e32 v0, 0x32c8, v147
	ds_write2_b32 v0, v98, v99 offset1:1
	v_add_u32_e32 v0, 0x32d0, v147
	ds_write2_b32 v0, v100, v101 offset1:1
	v_add_u32_e32 v0, 0x34d0, v147
	ds_write2_b32 v0, v110, v111 offset1:1
	v_add_u32_e32 v0, 0x34d8, v147
	ds_write2_b32 v0, v112, v113 offset1:1
	v_add_u32_e32 v0, 0x36d8, v147
	ds_write2_b32 v0, v106, v107 offset1:1
	v_add_u32_e32 v0, 0x36e0, v147
	ds_write2_b32 v0, v108, v109 offset1:1
	v_add_u32_e32 v0, 0x38e0, v147
	ds_write2_b32 v0, v118, v119 offset1:1
	v_add_u32_e32 v0, 0x38e8, v147
	ds_write2_b32 v0, v120, v121 offset1:1
	v_add_u32_e32 v0, 0x3ae8, v147
	ds_write2_b32 v0, v114, v115 offset1:1
	v_add_u32_e32 v0, 0x3af0, v147
	ds_write2_b32 v0, v116, v117 offset1:1
	v_add_u32_e32 v0, 0x3cf0, v147
	ds_write2_b32 v0, v126, v127 offset1:1
	v_add_u32_e32 v0, 0x3cf8, v147
	ds_write2_b32 v0, v128, v129 offset1:1
	v_add_u32_e32 v0, 0x3ef8, v147
	ds_write2_b32 v0, v122, v123 offset1:1
	v_add_u32_e32 v0, 0x3f00, v147
	ds_write2_b32 v0, v124, v125 offset1:1

; __device__ __forceinline__ void norm_rows(const float* x, const float* w, bf16* H, int gw, int ngw, int lane) {
;     for (int m0 = gw; m0 < M; m0 += 4 * ngw) {
;         f32x4 v[4][8]; float s[4];
; #pragma unroll
;         for (int q = 0; q < 4; ++q) { const int m = (m0 + q * ngw < M) ? m0 + q * ngw : m0; const f32x4* xr = (const f32x4*)(x + (size_t)m * D) + lane;
; #pragma unroll
;             for (int j = 0; j < 8; ++j) v[q][j] = xr[64 * j]; }
; #pragma unroll
;         for (int q = 0; q < 4; ++q) { float a = 0.f;
; #pragma unroll
;             for (int j = 0; j < 8; ++j) a += (v[q][j].x * v[q][j].x + v[q][j].y * v[q][j].y) + (v[q][j].z * v[q][j].z + v[q][j].w * v[q][j].w);
;             s[q] = rsqrtf(wave_sum(a) * (1.f / D) + 1e-6f); }
.LBB0_572:
	global_load_dwordx4 v[114:117], v[150:151], off offset:-4096
	global_load_dwordx4 v[94:97], v[150:151], off offset:-3072
	global_load_dwordx4 v[86:89], v[150:151], off offset:-2048
	global_load_dwordx4 v[54:57], v[150:151], off
	global_load_dwordx4 v[70:73], v[150:151], off offset:-1024
	global_load_dwordx4 v[38:41], v[150:151], off offset:1024
	global_load_dwordx4 v[22:25], v[150:151], off offset:2048
	global_load_dwordx4 v[2:5], v[150:151], off offset:3072
	s_add_i32 s0, s22, s10
	s_cmpk_lt_i32 s0, 0x4000
	s_cselect_b64 s[24:25], -1, 0
	s_and_b64 s[6:7], s[24:25], exec
	s_cselect_b32 s6, s0, s10
	s_ashr_i32 s7, s6, 31
	s_lshl_b64 s[6:7], s[6:7], 13
	v_lshl_add_u64 v[6:7], v[136:137], 0, s[6:7]
	global_load_dwordx4 v[118:121], v[6:7], off
	global_load_dwordx4 v[102:105], v[6:7], off offset:1024
	global_load_dwordx4 v[82:85], v[6:7], off offset:2048
	global_load_dwordx4 v[66:69], v[6:7], off offset:3072
	s_movk_i32 s1, 0x1000
	v_add_co_u32_e32 v6, vcc, s1, v6
	s_add_i32 s12, s49, s10
	s_nop 0
	v_addc_co_u32_e32 v7, vcc, 0, v7, vcc
	global_load_dwordx4 v[50:53], v[6:7], off
	global_load_dwordx4 v[34:37], v[6:7], off offset:1024
	global_load_dwordx4 v[18:21], v[6:7], off offset:2048
	global_load_dwordx4 v[10:13], v[6:7], off offset:3072
	s_cmpk_lt_i32 s12, 0x4000
	s_cselect_b64 s[30:31], -1, 0
	s_and_b64 s[6:7], s[30:31], exec
	s_cselect_b32 s6, s12, s10
	s_ashr_i32 s7, s6, 31
	s_lshl_b64 s[6:7], s[6:7], 13
	v_lshl_add_u64 v[6:7], v[136:137], 0, s[6:7]
	global_load_dwordx4 v[110:113], v[6:7], off
	global_load_dwordx4 v[98:101], v[6:7], off offset:1024
	global_load_dwordx4 v[78:81], v[6:7], off offset:2048
	global_load_dwordx4 v[62:65], v[6:7], off offset:3072
	v_add_co_u32_e32 v6, vcc, s1, v6
	s_add_i32 s20, s50, s10
	s_nop 0
	v_addc_co_u32_e32 v7, vcc, 0, v7, vcc
	global_load_dwordx4 v[46:49], v[6:7], off
	global_load_dwordx4 v[30:33], v[6:7], off offset:1024
	global_load_dwordx4 v[14:17], v[6:7], off offset:2048
	global_load_dwordx4 v[6:9], v[6:7], off offset:3072
	s_cmpk_lt_i32 s20, 0x4000
	s_cselect_b64 s[28:29], -1, 0
	s_and_b64 s[6:7], s[28:29], exec
	s_cselect_b32 s6, s20, s10
	s_ashr_i32 s7, s6, 31
	s_lshl_b64 s[6:7], s[6:7], 13
	s_cmpk_gt_i32 s0, 0x3fff
	s_mov_b32 s0, 0x3a000000
	s_waitcnt vmcnt(0)
	v_mov_b32_e32 v28, v115
	v_mov_b32_e32 v29, v95
	v_mov_b32_e32 v44, v117
	v_mov_b32_e32 v45, v97
	v_mov_b32_e32 v26, v114
	v_mov_b32_e32 v27, v94
	v_mov_b32_e32 v42, v116
	v_mov_b32_e32 v43, v96
	v_pk_mul_f32 v[58:59], v[88:89], v[88:89]
	v_pk_mul_f32 v[60:61], v[86:87], v[86:87]
	v_pk_mul_f32 v[28:29], v[28:29], v[28:29]
	v_pk_mul_f32 v[44:45], v[44:45], v[44:45]
	v_pk_mov_b32 v[76:77], v[60:61], v[58:59] op_sel:[1,0]
	v_mov_b32_e32 v61, v59
	v_pk_fma_f32 v[26:27], v[26:27], v[26:27], v[28:29]
	v_pk_fma_f32 v[28:29], v[42:43], v[42:43], v[44:45]
	v_mul_f32_e32 v0, v71, v71
	v_mul_f32_e32 v74, v73, v73
	v_pk_add_f32 v[42:43], v[76:77], v[60:61]
	v_pk_add_f32 v[26:27], v[26:27], v[28:29]
	v_mul_f32_e32 v90, v54, v54
	v_mul_f32_e32 v91, v55, v55
	v_mul_f32_e32 v92, v56, v56
	v_mul_f32_e32 v93, v57, v57
	v_pk_fma_f32 v[58:59], v[70:71], v[70:71], v[0:1] op_sel_hi:[1,1,0]
	v_pk_fma_f32 v[74:75], v[72:73], v[72:73], v[74:75] op_sel_hi:[1,1,0]
	v_pk_add_f32 v[28:29], v[42:43], v[42:43] op_sel:[0,1] op_sel_hi:[1,0]
	v_pk_add_f32 v[26:27], v[26:27], v[26:27] op_sel:[0,1] op_sel_hi:[1,0]
	v_mov_b32_e32 v59, v92
	v_mov_b32_e32 v75, v93
	v_mov_b32_e32 v29, v91
	v_mov_b32_e32 v27, v90
	v_pk_add_f32 v[26:27], v[26:27], v[28:29]
	v_pk_add_f32 v[28:29], v[58:59], v[74:75]
	v_pk_mul_f32 v[42:43], v[38:39], v[38:39]
	v_pk_add_f32 v[26:27], v[26:27], v[28:29]
	v_pk_mul_f32 v[28:29], v[40:41], v[40:41]
	v_mul_f32_e32 v0, v2, v2
	v_pk_mov_b32 v[44:45], v[42:43], v[28:29] op_sel:[1,0]
	v_mov_b32_e32 v43, v29
	v_pk_add_f32 v[28:29], v[44:45], v[42:43]
	v_mul_f32_e32 v42, v3, v3
	v_pk_add_f32 v[26:27], v[26:27], v[26:27] op_sel:[0,1] op_sel_hi:[1,0]
	v_pk_add_f32 v[28:29], v[28:29], v[28:29] op_sel:[0,1] op_sel_hi:[1,0]
	v_mov_b32_e32 v27, v0
	v_mov_b32_e32 v29, v42
	v_mul_f32_e32 v0, v23, v23
	v_mul_f32_e32 v43, v4, v4
	v_pk_add_f32 v[26:27], v[26:27], v[28:29]
	v_pk_fma_f32 v[28:29], v[22:23], v[22:23], v[0:1] op_sel_hi:[1,1,0]
	v_mul_f32_e32 v0, v25, v25
	v_mul_f32_e32 v44, v5, v5
	v_mov_b32_e32 v29, v43
	v_pk_fma_f32 v[42:43], v[24:25], v[24:25], v[0:1] op_sel_hi:[1,1,0]
	v_mov_b32_e32 v45, v105
	v_mov_b32_e32 v43, v44
	v_pk_add_f32 v[28:29], v[28:29], v[42:43]
	v_mov_b32_e32 v42, v119
	v_mov_b32_e32 v43, v103
	v_pk_add_f32 v[26:27], v[26:27], v[28:29]
	v_mov_b32_e32 v28, v118
	v_mov_b32_e32 v29, v102
	v_pk_mul_f32 v[42:43], v[42:43], v[42:43]
	v_mov_b32_e32 v44, v121
	v_pk_fma_f32 v[28:29], v[28:29], v[28:29], v[42:43]
	v_mov_b32_e32 v42, v120
	v_mov_b32_e32 v43, v104
	v_pk_mul_f32 v[44:45], v[44:45], v[44:45]
	v_mul_f32_e32 v0, v50, v50
	v_pk_fma_f32 v[42:43], v[42:43], v[42:43], v[44:45]
	v_pk_mul_f32 v[44:45], v[82:83], v[82:83]
	v_pk_add_f32 v[28:29], v[28:29], v[42:43]
	v_pk_mul_f32 v[42:43], v[84:85], v[84:85]
	v_pk_add_f32 v[28:29], v[28:29], v[28:29] op_sel:[0,1] op_sel_hi:[1,0]
	v_pk_mov_b32 v[58:59], v[44:45], v[42:43] op_sel:[1,0]
	v_mov_b32_e32 v45, v43
	v_pk_add_f32 v[42:43], v[58:59], v[44:45]
	v_mul_f32_e32 v44, v51, v51
	v_pk_add_f32 v[42:43], v[42:43], v[42:43] op_sel:[0,1] op_sel_hi:[1,0]
	v_mov_b32_e32 v29, v0
	v_mov_b32_e32 v43, v44
	v_mul_f32_e32 v0, v67, v67
	v_mul_f32_e32 v45, v52, v52
	v_pk_add_f32 v[28:29], v[28:29], v[42:43]
	v_pk_fma_f32 v[42:43], v[66:67], v[66:67], v[0:1] op_sel_hi:[1,1,0]
	v_mul_f32_e32 v0, v69, v69
	v_mul_f32_e32 v58, v53, v53
	v_mov_b32_e32 v43, v45
	v_pk_fma_f32 v[44:45], v[68:69], v[68:69], v[0:1] op_sel_hi:[1,1,0]
; __device__ __forceinline__ void norm_rows(const float* x, const float* w, bf16* H, int gw, int ngw, int lane) {
;     ...
;         for (int q = 0; q < 4; ++q) { float a = 0.f;
; #pragma unroll
;             for (int j = 0; j < 8; ++j) a += (v[q][j].x * v[q][j].x + v[q][j].y * v[q][j].y) + (v[q][j].z * v[q][j].z + v[q][j].w * v[q][j].w);
;             s[q] = rsqrtf(wave_sum(a) * (1.f / D) + 1e-6f); }
	v_mul_f32_e32 v0, v10, v10
	v_mov_b32_e32 v45, v58
	v_pk_add_f32 v[42:43], v[42:43], v[44:45]
	v_pk_mul_f32 v[44:45], v[34:35], v[34:35]
	v_pk_add_f32 v[28:29], v[28:29], v[42:43]
	v_pk_mul_f32 v[42:43], v[36:37], v[36:37]
	v_pk_add_f32 v[28:29], v[28:29], v[28:29] op_sel:[0,1] op_sel_hi:[1,0]
	v_pk_mov_b32 v[58:59], v[44:45], v[42:43] op_sel:[1,0]
	v_mov_b32_e32 v45, v43
	v_pk_add_f32 v[42:43], v[58:59], v[44:45]
	v_mul_f32_e32 v44, v11, v11
	v_pk_add_f32 v[42:43], v[42:43], v[42:43] op_sel:[0,1] op_sel_hi:[1,0]
	v_mov_b32_e32 v29, v0
	v_mov_b32_e32 v43, v44
	v_mul_f32_e32 v0, v19, v19
	v_mul_f32_e32 v45, v12, v12
	v_pk_add_f32 v[28:29], v[28:29], v[42:43]
	v_pk_fma_f32 v[42:43], v[18:19], v[18:19], v[0:1] op_sel_hi:[1,1,0]
	v_mul_f32_e32 v0, v21, v21
	v_mul_f32_e32 v58, v13, v13
	v_mov_b32_e32 v43, v45
	v_pk_fma_f32 v[44:45], v[20:21], v[20:21], v[0:1] op_sel_hi:[1,1,0]
	v_mov_b32_e32 v156, v113
	v_mov_b32_e32 v45, v58
	v_pk_add_f32 v[42:43], v[42:43], v[44:45]
	v_mov_b32_e32 v157, v101
	v_pk_add_f32 v[28:29], v[28:29], v[42:43]
	v_mov_b32_e32 v43, v26
	v_mov_b32_e32 v42, v28
	v_mov_b32_e32 v26, v29
	v_pk_add_f32 v[26:27], v[42:43], v[26:27]
	v_lshl_add_u64 v[42:43], v[136:137], 0, s[6:7]
	global_load_dwordx4 v[126:129], v[42:43], off
	global_load_dwordx4 v[122:125], v[42:43], off offset:1024
	global_load_dwordx4 v[106:109], v[42:43], off offset:2048
	global_load_dwordx4 v[90:93], v[42:43], off offset:3072
	ds_bpermute_b32 v29, v158, v27
	ds_bpermute_b32 v28, v158, v26
	v_add_co_u32_e32 v130, vcc, s1, v42
	v_pk_mul_f32 v[156:157], v[156:157], v[156:157]
	s_nop 0
	v_addc_co_u32_e32 v131, vcc, 0, v43, vcc
	s_waitcnt lgkmcnt(0)
	v_pk_add_f32 v[26:27], v[26:27], v[28:29]
	ds_bpermute_b32 v29, v159, v27
	ds_bpermute_b32 v28, v159, v26
	v_mul_f32_e32 v0, v46, v46
	s_waitcnt lgkmcnt(0)
	v_pk_add_f32 v[26:27], v[26:27], v[28:29]
	ds_bpermute_b32 v29, v160, v27
	ds_bpermute_b32 v28, v160, v26
	s_waitcnt lgkmcnt(0)
	v_pk_add_f32 v[132:133], v[26:27], v[28:29]
	global_load_dwordx4 v[74:77], v[130:131], off
	global_load_dwordx4 v[58:61], v[130:131], off offset:1024
	global_load_dwordx4 v[42:45], v[130:131], off offset:2048
	global_load_dwordx4 v[26:29], v[130:131], off offset:3072
	ds_bpermute_b32 v153, v161, v133
	ds_bpermute_b32 v152, v161, v132
	v_mov_b32_e32 v130, v110
	v_mov_b32_e32 v131, v98
	s_waitcnt lgkmcnt(0)
	v_pk_add_f32 v[152:153], v[132:133], v[152:153]
	v_mov_b32_e32 v132, v111
	v_mov_b32_e32 v133, v99
	v_pk_mul_f32 v[132:133], v[132:133], v[132:133]
	ds_bpermute_b32 v155, v162, v153
	v_pk_fma_f32 v[130:131], v[130:131], v[130:131], v[132:133]
	v_mov_b32_e32 v132, v112
	v_mov_b32_e32 v133, v100
	v_pk_fma_f32 v[132:133], v[132:133], v[132:133], v[156:157]
	v_pk_mul_f32 v[156:157], v[78:79], v[78:79]
	v_pk_add_f32 v[130:131], v[130:131], v[132:133]
	v_pk_mul_f32 v[132:133], v[80:81], v[80:81]
	v_pk_add_f32 v[130:131], v[130:131], v[130:131] op_sel:[0,1] op_sel_hi:[1,0]
	v_pk_mov_b32 v[164:165], v[156:157], v[132:133] op_sel:[1,0]
	v_mov_b32_e32 v157, v133
	v_pk_add_f32 v[132:133], v[164:165], v[156:157]
	v_mul_f32_e32 v156, v47, v47
	v_pk_add_f32 v[132:133], v[132:133], v[132:133] op_sel:[0,1] op_sel_hi:[1,0]
	v_mov_b32_e32 v131, v0
	v_mov_b32_e32 v133, v156
	v_mul_f32_e32 v0, v63, v63
	v_mul_f32_e32 v157, v48, v48
	v_pk_add_f32 v[130:131], v[130:131], v[132:133]
	v_pk_fma_f32 v[132:133], v[62:63], v[62:63], v[0:1] op_sel_hi:[1,1,0]
	v_mul_f32_e32 v0, v65, v65
	v_mul_f32_e32 v164, v49, v49
	v_mov_b32_e32 v133, v157
	v_pk_fma_f32 v[156:157], v[64:65], v[64:65], v[0:1] op_sel_hi:[1,1,0]
	v_mul_f32_e32 v0, v6, v6
	v_mov_b32_e32 v157, v164
	v_pk_add_f32 v[132:133], v[132:133], v[156:157]
	v_pk_mul_f32 v[156:157], v[30:31], v[30:31]
	v_pk_add_f32 v[130:131], v[130:131], v[132:133]
	v_pk_mul_f32 v[132:133], v[32:33], v[32:33]
	v_pk_add_f32 v[130:131], v[130:131], v[130:131] op_sel:[0,1] op_sel_hi:[1,0]
	v_pk_mov_b32 v[164:165], v[156:157], v[132:133] op_sel:[1,0]
	v_mov_b32_e32 v157, v133
	v_pk_add_f32 v[132:133], v[164:165], v[156:157]
	v_mul_f32_e32 v156, v7, v7
	v_pk_add_f32 v[132:133], v[132:133], v[132:133] op_sel:[0,1] op_sel_hi:[1,0]
	v_mov_b32_e32 v131, v0
	v_mov_b32_e32 v133, v156
	v_mul_f32_e32 v0, v15, v15
	v_mul_f32_e32 v157, v8, v8
	v_pk_add_f32 v[130:131], v[130:131], v[132:133]
	v_pk_fma_f32 v[132:133], v[14:15], v[14:15], v[0:1] op_sel_hi:[1,1,0]
	v_mul_f32_e32 v0, v17, v17
	v_mul_f32_e32 v164, v9, v9
	v_mov_b32_e32 v133, v157
	v_pk_fma_f32 v[156:157], v[16:17], v[16:17], v[0:1] op_sel_hi:[1,1,0]
	s_waitcnt vmcnt(6)
	v_mov_b32_e32 v165, v125
	v_mov_b32_e32 v157, v164
	v_pk_add_f32 v[132:133], v[132:133], v[156:157]
	v_mov_b32_e32 v164, v129
	v_pk_add_f32 v[156:157], v[130:131], v[132:133]
	v_mov_b32_e32 v132, v127
	v_mov_b32_e32 v133, v123
	v_mov_b32_e32 v130, v126
	v_mov_b32_e32 v131, v122
	v_pk_mul_f32 v[132:133], v[132:133], v[132:133]
	v_pk_mul_f32 v[164:165], v[164:165], v[164:165]
	v_pk_fma_f32 v[130:131], v[130:131], v[130:131], v[132:133]
	v_mov_b32_e32 v132, v128
	v_mov_b32_e32 v133, v124
	v_pk_fma_f32 v[132:133], v[132:133], v[132:133], v[164:165]
	ds_bpermute_b32 v154, v162, v152
	v_pk_add_f32 v[164:165], v[130:131], v[132:133]
	s_waitcnt vmcnt(5)
; __device__ __forceinline__ unsigned pk2(float lo, float hi) { f32x2_t v = {lo, hi}; bf16x2_t b = __builtin_convertvector(v, bf16x2_t); return __builtin_bit_cast(unsigned, b); }
; __device__ __forceinline__ void norm_rows(const float* x, const float* w, bf16* H, int gw, int ngw, int lane) {
;     ...
;         for (int q = 0; q < 4; ++q) { float a = 0.f;
; #pragma unroll
;             for (int j = 0; j < 8; ++j) a += (v[q][j].x * v[q][j].x + v[q][j].y * v[q][j].y) + (v[q][j].z * v[q][j].z + v[q][j].w * v[q][j].w);
;             s[q] = rsqrtf(wave_sum(a) * (1.f / D) + 1e-6f); }
; #pragma unroll
;         for (int j = 0; j < 8; ++j) { const f32x4 ww = ((const f32x4*)w)[lane + 64 * j];
; #pragma unroll
;             for (int q = 0; q < 4; ++q) { const int m = m0 + q * ngw;
;                 if (m < M) { u32x2v o; o.x = pk2(v[q][j].x * s[q] * ww.x, v[q][j].y * s[q] * ww.y); o.y = pk2(v[q][j].z * s[q] * ww.z, v[q][j].w * s[q] * ww.w); ((u32x2v*)(H + (size_t)m * D) + lane)[64 * j] = o; } } }
	v_pk_mul_f32 v[130:131], v[108:109], v[108:109]
	v_pk_mul_f32 v[132:133], v[106:107], v[106:107]
	v_pk_add_f32 v[164:165], v[164:165], v[164:165] op_sel:[0,1] op_sel_hi:[1,0]
	v_pk_mov_b32 v[166:167], v[132:133], v[130:131] op_sel:[1,0]
	v_mov_b32_e32 v133, v131
	v_pk_add_f32 v[166:167], v[166:167], v[132:133]
	global_load_dwordx4 v[130:133], v[140:141], off
	s_waitcnt vmcnt(4)
	v_mul_f32_e32 v0, v74, v74
	v_mul_f32_e32 v168, v75, v75
	v_pk_add_f32 v[166:167], v[166:167], v[166:167] op_sel:[0,1] op_sel_hi:[1,0]
	v_mov_b32_e32 v165, v0
	v_mov_b32_e32 v167, v168
	v_mul_f32_e32 v0, v91, v91
	v_mul_f32_e32 v169, v76, v76
	v_pk_add_f32 v[164:165], v[164:165], v[166:167]
	v_pk_fma_f32 v[166:167], v[90:91], v[90:91], v[0:1] op_sel_hi:[1,1,0]
	v_mul_f32_e32 v0, v93, v93
	v_mul_f32_e32 v170, v77, v77
	v_mov_b32_e32 v167, v169
	v_pk_fma_f32 v[168:169], v[92:93], v[92:93], v[0:1] op_sel_hi:[1,1,0]
	s_waitcnt vmcnt(1)
	v_mul_f32_e32 v0, v26, v26
	v_mov_b32_e32 v169, v170
	v_pk_add_f32 v[166:167], v[166:167], v[168:169]
	v_pk_mul_f32 v[168:169], v[58:59], v[58:59]
	v_pk_add_f32 v[164:165], v[164:165], v[166:167]
	v_pk_mul_f32 v[166:167], v[60:61], v[60:61]
	v_pk_add_f32 v[164:165], v[164:165], v[164:165] op_sel:[0,1] op_sel_hi:[1,0]
	v_pk_mov_b32 v[170:171], v[168:169], v[166:167] op_sel:[1,0]
	v_mov_b32_e32 v169, v167
	v_pk_add_f32 v[166:167], v[170:171], v[168:169]
	v_mul_f32_e32 v168, v27, v27
	v_pk_add_f32 v[166:167], v[166:167], v[166:167] op_sel:[0,1] op_sel_hi:[1,0]
	v_mov_b32_e32 v165, v0
	v_mov_b32_e32 v167, v168
	v_mul_f32_e32 v0, v43, v43
	v_mul_f32_e32 v169, v28, v28
	v_pk_add_f32 v[164:165], v[164:165], v[166:167]
	v_pk_fma_f32 v[166:167], v[42:43], v[42:43], v[0:1] op_sel_hi:[1,1,0]
	v_mul_f32_e32 v0, v45, v45
	v_mul_f32_e32 v170, v29, v29
	v_mov_b32_e32 v167, v169
	v_pk_fma_f32 v[168:169], v[44:45], v[44:45], v[0:1] op_sel_hi:[1,1,0]
	s_waitcnt lgkmcnt(0)
	v_pk_add_f32 v[152:153], v[152:153], v[154:155]
	v_mov_b32_e32 v169, v170
	v_pk_add_f32 v[166:167], v[166:167], v[168:169]
	ds_bpermute_b32 v155, v163, v153
	v_pk_add_f32 v[164:165], v[164:165], v[166:167]
	v_mov_b32_e32 v167, v156
	v_mov_b32_e32 v166, v164
	v_mov_b32_e32 v156, v165
	v_pk_add_f32 v[156:157], v[166:167], v[156:157]
	ds_bpermute_b32 v165, v158, v157
	ds_bpermute_b32 v164, v158, v156
	ds_bpermute_b32 v154, v163, v152
	s_waitcnt lgkmcnt(1)
	v_pk_add_f32 v[156:157], v[156:157], v[164:165]
	ds_bpermute_b32 v165, v159, v157
	ds_bpermute_b32 v164, v159, v156
	s_waitcnt lgkmcnt(2)
	v_pk_add_f32 v[152:153], v[152:153], v[154:155]
	s_waitcnt lgkmcnt(0)
	v_pk_add_f32 v[154:155], v[156:157], v[164:165]
	ds_bpermute_b32 v157, v160, v155
	ds_bpermute_b32 v156, v160, v154
	v_pk_fma_f32 v[152:153], v[152:153], s[0:1], v[178:179] op_sel_hi:[1,0,0]
	s_waitcnt lgkmcnt(0)
	v_pk_add_f32 v[154:155], v[154:155], v[156:157]
	ds_bpermute_b32 v157, v161, v155
	ds_bpermute_b32 v156, v161, v154
	v_mul_f32_e32 v0, 0x4b800000, v153
	v_cmp_gt_f32_e32 vcc, s33, v153
	v_cmp_gt_f32_e64 s[6:7], s33, v152
	s_waitcnt lgkmcnt(0)
	v_pk_add_f32 v[154:155], v[154:155], v[156:157]
	v_cndmask_b32_e32 v0, v153, v0, vcc
	v_rsq_f32_e32 v0, v0
	v_mul_f32_e32 v153, 0x4b800000, v152
	v_cndmask_b32_e64 v152, v152, v153, s[6:7]
	ds_bpermute_b32 v157, v162, v155
	ds_bpermute_b32 v156, v162, v154
	v_rsq_f32_e32 v153, v152
	v_mul_f32_e32 v152, 0x45800000, v0
	v_cndmask_b32_e32 v152, v0, v152, vcc
	s_waitcnt lgkmcnt(0)
	v_pk_add_f32 v[154:155], v[154:155], v[156:157]
	v_pk_mul_f32 v[114:115], v[114:115], v[152:153] op_sel_hi:[1,0]
	v_pk_mul_f32 v[116:117], v[116:117], v[152:153] op_sel_hi:[1,0]
	ds_bpermute_b32 v157, v163, v155
	ds_bpermute_b32 v156, v163, v154
	s_waitcnt vmcnt(0)
	v_pk_mul_f32 v[114:115], v[114:115], v[130:131]
	v_pk_mul_f32 v[116:117], v[116:117], v[132:133]
	v_cvt_pk_bf16_f32 v114, v114, v115
	v_cvt_pk_bf16_f32 v115, v116, v117
	v_lshl_add_u64 v[116:117], s[4:5], 0, v[134:135]
	v_add_co_u32_e32 v164, vcc, 0x6800000, v116
	v_mul_f32_e32 v0, 0x45800000, v153
	s_nop 0
	v_addc_co_u32_e32 v165, vcc, 0, v117, vcc
	v_cndmask_b32_e64 v0, v153, v0, s[6:7]
	flat_store_dwordx2 v[164:165], v[114:115]
	v_lshl_add_u64 v[114:115], s[2:3], 0, v[134:135]
	s_cbranch_scc1 .LBB0_574
	v_pk_mul_f32 v[118:119], v[118:119], v[0:1] op_sel_hi:[1,0]
	v_pk_mul_f32 v[120:121], v[120:121], v[0:1] op_sel_hi:[1,0]
	v_pk_mul_f32 v[118:119], v[118:119], v[130:131]
	v_pk_mul_f32 v[120:121], v[120:121], v[132:133]
	v_cvt_pk_bf16_f32 v118, v118, v119
	v_cvt_pk_bf16_f32 v119, v120, v121
	v_add_co_u32_e32 v120, vcc, 0x6800000, v114
	s_nop 1
	v_addc_co_u32_e32 v121, vcc, 0, v115, vcc
	flat_store_dwordx2 v[120:121], v[118:119]

; __device__ __forceinline__ void unpack8(u32x4v w, float* f) { f[0] = bflo(w.x); f[1] = bfhi(w.x); f[2] = bflo(w.y); f[3] = bfhi(w.y); f[4] = bflo(w.z); f[5] = bfhi(w.z); f[6] = bflo(w.w); f[7] = bfhi(w.w); }
; __device__ __forceinline__ void gdn_prep_unit(const Args& c, int ug, int l, LAS unsigned char* lds) {
;     ...
;     float qv[16], kv[16];
;     {
;         float xv[16];
; #pragma unroll
;         for (int sec = 0; sec < 3; ++sec) {
;             float acc[16];
; #pragma unroll
;             for (int e = 0; e < 16; ++e) acc[e] = 0.f;
; #pragma unroll
;             for (int i = 0; i < 4; ++i) {
;                 const int tin = 64 * chunk + tl - 3 + i; const bool ok = tin >= 0;
;                 const bf16* src = P + (tok0 + (ok ? tl - 3 + i : tl)) * PW + GDN_BASE + sec * 512 + h * 128 + sub * 16;
;                 const u32x4v a0 = *(const u32x4v*)src, a1 = *(const u32x4v*)(src + 8); float f[16]; unpack8(a0, f); unpack8(a1, f + 8);
;                 const f32x4* wp = (const f32x4*)(cw + i * 1536 + sec * 512 + h * 128 + sub * 16);
;                 const float okf = ok ? 1.f : 0.f;
; #pragma unroll
;                 for (int e4 = 0; e4 < 4; ++e4) { const f32x4 wv = wp[e4];
;                     acc[4 * e4] += f[4 * e4] * wv.x * okf; acc[4 * e4 + 1] += f[4 * e4 + 1] * wv.y * okf; acc[4 * e4 + 2] += f[4 * e4 + 2] * wv.z * okf; acc[4 * e4 + 3] += f[4 * e4 + 3] * wv.w * okf; }
.LBB0_624:
	v_readlane_b32 s0, v252, 57
	v_readlane_b32 s2, v252, 59
	v_readlane_b32 s3, v252, 60
	s_mov_b64 s[42:43], s[2:3]
	s_ashr_i32 s2, s17, 7
	s_ashr_i32 s3, s2, 31
	s_lshl_b64 s[4:5], s[2:3], 11
	s_and_b32 s2, s16, 0x7c0
	v_mov_b32_e32 v149, v179
	s_and_b32 s18, s17, 3
	s_or_b32 s4, s4, s2
	v_readlane_b32 s1, v252, 58
	s_mov_b32 s0, s15
	s_add_u32 s6, s42, 0xa800000
	s_addc_u32 s7, s43, 0
	s_ashr_i32 s1, s0, 31
	s_lshl_b64 s[0:1], s[0:1], 3
	v_readlane_b32 s20, v251, 0
	v_readlane_b32 s21, v251, 1
	s_add_u32 s24, s20, s0
	s_addc_u32 s25, s21, s1
	s_load_dwordx2 s[0:1], s[24:25], 0x90
	v_ashrrev_i32_e32 v114, 3, v149
	v_add_u32_e32 v50, s2, v114
	v_readlane_b32 s3, v250, 52
	v_add_u32_e32 v2, -3, v114
	v_cmp_lt_i32_e32 vcc, 2, v50
	s_waitcnt lgkmcnt(0)
	s_add_u32 s0, s0, s3
	v_readlane_b32 s3, v250, 51
	v_cndmask_b32_e32 v2, v114, v2, vcc
	s_addc_u32 s1, s1, s3
	s_lshl_b32 s2, s18, 9
	v_ashrrev_i32_e32 v3, 31, v2
	s_add_u32 s2, s0, s2
	v_lshl_add_u64 v[2:3], s[4:5], 0, v[2:3]
	v_mov_b64_e32 v[46:47], s[6:7]
	s_addc_u32 s3, s1, 0
	v_mad_u64_u32 v[4:5], s[0:1], v2, s27, v[46:47]
	v_and_b32_e32 v150, 7, v149
	v_mad_i32_i24 v5, v3, s27, v5
	s_lshl_b32 s14, s18, 8
	v_lshl_add_u64 v[2:3], v[4:5], 0, s[14:15]
	v_lshlrev_b32_e32 v116, 5, v150
	v_mov_b32_e32 v117, v1
	v_lshl_add_u64 v[86:87], v[2:3], 0, v[116:117]
	s_barrier
	flat_load_dwordx4 v[2:5], v[86:87] offset:3712
	flat_load_dwordx4 v[6:9], v[86:87] offset:3728
	v_cndmask_b32_e64 v118, 0, 1.0, vcc
	v_cmp_lt_i32_e32 vcc, 1, v50
	v_add_u32_e32 v14, -2, v114
	v_lshlrev_b32_e32 v0, 6, v150
	v_cndmask_b32_e32 v14, v114, v14, vcc
	v_ashrrev_i32_e32 v15, 31, v14
	v_lshl_add_u64 v[14:15], s[4:5], 0, v[14:15]
	v_lshl_add_u64 v[98:99], s[2:3], 0, v[0:1]
	v_mad_u64_u32 v[16:17], s[0:1], v14, s27, v[46:47]
	s_movk_i32 s6, 0x1000
	v_cndmask_b32_e64 v122, 0, 1.0, vcc
	v_mad_i32_i24 v17, v15, s27, v17
	v_add_co_u32_e32 v88, vcc, s6, v98
	v_lshl_add_u64 v[14:15], v[16:17], 0, s[14:15]
	s_mov_b64 s[0:1], 0x1800
	v_addc_co_u32_e32 v89, vcc, 0, v99, vcc
	v_lshl_add_u64 v[90:91], v[14:15], 0, v[116:117]
	v_lshl_add_u64 v[22:23], v[98:99], 0, s[0:1]
	v_cmp_lt_i32_e32 vcc, 0, v50
	v_ashrrev_i32_e32 v115, 31, v114
	s_waitcnt vmcnt(0) lgkmcnt(0)
	v_lshlrev_b32_e32 v108, 16, v2
	v_and_b32_e32 v109, 0xffff0000, v2
	v_lshlrev_b32_e32 v110, 16, v3
	v_and_b32_e32 v111, 0xffff0000, v3
	v_lshlrev_b32_e32 v128, 16, v4
	v_and_b32_e32 v129, 0xffff0000, v4
	v_lshlrev_b32_e32 v130, 16, v5
	v_and_b32_e32 v131, 0xffff0000, v5
	v_lshlrev_b32_e32 v92, 16, v6
	v_and_b32_e32 v93, 0xffff0000, v6
	v_lshlrev_b32_e32 v100, 16, v7
	v_and_b32_e32 v101, 0xffff0000, v7
	v_lshlrev_b32_e32 v104, 16, v8
	v_and_b32_e32 v105, 0xffff0000, v8
	v_lshlrev_b32_e32 v106, 16, v9
	v_and_b32_e32 v107, 0xffff0000, v9
	global_load_dwordx4 v[2:5], v0, s[2:3] offset:32
	global_load_dwordx4 v[6:9], v0, s[2:3] offset:48
	global_load_dwordx4 v[10:13], v0, s[2:3]
	global_load_dwordx4 v[58:61], v0, s[2:3] offset:16
	flat_load_dwordx4 v[34:37], v[90:91] offset:3712
	flat_load_dwordx4 v[14:17], v[90:91] offset:3728
	global_load_dwordx4 v[38:41], v[88:89], off offset:2048
	global_load_dwordx4 v[18:21], v[22:23], off offset:32
	global_load_dwordx4 v[26:29], v[22:23], off offset:48
	global_load_dwordx4 v[70:73], v[22:23], off offset:16
	v_cndmask_b32_e64 v124, 0, 1.0, vcc
	v_subbrev_co_u32_e32 v22, vcc, 0, v114, vcc
	v_ashrrev_i32_e32 v23, 31, v22
	v_lshl_add_u64 v[22:23], s[4:5], 0, v[22:23]
	v_mad_u64_u32 v[24:25], s[0:1], v22, s27, v[46:47]
	s_mov_b64 s[0:1], 0x3000
	s_nop 0
	v_lshl_add_u64 v[48:49], v[98:99], 0, s[0:1]
	s_movk_i32 s0, 0x3000
	v_add_co_u32_e32 v112, vcc, s0, v98
	v_mad_i32_i24 v25, v23, s27, v25
	s_nop 0
	v_addc_co_u32_e32 v113, vcc, 0, v99, vcc
	s_movk_i32 s0, 0x4000
	v_lshl_add_u64 v[22:23], v[24:25], 0, s[14:15]
	v_add_co_u32_e32 v96, vcc, s0, v98
	v_lshl_add_u64 v[94:95], v[22:23], 0, v[116:117]
	s_nop 0
	v_addc_co_u32_e32 v97, vcc, 0, v99, vcc
	flat_load_dwordx4 v[54:57], v[94:95] offset:3712
	flat_load_dwordx4 v[22:25], v[94:95] offset:3728
	global_load_dwordx4 v[62:65], v[96:97], off offset:-4096
	global_load_dwordx4 v[30:33], v[48:49], off offset:32
	global_load_dwordx4 v[42:45], v[48:49], off offset:48
	global_load_dwordx4 v[82:85], v[48:49], off offset:16
	v_lshl_add_u64 v[48:49], s[4:5], 0, v[114:115]
	v_mad_u64_u32 v[120:121], s[0:1], v48, s27, v[46:47]
	v_mad_i32_i24 v121, v49, s27, v121
	v_lshl_add_u64 v[46:47], v[120:121], 0, s[14:15]
	s_mov_b64 s[0:1], 0x4800
	v_lshl_add_u64 v[102:103], v[46:47], 0, v[116:117]
	v_lshl_add_u64 v[132:133], v[98:99], 0, s[0:1]
	v_cmp_lt_i32_e32 vcc, -1, v50
	flat_load_dwordx4 v[74:77], v[102:103] offset:3712
	flat_load_dwordx4 v[46:49], v[102:103] offset:3728
	global_load_dwordx4 v[78:81], v[96:97], off offset:2048
	global_load_dwordx4 v[50:53], v[132:133], off offset:32
	global_load_dwordx4 v[66:69], v[132:133], off offset:48
	global_load_dwordx4 v[132:135], v[132:133], off offset:16
	v_cndmask_b32_e64 v126, 0, 1.0, vcc
	s_mov_b64 s[4:5], 0x1280
	s_mov_b64 s[0:1], 0x2000
	s_waitcnt vmcnt(0)
	v_pk_mul_f32 v[4:5], v[4:5], v[100:101]
	v_pk_mul_f32 v[8:9], v[8:9], v[106:107]
	v_pk_mul_f32 v[12:13], v[12:13], v[110:111]
	v_pk_mul_f32 v[60:61], v[60:61], v[130:131]
	s_waitcnt lgkmcnt(0)
; __device__ __forceinline__ float sigmoidf_(float x) { return __builtin_amdgcn_rcpf(1.0f + __expf(-x)); }
; __device__ __forceinline__ void unpack8(u32x4v w, float* f) { f[0] = bflo(w.x); f[1] = bfhi(w.x); f[2] = bflo(w.y); f[3] = bfhi(w.y); f[4] = bflo(w.z); f[5] = bfhi(w.z); f[6] = bflo(w.w); f[7] = bfhi(w.w); }
; __device__ __forceinline__ void gdn_prep_unit(const Args& c, int ug, int l, LAS unsigned char* lds) {
;     ...
;             for (int i = 0; i < 4; ++i) {
;                 const int tin = 64 * chunk + tl - 3 + i; const bool ok = tin >= 0;
;                 const bf16* src = P + (tok0 + (ok ? tl - 3 + i : tl)) * PW + GDN_BASE + sec * 512 + h * 128 + sub * 16;
;                 const u32x4v a0 = *(const u32x4v*)src, a1 = *(const u32x4v*)(src + 8); float f[16]; unpack8(a0, f); unpack8(a1, f + 8);
;                 const f32x4* wp = (const f32x4*)(cw + i * 1536 + sec * 512 + h * 128 + sub * 16);
;                 const float okf = ok ? 1.f : 0.f;
; #pragma unroll
;                 for (int e4 = 0; e4 < 4; ++e4) { const f32x4 wv = wp[e4];
;                     acc[4 * e4] += f[4 * e4] * wv.x * okf; acc[4 * e4 + 1] += f[4 * e4 + 1] * wv.y * okf; acc[4 * e4 + 2] += f[4 * e4 + 2] * wv.z * okf; acc[4 * e4 + 3] += f[4 * e4 + 3] * wv.w * okf; }
;             }
; #pragma unroll
;             for (int e = 0; e < 16; ++e) acc[e] = acc[e] * sigmoidf_(acc[e]);
	v_lshlrev_b32_e32 v130, 16, v37
	v_and_b32_e32 v131, 0xffff0000, v37
	v_pk_fma_f32 v[60:61], v[118:119], v[60:61], 0 op_sel_hi:[0,1,0]
	v_pk_mul_f32 v[72:73], v[72:73], v[130:131]
	v_pk_mul_f32 v[58:59], v[58:59], v[128:129]
	v_pk_fma_f32 v[60:61], v[122:123], v[72:73], v[60:61] op_sel_hi:[0,1,1]
	v_pk_fma_f32 v[58:59], v[118:119], v[58:59], 0 op_sel_hi:[0,1,0]
	v_pk_fma_f32 v[12:13], v[118:119], v[12:13], 0 op_sel_hi:[0,1,0]
	v_pk_mul_f32 v[10:11], v[10:11], v[108:109]
	v_pk_fma_f32 v[8:9], v[118:119], v[8:9], 0 op_sel_hi:[0,1,0]
	v_pk_fma_f32 v[10:11], v[118:119], v[10:11], 0 op_sel_hi:[0,1,0]
	v_pk_mul_f32 v[6:7], v[6:7], v[104:105]
	v_pk_fma_f32 v[4:5], v[118:119], v[4:5], 0 op_sel_hi:[0,1,0]
	v_pk_fma_f32 v[6:7], v[118:119], v[6:7], 0 op_sel_hi:[0,1,0]
	v_pk_mul_f32 v[2:3], v[2:3], v[92:93]
	v_lshlrev_b32_e32 v72, 16, v57
	v_and_b32_e32 v73, 0xffff0000, v57
	v_pk_mul_f32 v[72:73], v[84:85], v[72:73]
	v_pk_fma_f32 v[2:3], v[118:119], v[2:3], 0 op_sel_hi:[0,1,0]
	v_pk_fma_f32 v[60:61], v[124:125], v[72:73], v[60:61] op_sel_hi:[0,1,1]
	v_lshlrev_b32_e32 v72, 16, v77
	v_and_b32_e32 v73, 0xffff0000, v77
	v_pk_mul_f32 v[72:73], v[134:135], v[72:73]
	s_nop 0
	v_pk_fma_f32 v[60:61], v[126:127], v[72:73], v[60:61] op_sel_hi:[0,1,1]
	v_mul_f32_e32 v37, 0xbfb8aa3b, v60
	v_exp_f32_e32 v37, v37
	s_nop 0
	v_add_f32_e32 v37, 1.0, v37
	v_rcp_f32_e32 v72, v37
	v_mul_f32_e32 v37, 0xbfb8aa3b, v61
	v_exp_f32_e32 v37, v37
	s_nop 0
	v_add_f32_e32 v37, 1.0, v37
	v_rcp_f32_e32 v73, v37
	s_nop 0
	v_pk_mul_f32 v[60:61], v[60:61], v[72:73]
	v_lshlrev_b32_e32 v72, 16, v36
	v_and_b32_e32 v73, 0xffff0000, v36
	v_pk_mul_f32 v[36:37], v[70:71], v[72:73]
	s_nop 0
	v_pk_fma_f32 v[36:37], v[122:123], v[36:37], v[58:59] op_sel_hi:[0,1,1]
	v_lshlrev_b32_e32 v58, 16, v56
	v_and_b32_e32 v59, 0xffff0000, v56
	v_pk_mul_f32 v[56:57], v[82:83], v[58:59]
	s_nop 0
	v_pk_fma_f32 v[36:37], v[124:125], v[56:57], v[36:37] op_sel_hi:[0,1,1]
	v_lshlrev_b32_e32 v56, 16, v76
	v_and_b32_e32 v57, 0xffff0000, v76
	v_pk_mul_f32 v[56:57], v[132:133], v[56:57]
	s_nop 0
	v_pk_fma_f32 v[36:37], v[126:127], v[56:57], v[36:37] op_sel_hi:[0,1,1]
	v_mul_f32_e32 v56, 0xbfb8aa3b, v36
	v_mul_f32_e32 v57, 0xbfb8aa3b, v37
	v_exp_f32_e32 v56, v56
	v_exp_f32_e32 v57, v57
	v_add_f32_e32 v56, 1.0, v56
	v_add_f32_e32 v57, 1.0, v57
	v_rcp_f32_e32 v56, v56
	v_rcp_f32_e32 v57, v57
	s_nop 0
	v_pk_mul_f32 v[36:37], v[36:37], v[56:57]
	v_lshlrev_b32_e32 v56, 16, v35
	v_and_b32_e32 v57, 0xffff0000, v35
	v_pk_mul_f32 v[40:41], v[40:41], v[56:57]
	s_nop 0
	v_pk_fma_f32 v[12:13], v[122:123], v[40:41], v[12:13] op_sel_hi:[0,1,1]
	v_lshlrev_b32_e32 v40, 16, v55
	v_and_b32_e32 v41, 0xffff0000, v55
	v_pk_mul_f32 v[40:41], v[64:65], v[40:41]
	s_nop 0
	v_pk_fma_f32 v[12:13], v[124:125], v[40:41], v[12:13] op_sel_hi:[0,1,1]
	v_lshlrev_b32_e32 v40, 16, v75
	v_and_b32_e32 v41, 0xffff0000, v75
	v_pk_mul_f32 v[40:41], v[80:81], v[40:41]
	s_nop 0
	v_pk_fma_f32 v[12:13], v[126:127], v[40:41], v[12:13] op_sel_hi:[0,1,1]
	v_mul_f32_e32 v35, 0xbfb8aa3b, v12
	v_exp_f32_e32 v35, v35
	s_nop 0
	v_add_f32_e32 v35, 1.0, v35
	v_rcp_f32_e32 v40, v35
	v_mul_f32_e32 v35, 0xbfb8aa3b, v13
	v_exp_f32_e32 v35, v35
	s_nop 0
	v_add_f32_e32 v35, 1.0, v35
	v_rcp_f32_e32 v41, v35
	s_nop 0
	v_pk_mul_f32 v[12:13], v[12:13], v[40:41]
	v_lshlrev_b32_e32 v40, 16, v34
	v_and_b32_e32 v41, 0xffff0000, v34
	v_pk_mul_f32 v[34:35], v[38:39], v[40:41]
	v_lshl_add_u64 v[40:41], v[94:95], 0, s[4:5]
	v_pk_fma_f32 v[10:11], v[122:123], v[34:35], v[10:11] op_sel_hi:[0,1,1]
	v_lshlrev_b32_e32 v34, 16, v54
	v_and_b32_e32 v35, 0xffff0000, v54
	v_pk_mul_f32 v[34:35], v[62:63], v[34:35]
	s_nop 0
	v_pk_fma_f32 v[10:11], v[124:125], v[34:35], v[10:11] op_sel_hi:[0,1,1]
	v_lshlrev_b32_e32 v34, 16, v74
	v_and_b32_e32 v35, 0xffff0000, v74
	v_pk_mul_f32 v[34:35], v[78:79], v[34:35]
	s_nop 0
	v_pk_fma_f32 v[10:11], v[126:127], v[34:35], v[10:11] op_sel_hi:[0,1,1]
	v_mul_f32_e32 v34, 0xbfb8aa3b, v10
	v_mul_f32_e32 v35, 0xbfb8aa3b, v11
	v_exp_f32_e32 v34, v34
	v_exp_f32_e32 v35, v35
	v_add_f32_e32 v34, 1.0, v34
	v_add_f32_e32 v35, 1.0, v35
	v_rcp_f32_e32 v34, v34
	v_rcp_f32_e32 v35, v35
	s_nop 0
	v_pk_mul_f32 v[10:11], v[10:11], v[34:35]
	v_lshlrev_b32_e32 v34, 16, v17
	v_and_b32_e32 v35, 0xffff0000, v17
	v_pk_mul_f32 v[28:29], v[28:29], v[34:35]
	s_nop 0
	v_pk_fma_f32 v[8:9], v[122:123], v[28:29], v[8:9] op_sel_hi:[0,1,1]
	v_lshlrev_b32_e32 v28, 16, v25
	v_and_b32_e32 v29, 0xffff0000, v25
	v_pk_mul_f32 v[28:29], v[44:45], v[28:29]
	s_nop 0
	v_pk_fma_f32 v[8:9], v[124:125], v[28:29], v[8:9] op_sel_hi:[0,1,1]
	v_lshlrev_b32_e32 v28, 16, v49
	v_and_b32_e32 v29, 0xffff0000, v49
	v_pk_mul_f32 v[28:29], v[68:69], v[28:29]
	s_nop 0
	v_pk_fma_f32 v[8:9], v[126:127], v[28:29], v[8:9] op_sel_hi:[0,1,1]
	v_mul_f32_e32 v17, 0xbfb8aa3b, v8
	v_exp_f32_e32 v17, v17
	s_nop 0
	v_add_f32_e32 v17, 1.0, v17
	v_rcp_f32_e32 v28, v17
	v_mul_f32_e32 v17, 0xbfb8aa3b, v9
	v_exp_f32_e32 v17, v17
	s_nop 0
	v_add_f32_e32 v17, 1.0, v17
	v_rcp_f32_e32 v29, v17
	s_nop 0
	v_pk_mul_f32 v[28:29], v[8:9], v[28:29]
	v_lshlrev_b32_e32 v8, 16, v16
	v_and_b32_e32 v9, 0xffff0000, v16
	v_pk_mul_f32 v[8:9], v[26:27], v[8:9]
	v_pk_mul_f32 v[34:35], v[28:29], v[28:29]
	v_pk_fma_f32 v[6:7], v[122:123], v[8:9], v[6:7] op_sel_hi:[0,1,1]
	v_lshlrev_b32_e32 v8, 16, v24
	v_and_b32_e32 v9, 0xffff0000, v24
	v_pk_mul_f32 v[8:9], v[42:43], v[8:9]
	s_nop 0
	v_pk_fma_f32 v[6:7], v[124:125], v[8:9], v[6:7] op_sel_hi:[0,1,1]
	v_lshlrev_b32_e32 v8, 16, v48
	v_and_b32_e32 v9, 0xffff0000, v48
	v_pk_mul_f32 v[8:9], v[66:67], v[8:9]
	s_nop 0
	v_pk_fma_f32 v[6:7], v[126:127], v[8:9], v[6:7] op_sel_hi:[0,1,1]
	v_mul_f32_e32 v8, 0xbfb8aa3b, v6
; __device__ __forceinline__ float sigmoidf_(float x) { return __builtin_amdgcn_rcpf(1.0f + __expf(-x)); }
; __device__ __forceinline__ void unpack8(u32x4v w, float* f) { f[0] = bflo(w.x); f[1] = bfhi(w.x); f[2] = bflo(w.y); f[3] = bfhi(w.y); f[4] = bflo(w.z); f[5] = bfhi(w.z); f[6] = bflo(w.w); f[7] = bfhi(w.w); }
; __device__ __forceinline__ void gdn_prep_unit(const Args& c, int ug, int l, LAS unsigned char* lds) {
;     ...
;             for (int i = 0; i < 4; ++i) {
;                 const int tin = 64 * chunk + tl - 3 + i; const bool ok = tin >= 0;
;                 const bf16* src = P + (tok0 + (ok ? tl - 3 + i : tl)) * PW + GDN_BASE + sec * 512 + h * 128 + sub * 16;
;                 const u32x4v a0 = *(const u32x4v*)src, a1 = *(const u32x4v*)(src + 8); float f[16]; unpack8(a0, f); unpack8(a1, f + 8);
;                 const f32x4* wp = (const f32x4*)(cw + i * 1536 + sec * 512 + h * 128 + sub * 16);
;                 const float okf = ok ? 1.f : 0.f;
; #pragma unroll
;                 for (int e4 = 0; e4 < 4; ++e4) { const f32x4 wv = wp[e4];
;                     acc[4 * e4] += f[4 * e4] * wv.x * okf; acc[4 * e4 + 1] += f[4 * e4 + 1] * wv.y * okf; acc[4 * e4 + 2] += f[4 * e4 + 2] * wv.z * okf; acc[4 * e4 + 3] += f[4 * e4 + 3] * wv.w * okf; }
;     ...
;             for (int e = 0; e < 16; ++e) acc[e] = acc[e] * sigmoidf_(acc[e]);
;             if (sec < 2) {
;                 float ss = 0.f;
; #pragma unroll
;                 for (int e = 0; e < 16; ++e) ss += acc[e] * acc[e];
;                 ss += __shfl_xor(ss, 1); ss += __shfl_xor(ss, 2); ss += __shfl_xor(ss, 4);
;                 const float rn = rsqrtf(ss + 1e-6f) * (sec == 0 ? 0.08838834764831845f : 1.0f);
; #pragma unroll
;                 for (int e = 0; e < 16; ++e) { if (sec == 0) qv[e] = acc[e] * rn; else kv[e] = acc[e] * rn; }
	v_mul_f32_e32 v9, 0xbfb8aa3b, v7
	v_exp_f32_e32 v8, v8
	v_exp_f32_e32 v9, v9
	v_add_f32_e32 v8, 1.0, v8
	v_add_f32_e32 v9, 1.0, v9
	v_rcp_f32_e32 v8, v8
	v_rcp_f32_e32 v9, v9
	s_nop 0
	v_pk_mul_f32 v[16:17], v[6:7], v[8:9]
	v_lshlrev_b32_e32 v6, 16, v15
	v_and_b32_e32 v7, 0xffff0000, v15
	v_pk_mul_f32 v[6:7], v[20:21], v[6:7]
	v_pk_mul_f32 v[24:25], v[16:17], v[16:17]
	v_pk_fma_f32 v[4:5], v[122:123], v[6:7], v[4:5] op_sel_hi:[0,1,1]
	v_lshlrev_b32_e32 v6, 16, v23
	v_and_b32_e32 v7, 0xffff0000, v23
	v_pk_mul_f32 v[6:7], v[32:33], v[6:7]
	v_lshl_add_u64 v[32:33], v[98:99], 0, s[0:1]
	v_pk_fma_f32 v[4:5], v[124:125], v[6:7], v[4:5] op_sel_hi:[0,1,1]
	v_lshlrev_b32_e32 v6, 16, v47
	v_and_b32_e32 v7, 0xffff0000, v47
	v_pk_mul_f32 v[6:7], v[52:53], v[6:7]
	s_movk_i32 s0, 0x2000
	v_pk_fma_f32 v[4:5], v[126:127], v[6:7], v[4:5] op_sel_hi:[0,1,1]
	v_mul_f32_e32 v6, 0xbfb8aa3b, v4
	v_mul_f32_e32 v7, 0xbfb8aa3b, v5
	v_exp_f32_e32 v6, v6
	v_exp_f32_e32 v7, v7
	v_add_f32_e32 v6, 1.0, v6
	v_add_f32_e32 v7, 1.0, v7
	v_rcp_f32_e32 v6, v6
	v_rcp_f32_e32 v7, v7
	s_nop 0
	v_pk_mul_f32 v[20:21], v[4:5], v[6:7]
	v_lshlrev_b32_e32 v4, 16, v14
	v_and_b32_e32 v5, 0xffff0000, v14
	v_pk_mul_f32 v[4:5], v[18:19], v[4:5]
	v_add_co_u32_e32 v18, vcc, s6, v86
	v_pk_fma_f32 v[2:3], v[122:123], v[4:5], v[2:3] op_sel_hi:[0,1,1]
	v_lshlrev_b32_e32 v4, 16, v22
	v_and_b32_e32 v5, 0xffff0000, v22
	v_pk_mul_f32 v[4:5], v[30:31], v[4:5]
	v_addc_co_u32_e32 v19, vcc, 0, v87, vcc
	v_pk_fma_f32 v[2:3], v[124:125], v[4:5], v[2:3] op_sel_hi:[0,1,1]
	v_lshlrev_b32_e32 v4, 16, v46
	v_and_b32_e32 v5, 0xffff0000, v46
	v_pk_mul_f32 v[4:5], v[50:51], v[4:5]
	v_add_co_u32_e32 v22, vcc, s6, v90
	v_pk_fma_f32 v[2:3], v[126:127], v[4:5], v[2:3] op_sel_hi:[0,1,1]
	v_mul_f32_e32 v4, 0xbfb8aa3b, v2
	v_mul_f32_e32 v5, 0xbfb8aa3b, v3
	v_exp_f32_e32 v4, v4
	v_exp_f32_e32 v5, v5
	v_lshl_add_u64 v[30:31], v[90:91], 0, s[4:5]
	v_addc_co_u32_e32 v23, vcc, 0, v91, vcc
	v_add_f32_e32 v4, 1.0, v4
	v_add_f32_e32 v5, 1.0, v5
	v_rcp_f32_e32 v4, v4
	v_rcp_f32_e32 v5, v5
	v_pk_mul_f32 v[26:27], v[20:21], v[20:21]
	v_pk_mul_f32 v[14:15], v[2:3], v[4:5]
	v_lshl_add_u64 v[2:3], v[86:87], 0, s[4:5]
	flat_load_dwordx4 v[44:47], v[18:19] offset:640
	flat_load_dwordx4 v[2:5], v[2:3] offset:16
	global_load_dwordx4 v[6:9], v0, s[2:3] offset:2080
	global_load_dwordx4 v[48:51], v0, s[2:3] offset:2064
	global_load_dwordx4 v[52:55], v0, s[2:3] offset:2048
	global_load_dwordx4 v[56:59], v0, s[2:3] offset:2096
	flat_load_dwordx4 v[62:65], v[22:23] offset:640
	flat_load_dwordx4 v[66:69], v[30:31] offset:16
	v_add_co_u32_e32 v30, vcc, s0, v98
	s_mov_b64 s[0:1], 0x3800
	s_nop 0
	v_addc_co_u32_e32 v31, vcc, 0, v99, vcc
	global_load_dwordx4 v[70:73], v[30:31], off
	global_load_dwordx4 v[74:77], v[32:33], off offset:32
	global_load_dwordx4 v[78:81], v[32:33], off offset:16
	global_load_dwordx4 v[82:85], v[32:33], off offset:48
	v_add_co_u32_e32 v32, vcc, s6, v94
	v_pk_mul_f32 v[38:39], v[14:15], v[14:15]
	s_nop 0
	v_addc_co_u32_e32 v33, vcc, 0, v95, vcc
	flat_load_dwordx4 v[104:107], v[32:33] offset:640
	flat_load_dwordx4 v[108:111], v[40:41] offset:16
	v_lshl_add_u64 v[40:41], v[98:99], 0, s[0:1]
	v_add_co_u32_e32 v42, vcc, s6, v102
	global_load_dwordx4 v[128:131], v[112:113], off offset:2048
	global_load_dwordx4 v[132:135], v[40:41], off offset:32
	global_load_dwordx4 v[136:139], v[40:41], off offset:16
	global_load_dwordx4 v[140:143], v[40:41], off offset:48
	v_lshl_add_u64 v[40:41], v[102:103], 0, s[4:5]
	v_addc_co_u32_e32 v43, vcc, 0, v103, vcc
	s_mov_b64 s[0:1], 0x5000
	flat_load_dwordx4 v[152:155], v[42:43] offset:640
	flat_load_dwordx4 v[156:159], v[40:41] offset:16
	v_lshl_add_u64 v[40:41], v[98:99], 0, s[0:1]
	s_movk_i32 s0, 0x5000
	v_add_co_u32_e32 v100, vcc, s0, v98
	s_mov_b32 s0, 0x358637bd
	s_nop 0
	v_addc_co_u32_e32 v101, vcc, 0, v99, vcc
	global_load_dwordx4 v[160:163], v[100:101], off
	global_load_dwordx4 v[164:167], v[40:41], off offset:32
	global_load_dwordx4 v[168:171], v[40:41], off offset:16
	global_load_dwordx4 v[172:175], v[40:41], off offset:48
	s_mov_b64 s[2:3], 0x1680
	s_waitcnt vmcnt(0) lgkmcnt(0)
	v_and_b32_e32 v41, 0xffff0000, v4
	v_lshlrev_b32_e32 v40, 16, v4
	v_pk_mul_f32 v[40:41], v[56:57], v[40:41]
	v_and_b32_e32 v57, 0xffff0000, v68
	v_lshlrev_b32_e32 v56, 16, v68
	v_pk_fma_f32 v[40:41], v[118:119], v[40:41], 0 op_sel_hi:[0,1,0]
	v_lshlrev_b32_e32 v68, 16, v44
	v_pk_mul_f32 v[56:57], v[82:83], v[56:57]
	s_nop 0
	v_pk_fma_f32 v[40:41], v[122:123], v[56:57], v[40:41] op_sel_hi:[0,1,1]
	v_and_b32_e32 v83, 0xffff0000, v5
	v_lshlrev_b32_e32 v82, 16, v5
	v_and_b32_e32 v57, 0xffff0000, v110
	v_lshlrev_b32_e32 v56, 16, v110
	v_pk_mul_f32 v[56:57], v[140:141], v[56:57]
	s_nop 0
	v_pk_fma_f32 v[40:41], v[124:125], v[56:57], v[40:41] op_sel_hi:[0,1,1]
	v_and_b32_e32 v57, 0xffff0000, v158
	v_lshlrev_b32_e32 v56, 16, v158
	v_pk_mul_f32 v[56:57], v[172:173], v[56:57]
	s_nop 0
	v_pk_fma_f32 v[40:41], v[126:127], v[56:57], v[40:41] op_sel_hi:[0,1,1]
	v_mul_f32_e32 v4, 0xbfb8aa3b, v40
	v_exp_f32_e32 v4, v4
	s_nop 0
	v_add_f32_e32 v4, 1.0, v4
	v_rcp_f32_e32 v56, v4
	v_mul_f32_e32 v4, 0xbfb8aa3b, v41
	v_exp_f32_e32 v4, v4
	s_nop 0
	v_add_f32_e32 v4, 1.0, v4
	v_rcp_f32_e32 v57, v4
	v_pk_mul_f32 v[4:5], v[58:59], v[82:83]
	v_and_b32_e32 v59, 0xffff0000, v69
	v_lshlrev_b32_e32 v58, 16, v69
	v_and_b32_e32 v69, 0xffff0000, v44
	v_pk_mul_f32 v[52:53], v[52:53], v[68:69]
	v_lshlrev_b32_e32 v68, 16, v62
	v_and_b32_e32 v69, 0xffff0000, v62
	v_pk_fma_f32 v[52:53], v[118:119], v[52:53], 0 op_sel_hi:[0,1,0]
	v_pk_mul_f32 v[68:69], v[70:71], v[68:69]
	v_pk_fma_f32 v[4:5], v[118:119], v[4:5], 0 op_sel_hi:[0,1,0]
; __device__ __forceinline__ float sigmoidf_(float x) { return __builtin_amdgcn_rcpf(1.0f + __expf(-x)); }
; __device__ __forceinline__ void unpack8(u32x4v w, float* f) { f[0] = bflo(w.x); f[1] = bfhi(w.x); f[2] = bflo(w.y); f[3] = bfhi(w.y); f[4] = bflo(w.z); f[5] = bfhi(w.z); f[6] = bflo(w.w); f[7] = bfhi(w.w); }
; __device__ __forceinline__ void gdn_prep_unit(const Args& c, int ug, int l, LAS unsigned char* lds) {
;     ...
;             for (int i = 0; i < 4; ++i) {
;                 const int tin = 64 * chunk + tl - 3 + i; const bool ok = tin >= 0;
;                 const bf16* src = P + (tok0 + (ok ? tl - 3 + i : tl)) * PW + GDN_BASE + sec * 512 + h * 128 + sub * 16;
;                 const u32x4v a0 = *(const u32x4v*)src, a1 = *(const u32x4v*)(src + 8); float f[16]; unpack8(a0, f); unpack8(a1, f + 8);
;                 const f32x4* wp = (const f32x4*)(cw + i * 1536 + sec * 512 + h * 128 + sub * 16);
;                 const float okf = ok ? 1.f : 0.f;
; #pragma unroll
;                 for (int e4 = 0; e4 < 4; ++e4) { const f32x4 wv = wp[e4];
;                     acc[4 * e4] += f[4 * e4] * wv.x * okf; acc[4 * e4 + 1] += f[4 * e4 + 1] * wv.y * okf; acc[4 * e4 + 2] += f[4 * e4 + 2] * wv.z * okf; acc[4 * e4 + 3] += f[4 * e4 + 3] * wv.w * okf; }
;             }
; #pragma unroll
;             for (int e = 0; e < 16; ++e) acc[e] = acc[e] * sigmoidf_(acc[e]);
	v_pk_fma_f32 v[52:53], v[122:123], v[68:69], v[52:53] op_sel_hi:[0,1,1]
	v_lshlrev_b32_e32 v68, 16, v104
	v_and_b32_e32 v69, 0xffff0000, v104
	v_pk_mul_f32 v[68:69], v[128:129], v[68:69]
	v_pk_mul_f32 v[58:59], v[84:85], v[58:59]
	v_pk_fma_f32 v[52:53], v[124:125], v[68:69], v[52:53] op_sel_hi:[0,1,1]
	v_lshlrev_b32_e32 v68, 16, v152
	v_and_b32_e32 v69, 0xffff0000, v152
	v_pk_mul_f32 v[68:69], v[160:161], v[68:69]
	v_pk_fma_f32 v[4:5], v[122:123], v[58:59], v[4:5] op_sel_hi:[0,1,1]
	v_pk_fma_f32 v[52:53], v[126:127], v[68:69], v[52:53] op_sel_hi:[0,1,1]
	v_mul_f32_e32 v44, 0xbfb8aa3b, v52
	v_exp_f32_e32 v44, v44
	v_and_b32_e32 v59, 0xffff0000, v111
	v_lshlrev_b32_e32 v58, 16, v111
	v_pk_mul_f32 v[58:59], v[142:143], v[58:59]
	v_add_f32_e32 v44, 1.0, v44
	v_rcp_f32_e32 v68, v44
	v_mul_f32_e32 v44, 0xbfb8aa3b, v53
	v_exp_f32_e32 v44, v44
	v_pk_fma_f32 v[4:5], v[124:125], v[58:59], v[4:5] op_sel_hi:[0,1,1]
	v_and_b32_e32 v59, 0xffff0000, v159
	v_lshlrev_b32_e32 v58, 16, v159
	v_add_f32_e32 v44, 1.0, v44
	v_rcp_f32_e32 v69, v44
	v_lshlrev_b32_e32 v44, 16, v45
	v_and_b32_e32 v45, 0xffff0000, v45
	v_pk_mul_f32 v[44:45], v[54:55], v[44:45]
	v_lshlrev_b32_e32 v54, 16, v63
	v_and_b32_e32 v55, 0xffff0000, v63
	v_pk_fma_f32 v[44:45], v[118:119], v[44:45], 0 op_sel_hi:[0,1,0]
	v_pk_mul_f32 v[54:55], v[72:73], v[54:55]
	v_pk_mul_f32 v[52:53], v[52:53], v[68:69]
	v_pk_fma_f32 v[44:45], v[122:123], v[54:55], v[44:45] op_sel_hi:[0,1,1]
	v_lshlrev_b32_e32 v54, 16, v105
	v_and_b32_e32 v55, 0xffff0000, v105
	v_pk_mul_f32 v[54:55], v[130:131], v[54:55]
	v_pk_mul_f32 v[58:59], v[174:175], v[58:59]
	v_pk_fma_f32 v[44:45], v[124:125], v[54:55], v[44:45] op_sel_hi:[0,1,1]
	v_lshlrev_b32_e32 v54, 16, v153
	v_and_b32_e32 v55, 0xffff0000, v153
	v_pk_mul_f32 v[54:55], v[162:163], v[54:55]
	v_mov_b32_e32 v62, v53
	v_pk_fma_f32 v[44:45], v[126:127], v[54:55], v[44:45] op_sel_hi:[0,1,1]
	v_mul_f32_e32 v54, 0xbfb8aa3b, v44
	v_mul_f32_e32 v55, 0xbfb8aa3b, v45
	v_exp_f32_e32 v54, v54
	v_exp_f32_e32 v55, v55
	v_mov_b32_e32 v63, v11
	v_pk_fma_f32 v[4:5], v[126:127], v[58:59], v[4:5] op_sel_hi:[0,1,1]
	v_add_f32_e32 v54, 1.0, v54
	v_add_f32_e32 v55, 1.0, v55
	v_rcp_f32_e32 v54, v54
	v_rcp_f32_e32 v55, v55
	v_pk_mul_f32 v[62:63], v[62:63], v[62:63]
	v_mul_f32_e32 v58, 0xbfb8aa3b, v4
	v_mul_f32_e32 v59, 0xbfb8aa3b, v5
	v_pk_mul_f32 v[44:45], v[44:45], v[54:55]
	v_lshlrev_b32_e32 v54, 16, v46
	v_and_b32_e32 v55, 0xffff0000, v46
	v_pk_mul_f32 v[48:49], v[48:49], v[54:55]
	v_lshlrev_b32_e32 v54, 16, v64
	v_and_b32_e32 v55, 0xffff0000, v64
	v_pk_fma_f32 v[48:49], v[118:119], v[48:49], 0 op_sel_hi:[0,1,0]
	v_pk_mul_f32 v[54:55], v[78:79], v[54:55]
	v_exp_f32_e32 v58, v58
	v_pk_fma_f32 v[48:49], v[122:123], v[54:55], v[48:49] op_sel_hi:[0,1,1]
	v_lshlrev_b32_e32 v54, 16, v106
	v_and_b32_e32 v55, 0xffff0000, v106
	v_pk_mul_f32 v[54:55], v[136:137], v[54:55]
	v_exp_f32_e32 v59, v59
	v_pk_fma_f32 v[48:49], v[124:125], v[54:55], v[48:49] op_sel_hi:[0,1,1]
	v_lshlrev_b32_e32 v54, 16, v154
	v_and_b32_e32 v55, 0xffff0000, v154
	v_pk_mul_f32 v[54:55], v[168:169], v[54:55]
	v_mov_b32_e32 v64, v45
	v_pk_fma_f32 v[48:49], v[126:127], v[54:55], v[48:49] op_sel_hi:[0,1,1]
	v_mul_f32_e32 v46, 0xbfb8aa3b, v48
	v_exp_f32_e32 v46, v46
	v_add_f32_e32 v58, 1.0, v58
	v_add_f32_e32 v59, 1.0, v59
	v_rcp_f32_e32 v58, v58
	v_add_f32_e32 v46, 1.0, v46
	v_rcp_f32_e32 v54, v46
	v_mul_f32_e32 v46, 0xbfb8aa3b, v49
	v_exp_f32_e32 v46, v46
	v_rcp_f32_e32 v59, v59
	v_pk_mul_f32 v[40:41], v[40:41], v[56:57]
	v_add_f32_e32 v46, 1.0, v46
	v_rcp_f32_e32 v55, v46
	v_lshlrev_b32_e32 v46, 16, v47
	v_and_b32_e32 v47, 0xffff0000, v47
	v_pk_mul_f32 v[46:47], v[50:51], v[46:47]
	v_lshlrev_b32_e32 v50, 16, v65
	v_and_b32_e32 v51, 0xffff0000, v65
	v_pk_fma_f32 v[46:47], v[118:119], v[46:47], 0 op_sel_hi:[0,1,0]
	v_pk_mul_f32 v[50:51], v[80:81], v[50:51]
	v_pk_mul_f32 v[48:49], v[48:49], v[54:55]
	v_pk_fma_f32 v[46:47], v[122:123], v[50:51], v[46:47] op_sel_hi:[0,1,1]
	v_lshlrev_b32_e32 v50, 16, v107
	v_and_b32_e32 v51, 0xffff0000, v107
	v_pk_mul_f32 v[50:51], v[138:139], v[50:51]
	v_mov_b32_e32 v54, v52
	v_pk_fma_f32 v[46:47], v[124:125], v[50:51], v[46:47] op_sel_hi:[0,1,1]
	v_lshlrev_b32_e32 v50, 16, v155
	v_and_b32_e32 v51, 0xffff0000, v155
	v_pk_mul_f32 v[50:51], v[170:171], v[50:51]
	v_mov_b32_e32 v55, v10
	v_pk_fma_f32 v[46:47], v[126:127], v[50:51], v[46:47] op_sel_hi:[0,1,1]
	v_mul_f32_e32 v50, 0xbfb8aa3b, v46
	v_mul_f32_e32 v51, 0xbfb8aa3b, v47
	v_exp_f32_e32 v50, v50
	v_exp_f32_e32 v51, v51
	v_pk_fma_f32 v[54:55], v[54:55], v[54:55], v[62:63]
	v_mov_b32_e32 v62, v44
	v_add_f32_e32 v50, 1.0, v50
	v_add_f32_e32 v51, 1.0, v51
	v_rcp_f32_e32 v50, v50
	v_rcp_f32_e32 v51, v51
	v_mov_b32_e32 v63, v12
	v_mov_b32_e32 v65, v13
	v_pk_fma_f32 v[54:55], v[62:63], v[62:63], v[54:55]
	v_pk_mul_f32 v[46:47], v[46:47], v[50:51]
	v_lshlrev_b32_e32 v50, 16, v2
	v_and_b32_e32 v51, 0xffff0000, v2
	v_pk_mul_f32 v[6:7], v[6:7], v[50:51]
	v_lshlrev_b32_e32 v50, 16, v66
	v_and_b32_e32 v51, 0xffff0000, v66
	v_pk_fma_f32 v[6:7], v[118:119], v[6:7], 0 op_sel_hi:[0,1,0]
	v_pk_mul_f32 v[50:51], v[74:75], v[50:51]
	v_pk_fma_f32 v[54:55], v[64:65], v[64:65], v[54:55]
	v_pk_fma_f32 v[6:7], v[122:123], v[50:51], v[6:7] op_sel_hi:[0,1,1]
	v_lshlrev_b32_e32 v50, 16, v108
	v_and_b32_e32 v51, 0xffff0000, v108
	v_pk_mul_f32 v[50:51], v[132:133], v[50:51]
	v_mov_b32_e32 v62, v48
	v_pk_fma_f32 v[6:7], v[124:125], v[50:51], v[6:7] op_sel_hi:[0,1,1]
	v_lshlrev_b32_e32 v50, 16, v156
	v_and_b32_e32 v51, 0xffff0000, v156
	v_pk_mul_f32 v[50:51], v[164:165], v[50:51]
	v_mov_b32_e32 v63, v36
	v_pk_fma_f32 v[6:7], v[126:127], v[50:51], v[6:7] op_sel_hi:[0,1,1]
; __device__ __forceinline__ void unpack8(u32x4v w, float* f) { f[0] = bflo(w.x); f[1] = bfhi(w.x); f[2] = bflo(w.y); f[3] = bfhi(w.y); f[4] = bflo(w.z); f[5] = bfhi(w.z); f[6] = bflo(w.w); f[7] = bfhi(w.w); }
; __device__ __forceinline__ void gdn_prep_unit(const Args& c, int ug, int l, LAS unsigned char* lds) {
;     ...
;             for (int i = 0; i < 4; ++i) {
;                 const int tin = 64 * chunk + tl - 3 + i; const bool ok = tin >= 0;
;                 const bf16* src = P + (tok0 + (ok ? tl - 3 + i : tl)) * PW + GDN_BASE + sec * 512 + h * 128 + sub * 16;
;                 const u32x4v a0 = *(const u32x4v*)src, a1 = *(const u32x4v*)(src + 8); float f[16]; unpack8(a0, f); unpack8(a1, f + 8);
;                 const f32x4* wp = (const f32x4*)(cw + i * 1536 + sec * 512 + h * 128 + sub * 16);
;                 const float okf = ok ? 1.f : 0.f;
; #pragma unroll
;                 for (int e4 = 0; e4 < 4; ++e4) { const f32x4 wv = wp[e4];
;                     acc[4 * e4] += f[4 * e4] * wv.x * okf; acc[4 * e4 + 1] += f[4 * e4 + 1] * wv.y * okf; acc[4 * e4 + 2] += f[4 * e4 + 2] * wv.z * okf; acc[4 * e4 + 3] += f[4 * e4 + 3] * wv.w * okf; }
;     ...
;                 float ss = 0.f;
; #pragma unroll
;                 for (int e = 0; e < 16; ++e) ss += acc[e] * acc[e];
;                 ss += __shfl_xor(ss, 1); ss += __shfl_xor(ss, 2); ss += __shfl_xor(ss, 4);
;                 const float rn = rsqrtf(ss + 1e-6f) * (sec == 0 ? 0.08838834764831845f : 1.0f);
; #pragma unroll
;                 for (int e = 0; e < 16; ++e) { if (sec == 0) qv[e] = acc[e] * rn; else kv[e] = acc[e] * rn; }
	v_mul_f32_e32 v2, 0xbfb8aa3b, v6
	v_exp_f32_e32 v2, v2
	v_mov_b32_e32 v64, v49
	v_mov_b32_e32 v65, v37
	v_pk_fma_f32 v[54:55], v[62:63], v[62:63], v[54:55]
	v_add_f32_e32 v2, 1.0, v2
	v_rcp_f32_e32 v50, v2
	v_mul_f32_e32 v2, 0xbfb8aa3b, v7
	v_exp_f32_e32 v2, v2
	v_pk_fma_f32 v[54:55], v[64:65], v[64:65], v[54:55]
	v_mov_b32_e32 v62, v46
	v_mov_b32_e32 v63, v60
	v_add_f32_e32 v2, 1.0, v2
	v_rcp_f32_e32 v51, v2
	v_lshlrev_b32_e32 v2, 16, v3
	v_and_b32_e32 v3, 0xffff0000, v3
	v_pk_mul_f32 v[2:3], v[8:9], v[2:3]
	v_lshlrev_b32_e32 v8, 16, v67
	v_and_b32_e32 v9, 0xffff0000, v67
	v_pk_fma_f32 v[2:3], v[118:119], v[2:3], 0 op_sel_hi:[0,1,0]
	v_pk_mul_f32 v[8:9], v[76:77], v[8:9]
	v_pk_mul_f32 v[6:7], v[6:7], v[50:51]
	v_pk_fma_f32 v[2:3], v[122:123], v[8:9], v[2:3] op_sel_hi:[0,1,1]
	v_lshlrev_b32_e32 v8, 16, v109
	v_and_b32_e32 v9, 0xffff0000, v109
	v_pk_mul_f32 v[8:9], v[134:135], v[8:9]
	v_pk_mul_f32 v[50:51], v[6:7], v[6:7]
	v_pk_fma_f32 v[2:3], v[124:125], v[8:9], v[2:3] op_sel_hi:[0,1,1]
	v_lshlrev_b32_e32 v8, 16, v157
	v_and_b32_e32 v9, 0xffff0000, v157
	v_pk_mul_f32 v[8:9], v[166:167], v[8:9]
	v_mov_b32_e32 v64, v47
	v_pk_fma_f32 v[2:3], v[126:127], v[8:9], v[2:3] op_sel_hi:[0,1,1]
	v_mul_f32_e32 v8, 0xbfb8aa3b, v2
	v_mul_f32_e32 v9, 0xbfb8aa3b, v3
	v_exp_f32_e32 v8, v8
	v_exp_f32_e32 v9, v9
	v_mov_b32_e32 v65, v61
	v_pk_fma_f32 v[54:55], v[62:63], v[62:63], v[54:55]
	v_add_f32_e32 v8, 1.0, v8
	v_add_f32_e32 v9, 1.0, v9
	v_rcp_f32_e32 v8, v8
	v_rcp_f32_e32 v9, v9
	v_pk_fma_f32 v[54:55], v[64:65], v[64:65], v[54:55]
	v_mov_b32_e32 v62, v50
	v_mov_b32_e32 v63, v38
	v_pk_mul_f32 v[2:3], v[2:3], v[8:9]
	v_pk_add_f32 v[54:55], v[62:63], v[54:55]
	v_pk_mul_f32 v[8:9], v[2:3], v[2:3]
	v_mov_b32_e32 v38, v51
	v_pk_add_f32 v[38:39], v[38:39], v[54:55]
	v_mov_b32_e32 v50, v8
	v_mov_b32_e32 v51, v26
	v_pk_mul_f32 v[56:57], v[40:41], v[40:41]
	v_pk_add_f32 v[38:39], v[50:51], v[38:39]
	v_mov_b32_e32 v26, v9
	v_pk_mul_f32 v[4:5], v[4:5], v[58:59]
	v_pk_add_f32 v[8:9], v[26:27], v[38:39]
	v_mov_b32_e32 v26, v56
	v_mov_b32_e32 v27, v24
	v_pk_mul_f32 v[58:59], v[4:5], v[4:5]
	v_pk_add_f32 v[8:9], v[26:27], v[8:9]
	v_mov_b32_e32 v24, v57
	v_pk_add_f32 v[8:9], v[24:25], v[8:9]
	v_mov_b32_e32 v24, v58
	v_mov_b32_e32 v25, v34
	v_pk_add_f32 v[8:9], v[24:25], v[8:9]
	v_mov_b32_e32 v34, v59
	v_pk_add_f32 v[8:9], v[34:35], v[8:9]
	ds_bpermute_b32 v25, v119, v9
	ds_bpermute_b32 v24, v119, v8
	s_waitcnt lgkmcnt(0)
	v_pk_add_f32 v[8:9], v[8:9], v[24:25]
	ds_bpermute_b32 v25, v123, v9
	ds_bpermute_b32 v24, v123, v8
	s_waitcnt lgkmcnt(0)
	v_pk_add_f32 v[8:9], v[8:9], v[24:25]
	ds_bpermute_b32 v25, v125, v9
	ds_bpermute_b32 v24, v125, v8
	s_waitcnt lgkmcnt(0)
	v_pk_add_f32 v[8:9], v[8:9], v[24:25]
	s_nop 0
	v_pk_add_f32 v[8:9], v[8:9], s[0:1] op_sel_hi:[1,0]
	s_mov_b64 s[0:1], 0x1000
	v_mul_f32_e32 v24, 0x4b800000, v9
	v_cmp_gt_f32_e64 s[6:7], s33, v9
	v_cmp_gt_f32_e32 vcc, s33, v8
	s_nop 0
	v_cndmask_b32_e64 v9, v9, v24, s[6:7]
	v_rsq_f32_e32 v9, v9
	s_nop 0
	v_mul_f32_e32 v24, 0x45800000, v9
	v_cndmask_b32_e64 v9, v9, v24, s[6:7]
	v_mul_f32_e32 v24, 0x3db504f3, v9
	v_mul_f32_e32 v9, 0x4b800000, v8
	v_cndmask_b32_e32 v8, v8, v9, vcc
	v_rsq_f32_e32 v8, v8
	v_pk_mul_f32 v[132:133], v[20:21], v[24:25] op_sel_hi:[1,0]
	v_pk_mul_f32 v[142:143], v[10:11], v[24:25] op_sel_hi:[1,0]
	v_pk_mul_f32 v[140:141], v[12:13], v[24:25] op_sel_hi:[1,0]
	v_mul_f32_e32 v9, 0x45800000, v8
	v_cndmask_b32_e32 v20, v8, v9, vcc
	v_pk_mul_f32 v[138:139], v[36:37], v[24:25] op_sel_hi:[1,0]
	v_pk_mul_f32 v[136:137], v[60:61], v[24:25] op_sel_hi:[1,0]
	v_pk_mul_f32 v[134:135], v[14:15], v[24:25] op_sel_hi:[1,0]
	v_pk_mul_f32 v[130:131], v[16:17], v[24:25] op_sel_hi:[1,0]
	v_pk_mul_f32 v[128:129], v[28:29], v[24:25] op_sel_hi:[1,0]
	v_pk_mul_f32 v[14:15], v[52:53], v[20:21] op_sel_hi:[1,0]
	v_pk_mul_f32 v[16:17], v[44:45], v[20:21] op_sel_hi:[1,0]
	v_pk_mul_f32 v[10:11], v[48:49], v[20:21] op_sel_hi:[1,0]
	v_pk_mul_f32 v[12:13], v[46:47], v[20:21] op_sel_hi:[1,0]
	v_pk_mul_f32 v[6:7], v[6:7], v[20:21] op_sel_hi:[1,0]
	v_pk_mul_f32 v[8:9], v[2:3], v[20:21] op_sel_hi:[1,0]
	v_pk_mul_f32 v[2:3], v[40:41], v[20:21] op_sel_hi:[1,0]
	v_pk_mul_f32 v[4:5], v[4:5], v[20:21] op_sel_hi:[1,0]
	v_lshl_add_u64 v[24:25], v[98:99], 0, s[0:1]
	v_lshl_add_u64 v[20:21], v[86:87], 0, s[2:3]
	flat_load_dwordx4 v[62:65], v[18:19] offset:1664
	flat_load_dwordx4 v[34:37], v[20:21] offset:16
	global_load_dwordx4 v[86:89], v[88:89], off
	global_load_dwordx4 v[18:21], v[24:25], off offset:48
	global_load_dwordx4 v[46:49], v[24:25], off offset:32
	global_load_dwordx4 v[66:69], v[24:25], off offset:16
	v_lshl_add_u64 v[24:25], v[90:91], 0, s[2:3]
	flat_load_dwordx4 v[58:61], v[22:23] offset:1664
	flat_load_dwordx4 v[26:29], v[24:25] offset:16
	s_mov_b64 s[0:1], 0x2800
	v_lshl_add_u64 v[38:39], v[98:99], 0, s[0:1]
	s_mov_b64 s[0:1], 0x4000
	global_load_dwordx4 v[90:93], v[30:31], off offset:2048
	global_load_dwordx4 v[22:25], v[38:39], off offset:48
	global_load_dwordx4 v[50:53], v[38:39], off offset:32
	global_load_dwordx4 v[74:77], v[38:39], off offset:16
	v_lshl_add_u64 v[30:31], v[94:95], 0, s[2:3]
	flat_load_dwordx4 v[70:73], v[32:33] offset:1664
	flat_load_dwordx4 v[38:41], v[30:31] offset:16
	v_lshl_add_u64 v[44:45], v[98:99], 0, s[0:1]
	global_load_dwordx4 v[94:97], v[96:97], off
	global_load_dwordx4 v[30:33], v[44:45], off offset:48
	global_load_dwordx4 v[54:57], v[44:45], off offset:32
	global_load_dwordx4 v[78:81], v[44:45], off offset:16
	v_lshl_add_u64 v[44:45], v[102:103], 0, s[2:3]
	flat_load_dwordx4 v[82:85], v[42:43] offset:1664
	flat_load_dwordx4 v[42:45], v[44:45] offset:16
	s_mov_b64 s[2:3], 0x5800
	v_lshl_add_u64 v[110:111], v[98:99], 0, s[2:3]
	global_load_dwordx4 v[98:101], v[100:101], off offset:2048
	global_load_dwordx4 v[102:105], v[110:111], off offset:48
	global_load_dwordx4 v[106:109], v[110:111], off offset:32
	global_load_dwordx4 v[110:113], v[110:111], off offset:16
	s_movk_i32 s1, 0x210
	v_readfirstlane_b32 s0, v149
	v_cmp_eq_u32_e32 vcc, 0, v150
	s_waitcnt vmcnt(0) lgkmcnt(0)
; __device__ __forceinline__ float sigmoidf_(float x) { return __builtin_amdgcn_rcpf(1.0f + __expf(-x)); }
; __device__ __forceinline__ void unpack8(u32x4v w, float* f) { f[0] = bflo(w.x); f[1] = bfhi(w.x); f[2] = bflo(w.y); f[3] = bfhi(w.y); f[4] = bflo(w.z); f[5] = bfhi(w.z); f[6] = bflo(w.w); f[7] = bfhi(w.w); }
; __device__ __forceinline__ void gdn_prep_unit(const Args& c, int ug, int l, LAS unsigned char* lds) {
;     ...
;             for (int i = 0; i < 4; ++i) {
;                 const int tin = 64 * chunk + tl - 3 + i; const bool ok = tin >= 0;
;                 const bf16* src = P + (tok0 + (ok ? tl - 3 + i : tl)) * PW + GDN_BASE + sec * 512 + h * 128 + sub * 16;
;                 const u32x4v a0 = *(const u32x4v*)src, a1 = *(const u32x4v*)(src + 8); float f[16]; unpack8(a0, f); unpack8(a1, f + 8);
;                 const f32x4* wp = (const f32x4*)(cw + i * 1536 + sec * 512 + h * 128 + sub * 16);
;                 const float okf = ok ? 1.f : 0.f;
; #pragma unroll
;                 for (int e4 = 0; e4 < 4; ++e4) { const f32x4 wv = wp[e4];
;                     acc[4 * e4] += f[4 * e4] * wv.x * okf; acc[4 * e4 + 1] += f[4 * e4 + 1] * wv.y * okf; acc[4 * e4 + 2] += f[4 * e4 + 2] * wv.z * okf; acc[4 * e4 + 3] += f[4 * e4 + 3] * wv.w * okf; }
;             }
; #pragma unroll
;             for (int e = 0; e < 16; ++e) acc[e] = acc[e] * sigmoidf_(acc[e]);
	v_lshlrev_b32_e32 v152, 16, v62
	v_and_b32_e32 v153, 0xffff0000, v62
	v_pk_mul_f32 v[86:87], v[86:87], v[152:153]
	v_lshlrev_b32_e32 v62, 16, v63
	v_pk_fma_f32 v[86:87], v[118:119], v[86:87], 0 op_sel_hi:[0,1,0]
	v_and_b32_e32 v63, 0xffff0000, v63
	v_lshlrev_b32_e32 v152, 16, v58
	v_and_b32_e32 v153, 0xffff0000, v58
	v_pk_mul_f32 v[90:91], v[90:91], v[152:153]
	v_pk_mul_f32 v[62:63], v[88:89], v[62:63]
	v_pk_fma_f32 v[86:87], v[122:123], v[90:91], v[86:87] op_sel_hi:[0,1,1]
	v_pk_fma_f32 v[62:63], v[118:119], v[62:63], 0 op_sel_hi:[0,1,0]
	v_lshlrev_b32_e32 v90, 16, v70
	v_and_b32_e32 v91, 0xffff0000, v70
	v_pk_mul_f32 v[90:91], v[94:95], v[90:91]
	v_lshlrev_b32_e32 v70, 16, v64
	v_pk_fma_f32 v[86:87], v[124:125], v[90:91], v[86:87] op_sel_hi:[0,1,1]
	v_lshlrev_b32_e32 v90, 16, v82
	v_and_b32_e32 v91, 0xffff0000, v82
	v_pk_mul_f32 v[90:91], v[98:99], v[90:91]
	s_nop 0
	v_pk_fma_f32 v[86:87], v[126:127], v[90:91], v[86:87] op_sel_hi:[0,1,1]
	v_mul_f32_e32 v58, 0xbfb8aa3b, v86
	v_exp_f32_e32 v58, v58
	s_nop 0
	v_add_f32_e32 v58, 1.0, v58
	v_rcp_f32_e32 v90, v58
	v_mul_f32_e32 v58, 0xbfb8aa3b, v87
	v_exp_f32_e32 v58, v58
	s_nop 0
	v_add_f32_e32 v58, 1.0, v58
	v_rcp_f32_e32 v91, v58
	v_lshlrev_b32_e32 v58, 16, v59
	v_and_b32_e32 v59, 0xffff0000, v59
	v_pk_mul_f32 v[58:59], v[92:93], v[58:59]
	s_nop 0
	v_pk_fma_f32 v[58:59], v[122:123], v[58:59], v[62:63] op_sel_hi:[0,1,1]
	v_lshlrev_b32_e32 v62, 16, v71
	v_and_b32_e32 v63, 0xffff0000, v71
	v_and_b32_e32 v71, 0xffff0000, v64
	v_lshlrev_b32_e32 v64, 16, v65
	v_and_b32_e32 v65, 0xffff0000, v65
	v_pk_mul_f32 v[64:65], v[68:69], v[64:65]
	v_lshlrev_b32_e32 v68, 16, v34
	v_and_b32_e32 v69, 0xffff0000, v34
	v_pk_mul_f32 v[46:47], v[46:47], v[68:69]
	v_lshlrev_b32_e32 v68, 16, v26
	v_and_b32_e32 v69, 0xffff0000, v26
	v_pk_fma_f32 v[46:47], v[118:119], v[46:47], 0 op_sel_hi:[0,1,0]
	v_pk_mul_f32 v[50:51], v[50:51], v[68:69]
	v_lshlrev_b32_e32 v34, 16, v35
	v_pk_fma_f32 v[46:47], v[122:123], v[50:51], v[46:47] op_sel_hi:[0,1,1]
	v_lshlrev_b32_e32 v50, 16, v38
	v_and_b32_e32 v51, 0xffff0000, v38
	v_pk_mul_f32 v[50:51], v[54:55], v[50:51]
	v_and_b32_e32 v35, 0xffff0000, v35
	v_pk_fma_f32 v[46:47], v[124:125], v[50:51], v[46:47] op_sel_hi:[0,1,1]
	v_lshlrev_b32_e32 v50, 16, v42
	v_and_b32_e32 v51, 0xffff0000, v42
	v_pk_mul_f32 v[50:51], v[106:107], v[50:51]
	v_pk_mul_f32 v[34:35], v[48:49], v[34:35]
	v_pk_fma_f32 v[46:47], v[126:127], v[50:51], v[46:47] op_sel_hi:[0,1,1]
	v_mul_f32_e32 v26, 0xbfb8aa3b, v46
	v_exp_f32_e32 v26, v26
	v_pk_fma_f32 v[34:35], v[118:119], v[34:35], 0 op_sel_hi:[0,1,0]
	v_lshlrev_b32_e32 v38, 16, v36
	v_pk_mul_f32 v[66:67], v[66:67], v[70:71]
	v_add_f32_e32 v26, 1.0, v26
	v_rcp_f32_e32 v50, v26
	v_mul_f32_e32 v26, 0xbfb8aa3b, v47
	v_exp_f32_e32 v26, v26
	v_lshlrev_b32_e32 v70, 16, v60
	v_and_b32_e32 v71, 0xffff0000, v60
	v_pk_fma_f32 v[66:67], v[118:119], v[66:67], 0 op_sel_hi:[0,1,0]
	v_add_f32_e32 v26, 1.0, v26
	v_rcp_f32_e32 v51, v26
	v_lshlrev_b32_e32 v26, 16, v27
	v_and_b32_e32 v27, 0xffff0000, v27
	v_pk_mul_f32 v[26:27], v[52:53], v[26:27]
	v_pk_mul_f32 v[70:71], v[74:75], v[70:71]
	v_pk_fma_f32 v[26:27], v[122:123], v[26:27], v[34:35] op_sel_hi:[0,1,1]
	v_lshlrev_b32_e32 v34, 16, v39
	v_and_b32_e32 v35, 0xffff0000, v39
	v_and_b32_e32 v39, 0xffff0000, v36
	v_pk_mul_f32 v[18:19], v[18:19], v[38:39]
	v_lshlrev_b32_e32 v38, 16, v28
	v_and_b32_e32 v39, 0xffff0000, v28
	v_pk_fma_f32 v[18:19], v[118:119], v[18:19], 0 op_sel_hi:[0,1,0]
	v_pk_mul_f32 v[22:23], v[22:23], v[38:39]
	v_pk_fma_f32 v[66:67], v[122:123], v[70:71], v[66:67] op_sel_hi:[0,1,1]
	v_pk_fma_f32 v[18:19], v[122:123], v[22:23], v[18:19] op_sel_hi:[0,1,1]
	v_lshlrev_b32_e32 v22, 16, v40
	v_and_b32_e32 v23, 0xffff0000, v40
	v_pk_mul_f32 v[22:23], v[30:31], v[22:23]
	v_lshlrev_b32_e32 v70, 16, v72
	v_pk_fma_f32 v[18:19], v[124:125], v[22:23], v[18:19] op_sel_hi:[0,1,1]
	v_lshlrev_b32_e32 v22, 16, v44
	v_and_b32_e32 v23, 0xffff0000, v44
	v_pk_mul_f32 v[22:23], v[102:103], v[22:23]
	v_and_b32_e32 v71, 0xffff0000, v72
	v_pk_fma_f32 v[22:23], v[126:127], v[22:23], v[18:19] op_sel_hi:[0,1,1]
	v_mul_f32_e32 v18, 0xbfb8aa3b, v22
	v_pk_mul_f32 v[70:71], v[78:79], v[70:71]
	v_exp_f32_e32 v18, v18
	v_pk_fma_f32 v[66:67], v[124:125], v[70:71], v[66:67] op_sel_hi:[0,1,1]
	v_lshlrev_b32_e32 v70, 16, v84
	v_and_b32_e32 v71, 0xffff0000, v84
	v_pk_mul_f32 v[70:71], v[110:111], v[70:71]
	v_add_f32_e32 v18, 1.0, v18
	v_pk_fma_f32 v[66:67], v[126:127], v[70:71], v[66:67] op_sel_hi:[0,1,1]
	v_mul_f32_e32 v60, 0xbfb8aa3b, v66
	v_exp_f32_e32 v60, v60
	v_rcp_f32_e32 v30, v18
	v_mul_f32_e32 v18, 0xbfb8aa3b, v23
	v_exp_f32_e32 v18, v18
	v_add_f32_e32 v60, 1.0, v60
	v_rcp_f32_e32 v70, v60
	v_mul_f32_e32 v60, 0xbfb8aa3b, v67
	v_add_f32_e32 v18, 1.0, v18
	v_exp_f32_e32 v60, v60
	v_rcp_f32_e32 v31, v18
	v_lshlrev_b32_e32 v18, 16, v37
	v_and_b32_e32 v19, 0xffff0000, v37
	v_pk_mul_f32 v[18:19], v[20:21], v[18:19]
	v_lshlrev_b32_e32 v20, 16, v29
	v_and_b32_e32 v21, 0xffff0000, v29
	v_pk_fma_f32 v[18:19], v[118:119], v[18:19], 0 op_sel_hi:[0,1,0]
	v_pk_mul_f32 v[20:21], v[24:25], v[20:21]
	v_add_f32_e32 v60, 1.0, v60
	v_pk_fma_f32 v[18:19], v[122:123], v[20:21], v[18:19] op_sel_hi:[0,1,1]
	v_lshlrev_b32_e32 v20, 16, v41
	v_and_b32_e32 v21, 0xffff0000, v41
	v_pk_mul_f32 v[20:21], v[32:33], v[20:21]
	v_rcp_f32_e32 v71, v60
	v_lshlrev_b32_e32 v60, 16, v61
	v_and_b32_e32 v61, 0xffff0000, v61
	v_pk_fma_f32 v[18:19], v[124:125], v[20:21], v[18:19] op_sel_hi:[0,1,1]
	v_lshlrev_b32_e32 v20, 16, v45
; #define LAS __attribute__((address_space(3)))
; __device__ __forceinline__ unsigned pk2(float lo, float hi) { f32x2_t v = {lo, hi}; bf16x2_t b = __builtin_convertvector(v, bf16x2_t); return __builtin_bit_cast(unsigned, b); }
; __device__ __forceinline__ float sigmoidf_(float x) { return __builtin_amdgcn_rcpf(1.0f + __expf(-x)); }
; __device__ __forceinline__ void gdn_prep_unit(const Args& c, int ug, int l, LAS unsigned char* lds) {
;     ...
;             for (int e = 0; e < 16; ++e) acc[e] = acc[e] * sigmoidf_(acc[e]);
;             if (sec < 2) {
;                 float ss = 0.f;
; #pragma unroll
;                 for (int e = 0; e < 16; ++e) ss += acc[e] * acc[e];
;                 ss += __shfl_xor(ss, 1); ss += __shfl_xor(ss, 2); ss += __shfl_xor(ss, 4);
;                 const float rn = rsqrtf(ss + 1e-6f) * (sec == 0 ? 0.08838834764831845f : 1.0f);
; #pragma unroll
;                 for (int e = 0; e < 16; ++e) { if (sec == 0) qv[e] = acc[e] * rn; else kv[e] = acc[e] * rn; }
;             } else {
; #pragma unroll
;                 for (int e = 0; e < 16; ++e) xv[e] = acc[e];
;             }
;         }
; #pragma unroll
;         for (int e = 0; e < 16; e += 4) {
;             *(LAS f32x4*)(kf + tl * 132 + sub * 16 + e) = (f32x4){kv[e], kv[e + 1], kv[e + 2], kv[e + 3]};
;             *(LAS f32x4*)(vf + tl * 132 + sub * 16 + e) = (f32x4){xv[e], xv[e + 1], xv[e + 2], xv[e + 3]};
;         }
;         u32x4v o;
;         o.x = pk2(kv[0], kv[1]); o.y = pk2(kv[2], kv[3]); o.z = pk2(kv[4], kv[5]); o.w = pk2(kv[6], kv[7]); *(LAS u32x4v*)(kb + tl * 136 + sub * 16) = o;
;         o.x = pk2(kv[8], kv[9]); o.y = pk2(kv[10], kv[11]); o.z = pk2(kv[12], kv[13]); o.w = pk2(kv[14], kv[15]); *(LAS u32x4v*)(kb + tl * 136 + sub * 16 + 8) = o;
;         o.x = pk2(qv[0], qv[1]); o.y = pk2(qv[2], qv[3]); o.z = pk2(qv[4], qv[5]); o.w = pk2(qv[6], qv[7]); *(LAS u32x4v*)(qb + tl * 136 + sub * 16) = o;
;         o.x = pk2(qv[8], qv[9]); o.y = pk2(qv[10], qv[11]); o.z = pk2(qv[12], qv[13]); o.w = pk2(qv[14], qv[15]); *(LAS u32x4v*)(qb + tl * 136 + sub * 16 + 8) = o;
;         if (sub == 0) {
;             const float a_ = bf2f(P[(tok0 + tl) * PW + GDN_BASE + 2048 + h]), b_ = bf2f(P[(tok0 + tl) * PW + GDN_BASE + 2052 + h]);
;             bet[tl] = sigmoidf_(b_);
;             gcs[tl] = -__expf(c.in[19 + z_][l * 4 + h]) * softplusf_(a_ + c.in[20 + z_][l * 4 + h]);
;         }
	v_and_b32_e32 v21, 0xffff0000, v45
	v_pk_fma_f32 v[64:65], v[118:119], v[64:65], 0 op_sel_hi:[0,1,0]
	v_pk_mul_f32 v[60:61], v[76:77], v[60:61]
	v_pk_mul_f32 v[20:21], v[104:105], v[20:21]
	v_pk_mul_f32 v[62:63], v[96:97], v[62:63]
	v_pk_fma_f32 v[60:61], v[122:123], v[60:61], v[64:65] op_sel_hi:[0,1,1]
	v_lshlrev_b32_e32 v64, 16, v73
	v_and_b32_e32 v65, 0xffff0000, v73
	v_pk_fma_f32 v[24:25], v[126:127], v[20:21], v[18:19] op_sel_hi:[0,1,1]
	v_pk_fma_f32 v[58:59], v[124:125], v[62:63], v[58:59] op_sel_hi:[0,1,1]
	v_lshlrev_b32_e32 v62, 16, v83
	v_and_b32_e32 v63, 0xffff0000, v83
	v_pk_mul_f32 v[64:65], v[80:81], v[64:65]
	v_mul_f32_e32 v18, 0xbfb8aa3b, v24
	v_pk_mul_f32 v[62:63], v[100:101], v[62:63]
	v_pk_fma_f32 v[60:61], v[124:125], v[64:65], v[60:61] op_sel_hi:[0,1,1]
	v_lshlrev_b32_e32 v64, 16, v85
	v_and_b32_e32 v65, 0xffff0000, v85
	v_pk_mul_f32 v[34:35], v[56:57], v[34:35]
	v_exp_f32_e32 v18, v18
	v_pk_fma_f32 v[58:59], v[126:127], v[62:63], v[58:59] op_sel_hi:[0,1,1]
	v_pk_mul_f32 v[64:65], v[112:113], v[64:65]
	v_pk_fma_f32 v[26:27], v[124:125], v[34:35], v[26:27] op_sel_hi:[0,1,1]
	v_lshlrev_b32_e32 v34, 16, v43
	v_and_b32_e32 v35, 0xffff0000, v43
	v_mul_f32_e32 v62, 0xbfb8aa3b, v58
	v_mul_f32_e32 v63, 0xbfb8aa3b, v59
	v_pk_fma_f32 v[60:61], v[126:127], v[64:65], v[60:61] op_sel_hi:[0,1,1]
	v_pk_mul_f32 v[34:35], v[108:109], v[34:35]
	v_exp_f32_e32 v62, v62
	v_exp_f32_e32 v63, v63
	v_mul_f32_e32 v64, 0xbfb8aa3b, v60
	v_mul_f32_e32 v65, 0xbfb8aa3b, v61
	v_pk_fma_f32 v[26:27], v[126:127], v[34:35], v[26:27] op_sel_hi:[0,1,1]
	v_exp_f32_e32 v64, v64
	v_exp_f32_e32 v65, v65
	v_mul_f32_e32 v34, 0xbfb8aa3b, v26
	v_mul_f32_e32 v35, 0xbfb8aa3b, v27
	v_add_f32_e32 v18, 1.0, v18
	v_exp_f32_e32 v34, v34
	v_exp_f32_e32 v35, v35
	v_rcp_f32_e32 v28, v18
	v_mul_f32_e32 v18, 0xbfb8aa3b, v25
	v_exp_f32_e32 v18, v18
	v_add_f32_e32 v62, 1.0, v62
	v_add_f32_e32 v63, 1.0, v63
	v_rcp_f32_e32 v62, v62
	v_rcp_f32_e32 v63, v63
	v_add_f32_e32 v64, 1.0, v64
	v_add_f32_e32 v65, 1.0, v65
	v_rcp_f32_e32 v64, v64
	v_rcp_f32_e32 v65, v65
	v_add_f32_e32 v34, 1.0, v34
	v_add_f32_e32 v35, 1.0, v35
	v_rcp_f32_e32 v34, v34
	v_rcp_f32_e32 v35, v35
	v_add_f32_e32 v18, 1.0, v18
	v_rcp_f32_e32 v29, v18
	v_mul_lo_u32 v18, v114, s1
	v_add3_u32 v0, 0, v18, v0
	v_pk_mul_f32 v[18:19], v[86:87], v[90:91]
	v_pk_mul_f32 v[20:21], v[58:59], v[62:63]
	ds_write_b128 v0, v[14:17]
	ds_write_b128 v0, v[18:21] offset:33792
	ds_write_b128 v0, v[10:13] offset:16
	v_pk_mul_f32 v[18:19], v[66:67], v[70:71]
	v_pk_mul_f32 v[20:21], v[60:61], v[64:65]
	ds_write_b128 v0, v[18:21] offset:33808
	ds_write_b128 v0, v[6:9] offset:32
	v_pk_mul_f32 v[18:19], v[46:47], v[50:51]
	v_pk_mul_f32 v[20:21], v[26:27], v[34:35]
	ds_write_b128 v0, v[18:21] offset:33824
	ds_write_b128 v0, v[2:5] offset:48
	v_pk_mul_f32 v[18:19], v[22:23], v[30:31]
	v_pk_mul_f32 v[20:21], v[24:25], v[28:29]
	s_movk_i32 s1, 0x110
	ds_write_b128 v0, v[18:21] offset:33840
	v_mul_lo_u32 v0, v114, s1
	v_readlane_b32 s1, v253, 35
	v_cvt_pk_bf16_f32 v18, v14, v15
	v_cvt_pk_bf16_f32 v19, v16, v17
	v_cvt_pk_bf16_f32 v20, v10, v11
	v_cvt_pk_bf16_f32 v21, v12, v13
	v_add3_u32 v22, s1, v0, v116
	ds_write_b128 v22, v[18:21]
	v_cvt_pk_bf16_f32 v18, v6, v7
	v_cvt_pk_bf16_f32 v19, v8, v9
	v_cvt_pk_bf16_f32 v20, v2, v3
	v_cvt_pk_bf16_f32 v21, v4, v5
	v_readlane_b32 s1, v253, 36
	ds_write_b128 v22, v[18:21] offset:16
	v_cvt_pk_bf16_f32 v18, v142, v143
	v_cvt_pk_bf16_f32 v19, v140, v141
	v_cvt_pk_bf16_f32 v20, v138, v139
	v_cvt_pk_bf16_f32 v21, v136, v137
	v_add3_u32 v0, s1, v0, v116
	ds_write_b128 v0, v[18:21]
	v_cvt_pk_bf16_f32 v18, v134, v135
	v_cvt_pk_bf16_f32 v19, v132, v133
	v_cvt_pk_bf16_f32 v20, v130, v131
	v_cvt_pk_bf16_f32 v21, v128, v129
	ds_write_b128 v0, v[18:21] offset:16
	v_lshl_add_u32 v0, v114, 2, 0
	s_and_saveexec_b64 s[2:3], vcc
	s_cbranch_execz .LBB0_626
	s_lshl_b32 s14, s18, 1
	v_lshl_add_u64 v[18:19], v[120:121], 0, s[14:15]
	v_add_co_u32_e32 v18, vcc, 0x1000, v18
	s_load_dwordx4 s[4:7], s[24:25], 0x98
	s_nop 0
	v_addc_co_u32_e32 v19, vcc, 0, v19, vcc
	flat_load_ushort v20, v[18:19] offset:3712
	v_readlane_b32 s1, v250, 53
	flat_load_ushort v18, v[18:19] offset:3720
	s_or_b32 s18, s18, s1
	s_ashr_i32 s19, s18, 31
	s_lshl_b64 s[18:19], s[18:19], 2
	s_waitcnt lgkmcnt(0)
	s_add_u32 s4, s4, s18
	v_add_u32_e32 v19, 0x14d00, v0
	s_addc_u32 s5, s5, s19
	s_waitcnt vmcnt(0)
	v_lshlrev_b32_e32 v20, 16, v20
	v_lshlrev_b32_e32 v18, 16, v18
	v_mul_f32_e32 v18, 0xbfb8aa3b, v18
	v_exp_f32_e32 v18, v18
	s_nop 0
	v_add_f32_e32 v18, 1.0, v18
	v_rcp_f32_e32 v18, v18
	ds_write_b32 v19, v18
	global_load_dword v18, v1, s[4:5]
	s_add_u32 s4, s6, s18
	s_addc_u32 s5, s7, s19
	global_load_dword v19, v1, s[4:5]
	s_waitcnt vmcnt(1)
	v_mul_f32_e32 v18, 0x3fb8aa3b, v18
	v_exp_f32_e32 v18, v18
	s_waitcnt vmcnt(0)
	v_add_f32_e32 v19, v19, v20
	v_max_f32_e32 v20, 0, v19
	v_mul_f32_e64 v19, |v19|, s29
	v_exp_f32_e32 v19, v19
	s_nop 0
	v_add_f32_e32 v19, 1.0, v19
	v_cmp_gt_f32_e32 vcc, s33, v19
	s_nop 1
	v_cndmask_b32_e64 v21, 0, 32, vcc
	v_ldexp_f32 v19, v19, v21
	v_log_f32_e32 v19, v19
	s_nop 0
	v_mul_f32_e32 v21, 0x3f317217, v19
	v_fma_f32 v21, v19, s30, -v21
	v_fmac_f32_e32 v21, 0x3377d1cf, v19
	v_fmac_f32_e32 v21, 0x3f317217, v19
	v_cmp_lt_f32_e64 s[6:7], |v19|, s28
	s_nop 1
	v_cndmask_b32_e64 v19, v19, v21, s[6:7]
	v_cndmask_b32_e32 v21, 0, v198, vcc
	v_sub_f32_e32 v19, v19, v21
	v_add_f32_e32 v19, v20, v19
	v_mul_f32_e64 v18, v19, -v18
	v_add_u32_e32 v19, 0x14c00, v0
	ds_write_b32 v19, v18
